# baseline (speedup 1.0000x reference)
.LBB0_65:
	ds_read_b128 v[128:131], v173
	ds_read_b128 v[132:135], v173 offset:1024
	ds_read_b128 v[158:161], v173 offset:2048
	ds_read_b128 v[178:181], v173 offset:3072
	ds_read_b128 v[182:185], v174
	ds_read_b128 v[186:189], v174 offset:1024
	ds_read_b128 v[190:193], v174 offset:2048
	ds_read_b128 v[194:197], v174 offset:3072
	s_add_u32 s3, s14, 0xfff80080
	s_addc_u32 s34, s15, -1
	s_cmp_eq_u32 s37, 28
	s_cselect_b32 s91, s0, s34
	s_cselect_b32 s90, s1, s3
	s_cselect_b32 s35, s7, s36
	s_cselect_b32 s34, s13, s24
	s_add_i32 m0, s27, 0xc000
	ds_read_b128 v[198:201], v175
	ds_read_b128 v[202:205], v175 offset:1024
	ds_read_b128 v[206:209], v175 offset:2048
	ds_read_b128 v[210:213], v175 offset:3072
	ds_read_b128 v[214:217], v175 offset:4096
	ds_read_b128 v[218:221], v175 offset:5120
	ds_read_b128 v[222:225], v175 offset:6144
	ds_read_b128 v[230:233], v175 offset:7168
	global_load_lds_dwordx4 v148, s[14:15]
	s_add_i32 m0, s27, 0xe000
	s_nop 0
	global_load_lds_dwordx4 v150, s[14:15]
	s_waitcnt vmcnt(8)
	s_waitcnt lgkmcnt(0)
	s_barrier
	s_setprio 1
	s_waitcnt lgkmcnt(0)
	v_mfma_f32_16x16x32_bf16 v[124:127], v[128:131], v[198:201], v[124:127]
	v_mfma_f32_16x16x32_bf16 v[120:123], v[158:161], v[198:201], v[120:123]
	v_mfma_f32_16x16x32_bf16 v[108:111], v[128:131], v[206:209], v[108:111]
	v_mfma_f32_16x16x32_bf16 v[104:107], v[158:161], v[206:209], v[104:107]
	v_mfma_f32_16x16x32_bf16 v[92:95], v[128:131], v[214:217], v[92:95]
	v_mfma_f32_16x16x32_bf16 v[88:91], v[158:161], v[214:217], v[88:91]
	v_mfma_f32_16x16x32_bf16 v[76:79], v[128:131], v[222:225], v[76:79]
	v_mfma_f32_16x16x32_bf16 v[72:75], v[158:161], v[222:225], v[72:75]
	v_mfma_f32_16x16x32_bf16 v[124:127], v[132:135], v[202:205], v[124:127]
	v_mfma_f32_16x16x32_bf16 v[120:123], v[178:181], v[202:205], v[120:123]
	v_mfma_f32_16x16x32_bf16 v[108:111], v[132:135], v[210:213], v[108:111]
	v_mfma_f32_16x16x32_bf16 v[104:107], v[178:181], v[210:213], v[104:107]
	v_mfma_f32_16x16x32_bf16 v[92:95], v[132:135], v[218:221], v[92:95]
	v_mfma_f32_16x16x32_bf16 v[88:91], v[178:181], v[218:221], v[88:91]
	v_mfma_f32_16x16x32_bf16 v[76:79], v[132:135], v[230:233], v[76:79]
	v_mfma_f32_16x16x32_bf16 v[72:75], v[178:181], v[230:233], v[72:75]
	v_mfma_f32_16x16x32_bf16 v[116:119], v[182:185], v[198:201], v[116:119]
	v_mfma_f32_16x16x32_bf16 v[112:115], v[190:193], v[198:201], v[112:115]
	v_mfma_f32_16x16x32_bf16 v[100:103], v[182:185], v[206:209], v[100:103]
	v_mfma_f32_16x16x32_bf16 v[96:99], v[190:193], v[206:209], v[96:99]
	v_mfma_f32_16x16x32_bf16 v[84:87], v[182:185], v[214:217], v[84:87]
	v_mfma_f32_16x16x32_bf16 v[80:83], v[190:193], v[214:217], v[80:83]
	v_mfma_f32_16x16x32_bf16 v[68:71], v[182:185], v[222:225], v[68:71]
	v_mfma_f32_16x16x32_bf16 v[64:67], v[190:193], v[222:225], v[64:67]
	v_mfma_f32_16x16x32_bf16 v[116:119], v[186:189], v[202:205], v[116:119]
	v_mfma_f32_16x16x32_bf16 v[112:115], v[194:197], v[202:205], v[112:115]
	v_mfma_f32_16x16x32_bf16 v[100:103], v[186:189], v[210:213], v[100:103]
	v_mfma_f32_16x16x32_bf16 v[96:99], v[194:197], v[210:213], v[96:99]
	v_mfma_f32_16x16x32_bf16 v[84:87], v[186:189], v[218:221], v[84:87]
	v_mfma_f32_16x16x32_bf16 v[80:83], v[194:197], v[218:221], v[80:83]
	v_mfma_f32_16x16x32_bf16 v[68:71], v[186:189], v[230:233], v[68:71]
	v_mfma_f32_16x16x32_bf16 v[64:67], v[194:197], v[230:233], v[64:67]
	s_setprio 0
	s_barrier
	s_add_i32 s3, s78, s25
	s_mov_b32 m0, s3
	ds_read_b128 v[198:201], v175 offset:16384
	ds_read_b128 v[202:205], v175 offset:17408
	ds_read_b128 v[206:209], v175 offset:18432
	ds_read_b128 v[210:213], v175 offset:19456
	ds_read_b128 v[214:217], v175 offset:20480
	ds_read_b128 v[218:221], v175 offset:21504
	ds_read_b128 v[222:225], v175 offset:22528
	ds_read_b128 v[230:233], v175 offset:23552
	global_load_lds_dwordx4 v138, s[34:35]
	s_add_i32 m0, s3, 0x2000
	s_add_u32 s42, s34, 0x80000
	s_addc_u32 s43, s35, 0
	s_add_i32 s3, s79, s25
	global_load_lds_dwordx4 v142, s[34:35]
	s_mov_b32 m0, s3
	s_nop 0
	global_load_lds_dwordx4 v138, s[42:43]
	s_add_i32 m0, s3, 0x2000
	s_nop 0
	global_load_lds_dwordx4 v142, s[42:43]
	s_mov_b32 m0, s27
	s_nop 0
	global_load_lds_dwordx4 v136, s[90:91]
	s_mov_b32 m0, s30
	s_nop 0
	global_load_lds_dwordx4 v140, s[90:91]
	s_waitcnt vmcnt(8)
	s_waitcnt lgkmcnt(0)
	s_barrier
	s_setprio 1
	s_waitcnt lgkmcnt(0)
	v_mfma_f32_16x16x32_bf16 v[60:63], v[128:131], v[198:201], v[60:63]
	v_mfma_f32_16x16x32_bf16 v[56:59], v[158:161], v[198:201], v[56:59]
	v_mfma_f32_16x16x32_bf16 v[44:47], v[128:131], v[206:209], v[44:47]
	v_mfma_f32_16x16x32_bf16 v[40:43], v[158:161], v[206:209], v[40:43]
	v_mfma_f32_16x16x32_bf16 v[28:31], v[128:131], v[214:217], v[28:31]
	v_mfma_f32_16x16x32_bf16 v[24:27], v[158:161], v[214:217], v[24:27]
	v_mfma_f32_16x16x32_bf16 v[12:15], v[128:131], v[222:225], v[12:15]
	v_mfma_f32_16x16x32_bf16 v[8:11], v[158:161], v[222:225], v[8:11]
	v_mfma_f32_16x16x32_bf16 v[60:63], v[132:135], v[202:205], v[60:63]
	v_mfma_f32_16x16x32_bf16 v[56:59], v[178:181], v[202:205], v[56:59]
	v_mfma_f32_16x16x32_bf16 v[44:47], v[132:135], v[210:213], v[44:47]
	v_mfma_f32_16x16x32_bf16 v[40:43], v[178:181], v[210:213], v[40:43]
	v_mfma_f32_16x16x32_bf16 v[28:31], v[132:135], v[218:221], v[28:31]
	v_mfma_f32_16x16x32_bf16 v[24:27], v[178:181], v[218:221], v[24:27]
	v_mfma_f32_16x16x32_bf16 v[12:15], v[132:135], v[230:233], v[12:15]
	v_mfma_f32_16x16x32_bf16 v[8:11], v[178:181], v[230:233], v[8:11]
	v_mfma_f32_16x16x32_bf16 v[52:55], v[182:185], v[198:201], v[52:55]
	v_mfma_f32_16x16x32_bf16 v[48:51], v[190:193], v[198:201], v[48:51]
	v_mfma_f32_16x16x32_bf16 v[36:39], v[182:185], v[206:209], v[36:39]
	v_mfma_f32_16x16x32_bf16 v[32:35], v[190:193], v[206:209], v[32:35]
	v_mfma_f32_16x16x32_bf16 v[20:23], v[182:185], v[214:217], v[20:23]
	v_mfma_f32_16x16x32_bf16 v[16:19], v[190:193], v[214:217], v[16:19]
	v_mfma_f32_16x16x32_bf16 v[4:7], v[182:185], v[222:225], v[4:7]
	v_mfma_f32_16x16x32_bf16 v[0:3], v[190:193], v[222:225], v[0:3]
	v_mfma_f32_16x16x32_bf16 v[52:55], v[186:189], v[202:205], v[52:55]
	v_mfma_f32_16x16x32_bf16 v[48:51], v[194:197], v[202:205], v[48:51]
	v_mfma_f32_16x16x32_bf16 v[36:39], v[186:189], v[210:213], v[36:39]
	v_mfma_f32_16x16x32_bf16 v[32:35], v[194:197], v[210:213], v[32:35]
	v_mfma_f32_16x16x32_bf16 v[20:23], v[186:189], v[218:221], v[20:23]
	v_mfma_f32_16x16x32_bf16 v[16:19], v[194:197], v[218:221], v[16:19]
	v_mfma_f32_16x16x32_bf16 v[4:7], v[186:189], v[230:233], v[4:7]
	v_mfma_f32_16x16x32_bf16 v[0:3], v[194:197], v[230:233], v[0:3]
	s_setprio 0
	s_barrier
	s_add_i32 s3, 0, 0x18000
	v_add_u32_e32 v144, s3, v165
	s_add_i32 s44, 0, 0x1c000
	ds_read_b128 v[128:131], v144
	ds_read_b128 v[132:135], v144 offset:1024
	ds_read_b128 v[158:161], v144 offset:2048
	ds_read_b128 v[178:181], v144 offset:3072
	v_add_u32_e32 v144, s44, v165
	ds_read_b128 v[182:185], v144
	ds_read_b128 v[186:189], v144 offset:1024
	ds_read_b128 v[190:193], v144 offset:2048
	ds_read_b128 v[194:197], v144 offset:3072
	s_add_u32 s42, s90, 0x80000
	s_addc_u32 s43, s91, 0
	s_mov_b32 m0, s31
	ds_read_b128 v[198:201], v175 offset:32768
	ds_read_b128 v[202:205], v175 offset:33792
	ds_read_b128 v[206:209], v175 offset:34816
	ds_read_b128 v[210:213], v175 offset:35840
	ds_read_b128 v[214:217], v175 offset:36864
	ds_read_b128 v[218:221], v175 offset:37888
	ds_read_b128 v[222:225], v175 offset:38912
	ds_read_b128 v[230:233], v175 offset:39936
	global_load_lds_dwordx4 v136, s[42:43]
	s_mov_b32 m0, s33
	s_nop 0
	global_load_lds_dwordx4 v140, s[42:43]
	s_waitcnt vmcnt(8)
	s_waitcnt lgkmcnt(0)
	s_barrier
	s_setprio 1
	s_waitcnt lgkmcnt(0)
	v_mfma_f32_16x16x32_bf16 v[124:127], v[128:131], v[198:201], v[124:127]
	v_mfma_f32_16x16x32_bf16 v[120:123], v[158:161], v[198:201], v[120:123]
	v_mfma_f32_16x16x32_bf16 v[108:111], v[128:131], v[206:209], v[108:111]
	v_mfma_f32_16x16x32_bf16 v[104:107], v[158:161], v[206:209], v[104:107]
	v_mfma_f32_16x16x32_bf16 v[92:95], v[128:131], v[214:217], v[92:95]
	v_mfma_f32_16x16x32_bf16 v[88:91], v[158:161], v[214:217], v[88:91]
	v_mfma_f32_16x16x32_bf16 v[76:79], v[128:131], v[222:225], v[76:79]
	v_mfma_f32_16x16x32_bf16 v[72:75], v[158:161], v[222:225], v[72:75]
	v_mfma_f32_16x16x32_bf16 v[124:127], v[132:135], v[202:205], v[124:127]
	v_mfma_f32_16x16x32_bf16 v[120:123], v[178:181], v[202:205], v[120:123]
	v_mfma_f32_16x16x32_bf16 v[108:111], v[132:135], v[210:213], v[108:111]
	v_mfma_f32_16x16x32_bf16 v[104:107], v[178:181], v[210:213], v[104:107]
	v_mfma_f32_16x16x32_bf16 v[92:95], v[132:135], v[218:221], v[92:95]
	v_mfma_f32_16x16x32_bf16 v[88:91], v[178:181], v[218:221], v[88:91]
	v_mfma_f32_16x16x32_bf16 v[76:79], v[132:135], v[230:233], v[76:79]
	v_mfma_f32_16x16x32_bf16 v[72:75], v[178:181], v[230:233], v[72:75]
	v_mfma_f32_16x16x32_bf16 v[116:119], v[182:185], v[198:201], v[116:119]
	v_mfma_f32_16x16x32_bf16 v[112:115], v[190:193], v[198:201], v[112:115]
	v_mfma_f32_16x16x32_bf16 v[100:103], v[182:185], v[206:209], v[100:103]
	v_mfma_f32_16x16x32_bf16 v[96:99], v[190:193], v[206:209], v[96:99]
	v_mfma_f32_16x16x32_bf16 v[84:87], v[182:185], v[214:217], v[84:87]
	v_mfma_f32_16x16x32_bf16 v[80:83], v[190:193], v[214:217], v[80:83]
	v_mfma_f32_16x16x32_bf16 v[68:71], v[182:185], v[222:225], v[68:71]
	v_mfma_f32_16x16x32_bf16 v[64:67], v[190:193], v[222:225], v[64:67]
	v_mfma_f32_16x16x32_bf16 v[116:119], v[186:189], v[202:205], v[116:119]
	v_mfma_f32_16x16x32_bf16 v[112:115], v[194:197], v[202:205], v[112:115]
	v_mfma_f32_16x16x32_bf16 v[100:103], v[186:189], v[210:213], v[100:103]
	v_mfma_f32_16x16x32_bf16 v[96:99], v[194:197], v[210:213], v[96:99]
	v_mfma_f32_16x16x32_bf16 v[84:87], v[186:189], v[218:221], v[84:87]
	v_mfma_f32_16x16x32_bf16 v[80:83], v[194:197], v[218:221], v[80:83]
	v_mfma_f32_16x16x32_bf16 v[68:71], v[186:189], v[230:233], v[68:71]
	v_mfma_f32_16x16x32_bf16 v[64:67], v[194:197], v[230:233], v[64:67]
	s_setprio 0
	s_barrier
	s_add_i32 s3, s3, s25
	s_add_u32 s34, s34, 0x80
	s_addc_u32 s35, s35, 0
	s_mov_b32 m0, s3
	ds_read_b128 v[198:201], v175 offset:49152
	ds_read_b128 v[202:205], v175 offset:50176
	ds_read_b128 v[206:209], v175 offset:51200
	ds_read_b128 v[210:213], v175 offset:52224
	ds_read_b128 v[214:217], v175 offset:53248
	ds_read_b128 v[218:221], v175 offset:54272
	ds_read_b128 v[222:225], v175 offset:55296
	ds_read_b128 v[230:233], v175 offset:56320
	global_load_lds_dwordx4 v138, s[34:35]
	s_add_i32 m0, s3, 0x2000
	s_add_i32 s3, s44, s25
	global_load_lds_dwordx4 v142, s[34:35]
	s_add_u32 s34, s34, 0x80000
	s_addc_u32 s35, s35, 0
	s_mov_b32 m0, s3
	s_nop 0
	global_load_lds_dwordx4 v138, s[34:35]
	s_add_i32 m0, s3, 0x2000
	s_nop 0
	global_load_lds_dwordx4 v142, s[34:35]
	s_add_u32 s90, s90, 0x80
	s_addc_u32 s91, s91, 0
	s_mov_b32 m0, s58
	s_nop 0
	global_load_lds_dwordx4 v136, s[90:91]
	s_mov_b32 m0, s59
	s_nop 0
	global_load_lds_dwordx4 v140, s[90:91]
	s_waitcnt vmcnt(8)
	s_waitcnt lgkmcnt(0)
	s_barrier
	s_setprio 1
	s_waitcnt lgkmcnt(0)
	v_mfma_f32_16x16x32_bf16 v[60:63], v[128:131], v[198:201], v[60:63]
	v_mfma_f32_16x16x32_bf16 v[56:59], v[158:161], v[198:201], v[56:59]
	v_mfma_f32_16x16x32_bf16 v[44:47], v[128:131], v[206:209], v[44:47]
	v_mfma_f32_16x16x32_bf16 v[40:43], v[158:161], v[206:209], v[40:43]
	v_mfma_f32_16x16x32_bf16 v[28:31], v[128:131], v[214:217], v[28:31]
	v_mfma_f32_16x16x32_bf16 v[24:27], v[158:161], v[214:217], v[24:27]
	v_mfma_f32_16x16x32_bf16 v[12:15], v[128:131], v[222:225], v[12:15]
	v_mfma_f32_16x16x32_bf16 v[8:11], v[158:161], v[222:225], v[8:11]
	v_mfma_f32_16x16x32_bf16 v[60:63], v[132:135], v[202:205], v[60:63]
	v_mfma_f32_16x16x32_bf16 v[56:59], v[178:181], v[202:205], v[56:59]
	v_mfma_f32_16x16x32_bf16 v[44:47], v[132:135], v[210:213], v[44:47]
	v_mfma_f32_16x16x32_bf16 v[40:43], v[178:181], v[210:213], v[40:43]
	v_mfma_f32_16x16x32_bf16 v[28:31], v[132:135], v[218:221], v[28:31]
	v_mfma_f32_16x16x32_bf16 v[24:27], v[178:181], v[218:221], v[24:27]
	v_mfma_f32_16x16x32_bf16 v[12:15], v[132:135], v[230:233], v[12:15]
	v_mfma_f32_16x16x32_bf16 v[8:11], v[178:181], v[230:233], v[8:11]
	v_mfma_f32_16x16x32_bf16 v[52:55], v[182:185], v[198:201], v[52:55]
	v_mfma_f32_16x16x32_bf16 v[48:51], v[190:193], v[198:201], v[48:51]
	v_mfma_f32_16x16x32_bf16 v[36:39], v[182:185], v[206:209], v[36:39]
	v_mfma_f32_16x16x32_bf16 v[32:35], v[190:193], v[206:209], v[32:35]
	v_mfma_f32_16x16x32_bf16 v[20:23], v[182:185], v[214:217], v[20:23]
	v_mfma_f32_16x16x32_bf16 v[16:19], v[190:193], v[214:217], v[16:19]
	v_mfma_f32_16x16x32_bf16 v[4:7], v[182:185], v[222:225], v[4:7]
	v_mfma_f32_16x16x32_bf16 v[0:3], v[190:193], v[222:225], v[0:3]
	v_mfma_f32_16x16x32_bf16 v[52:55], v[186:189], v[202:205], v[52:55]
	v_mfma_f32_16x16x32_bf16 v[48:51], v[194:197], v[202:205], v[48:51]
	v_mfma_f32_16x16x32_bf16 v[36:39], v[186:189], v[210:213], v[36:39]
	v_mfma_f32_16x16x32_bf16 v[32:35], v[194:197], v[210:213], v[32:35]
	v_mfma_f32_16x16x32_bf16 v[20:23], v[186:189], v[218:221], v[20:23]
	v_mfma_f32_16x16x32_bf16 v[16:19], v[194:197], v[218:221], v[16:19]
	v_mfma_f32_16x16x32_bf16 v[4:7], v[186:189], v[230:233], v[4:7]
	v_mfma_f32_16x16x32_bf16 v[0:3], v[194:197], v[230:233], v[0:3]
	s_setprio 0
	s_barrier
	s_add_i32 s37, s37, 2
	s_add_u32 s14, s14, 0x100
	s_addc_u32 s15, s15, 0
	s_add_u32 s24, s24, 0x100
	s_addc_u32 s36, s36, 0
	s_cmp_gt_u32 s37, 29
	s_cbranch_scc0 .LBB0_65
	s_and_b64 vcc, exec, s[48:49]
	s_cbranch_vccz .LBB0_68
	s_barrier

.LBB0_539:
	ds_read_b128 v[144:147], v153
	ds_read_b128 v[156:159], v153 offset:1024
	ds_read_b128 v[160:163], v153 offset:2048
	ds_read_b128 v[164:167], v153 offset:3072
	ds_read_b128 v[168:171], v154
	ds_read_b128 v[172:175], v154 offset:1024
	ds_read_b128 v[176:179], v154 offset:2048
	ds_read_b128 v[180:183], v154 offset:3072
	s_add_u32 s3, s86, 0xfffc0080
	s_addc_u32 s37, s87, -1
	s_cmp_eq_u32 s36, 12
	s_cselect_b32 s91, s0, s37
	s_cselect_b32 s90, s1, s3
	s_cselect_b32 s89, s17, s35
	s_cselect_b32 s88, s27, s33
	s_add_i32 m0, s19, 0xc000
	ds_read_b128 v[184:187], v155
	ds_read_b128 v[188:191], v155 offset:1024
	ds_read_b128 v[192:195], v155 offset:2048
	ds_read_b128 v[196:199], v155 offset:3072
	ds_read_b128 v[200:203], v155 offset:4096
	ds_read_b128 v[204:207], v155 offset:5120
	ds_read_b128 v[208:211], v155 offset:6144
	ds_read_b128 v[212:215], v155 offset:7168
	global_load_lds_dwordx4 v136, s[86:87]
	s_add_i32 m0, s19, 0xe000
	s_nop 0
	global_load_lds_dwordx4 v138, s[86:87]
	s_waitcnt vmcnt(8)
	s_waitcnt lgkmcnt(0)
	s_barrier
	s_setprio 1
	s_waitcnt lgkmcnt(0)
	v_mfma_f32_16x16x32_bf16 v[124:127], v[144:147], v[184:187], v[124:127]
	v_mfma_f32_16x16x32_bf16 v[120:123], v[160:163], v[184:187], v[120:123]
	v_mfma_f32_16x16x32_bf16 v[108:111], v[144:147], v[192:195], v[108:111]
	v_mfma_f32_16x16x32_bf16 v[104:107], v[160:163], v[192:195], v[104:107]
	v_mfma_f32_16x16x32_bf16 v[92:95], v[144:147], v[200:203], v[92:95]
	v_mfma_f32_16x16x32_bf16 v[88:91], v[160:163], v[200:203], v[88:91]
	v_mfma_f32_16x16x32_bf16 v[76:79], v[144:147], v[208:211], v[76:79]
	v_mfma_f32_16x16x32_bf16 v[72:75], v[160:163], v[208:211], v[72:75]
	v_mfma_f32_16x16x32_bf16 v[124:127], v[156:159], v[188:191], v[124:127]
	v_mfma_f32_16x16x32_bf16 v[120:123], v[164:167], v[188:191], v[120:123]
	v_mfma_f32_16x16x32_bf16 v[108:111], v[156:159], v[196:199], v[108:111]
	v_mfma_f32_16x16x32_bf16 v[104:107], v[164:167], v[196:199], v[104:107]
	v_mfma_f32_16x16x32_bf16 v[92:95], v[156:159], v[204:207], v[92:95]
	v_mfma_f32_16x16x32_bf16 v[88:91], v[164:167], v[204:207], v[88:91]
	v_mfma_f32_16x16x32_bf16 v[76:79], v[156:159], v[212:215], v[76:79]
	v_mfma_f32_16x16x32_bf16 v[72:75], v[164:167], v[212:215], v[72:75]
	v_mfma_f32_16x16x32_bf16 v[116:119], v[168:171], v[184:187], v[116:119]
	v_mfma_f32_16x16x32_bf16 v[112:115], v[176:179], v[184:187], v[112:115]
	v_mfma_f32_16x16x32_bf16 v[100:103], v[168:171], v[192:195], v[100:103]
	v_mfma_f32_16x16x32_bf16 v[96:99], v[176:179], v[192:195], v[96:99]
	v_mfma_f32_16x16x32_bf16 v[84:87], v[168:171], v[200:203], v[84:87]
	v_mfma_f32_16x16x32_bf16 v[80:83], v[176:179], v[200:203], v[80:83]
	v_mfma_f32_16x16x32_bf16 v[68:71], v[168:171], v[208:211], v[68:71]
	v_mfma_f32_16x16x32_bf16 v[64:67], v[176:179], v[208:211], v[64:67]
	v_mfma_f32_16x16x32_bf16 v[116:119], v[172:175], v[188:191], v[116:119]
	v_mfma_f32_16x16x32_bf16 v[112:115], v[180:183], v[188:191], v[112:115]
	v_mfma_f32_16x16x32_bf16 v[100:103], v[172:175], v[196:199], v[100:103]
	v_mfma_f32_16x16x32_bf16 v[96:99], v[180:183], v[196:199], v[96:99]
	v_mfma_f32_16x16x32_bf16 v[84:87], v[172:175], v[204:207], v[84:87]
	v_mfma_f32_16x16x32_bf16 v[80:83], v[180:183], v[204:207], v[80:83]
	v_mfma_f32_16x16x32_bf16 v[68:71], v[172:175], v[212:215], v[68:71]
	v_mfma_f32_16x16x32_bf16 v[64:67], v[180:183], v[212:215], v[64:67]
	s_setprio 0
	s_barrier
	s_add_i32 s3, s57, s18
	s_mov_b32 m0, s3
	ds_read_b128 v[184:187], v155 offset:16384
	ds_read_b128 v[188:191], v155 offset:17408
	ds_read_b128 v[192:195], v155 offset:18432
	ds_read_b128 v[196:199], v155 offset:19456
	ds_read_b128 v[200:203], v155 offset:20480
	ds_read_b128 v[204:207], v155 offset:21504
	ds_read_b128 v[208:211], v155 offset:22528
	ds_read_b128 v[212:215], v155 offset:23552
	global_load_lds_dwordx4 v130, s[88:89]
	s_add_i32 m0, s3, 0x2000
	s_add_u32 s42, s88, 0x40000
	s_addc_u32 s43, s89, 0
	s_add_i32 s3, s58, s18
	global_load_lds_dwordx4 v134, s[88:89]
	s_mov_b32 m0, s3
	s_nop 0
	global_load_lds_dwordx4 v130, s[42:43]
	s_add_i32 m0, s3, 0x2000
	s_nop 0
	global_load_lds_dwordx4 v134, s[42:43]
	s_mov_b32 m0, s19
	s_nop 0
	global_load_lds_dwordx4 v128, s[90:91]
	s_mov_b32 m0, s25
	s_nop 0
	global_load_lds_dwordx4 v132, s[90:91]
	s_waitcnt vmcnt(8)
	s_waitcnt lgkmcnt(0)
	s_barrier
	s_setprio 1
	s_waitcnt lgkmcnt(0)
	v_mfma_f32_16x16x32_bf16 v[60:63], v[144:147], v[184:187], v[60:63]
	v_mfma_f32_16x16x32_bf16 v[56:59], v[160:163], v[184:187], v[56:59]
	v_mfma_f32_16x16x32_bf16 v[44:47], v[144:147], v[192:195], v[44:47]
	v_mfma_f32_16x16x32_bf16 v[40:43], v[160:163], v[192:195], v[40:43]
	v_mfma_f32_16x16x32_bf16 v[28:31], v[144:147], v[200:203], v[28:31]
	v_mfma_f32_16x16x32_bf16 v[24:27], v[160:163], v[200:203], v[24:27]
	v_mfma_f32_16x16x32_bf16 v[12:15], v[144:147], v[208:211], v[12:15]
	v_mfma_f32_16x16x32_bf16 v[8:11], v[160:163], v[208:211], v[8:11]
	v_mfma_f32_16x16x32_bf16 v[60:63], v[156:159], v[188:191], v[60:63]
	v_mfma_f32_16x16x32_bf16 v[56:59], v[164:167], v[188:191], v[56:59]
	v_mfma_f32_16x16x32_bf16 v[44:47], v[156:159], v[196:199], v[44:47]
	v_mfma_f32_16x16x32_bf16 v[40:43], v[164:167], v[196:199], v[40:43]
	v_mfma_f32_16x16x32_bf16 v[28:31], v[156:159], v[204:207], v[28:31]
	v_mfma_f32_16x16x32_bf16 v[24:27], v[164:167], v[204:207], v[24:27]
	v_mfma_f32_16x16x32_bf16 v[12:15], v[156:159], v[212:215], v[12:15]
	v_mfma_f32_16x16x32_bf16 v[8:11], v[164:167], v[212:215], v[8:11]
	v_mfma_f32_16x16x32_bf16 v[52:55], v[168:171], v[184:187], v[52:55]
	v_mfma_f32_16x16x32_bf16 v[48:51], v[176:179], v[184:187], v[48:51]
	v_mfma_f32_16x16x32_bf16 v[36:39], v[168:171], v[192:195], v[36:39]
	v_mfma_f32_16x16x32_bf16 v[32:35], v[176:179], v[192:195], v[32:35]
	v_mfma_f32_16x16x32_bf16 v[20:23], v[168:171], v[200:203], v[20:23]
	v_mfma_f32_16x16x32_bf16 v[16:19], v[176:179], v[200:203], v[16:19]
	v_mfma_f32_16x16x32_bf16 v[4:7], v[168:171], v[208:211], v[4:7]
	v_mfma_f32_16x16x32_bf16 v[0:3], v[176:179], v[208:211], v[0:3]
	v_mfma_f32_16x16x32_bf16 v[52:55], v[172:175], v[188:191], v[52:55]
	v_mfma_f32_16x16x32_bf16 v[48:51], v[180:183], v[188:191], v[48:51]
	v_mfma_f32_16x16x32_bf16 v[36:39], v[172:175], v[196:199], v[36:39]
	v_mfma_f32_16x16x32_bf16 v[32:35], v[180:183], v[196:199], v[32:35]
	v_mfma_f32_16x16x32_bf16 v[20:23], v[172:175], v[204:207], v[20:23]
	v_mfma_f32_16x16x32_bf16 v[16:19], v[180:183], v[204:207], v[16:19]
	v_mfma_f32_16x16x32_bf16 v[4:7], v[172:175], v[212:215], v[4:7]
	v_mfma_f32_16x16x32_bf16 v[0:3], v[180:183], v[212:215], v[0:3]
	s_setprio 0
	s_barrier
	s_add_i32 s3, 0, 0x18000
	s_add_i32 s37, 0, 0x1c000
	v_add_u32_e32 v164, s3, v151
	v_add_u32_e32 v180, s37, v151
	ds_read_b128 v[144:147], v164
	ds_read_b128 v[156:159], v164 offset:1024
	ds_read_b128 v[160:163], v164 offset:2048
	ds_read_b128 v[164:167], v164 offset:3072
	ds_read_b128 v[168:171], v180
	ds_read_b128 v[172:175], v180 offset:1024
	ds_read_b128 v[176:179], v180 offset:2048
	ds_read_b128 v[180:183], v180 offset:3072
	s_add_u32 s42, s90, 0x40000
	s_addc_u32 s43, s91, 0
	s_mov_b32 m0, s30
	ds_read_b128 v[184:187], v155 offset:32768
	ds_read_b128 v[188:191], v155 offset:33792
	ds_read_b128 v[192:195], v155 offset:34816
	ds_read_b128 v[196:199], v155 offset:35840
	ds_read_b128 v[200:203], v155 offset:36864
	ds_read_b128 v[204:207], v155 offset:37888
	ds_read_b128 v[208:211], v155 offset:38912
	ds_read_b128 v[212:215], v155 offset:39936
	global_load_lds_dwordx4 v128, s[42:43]
	v_lshl_add_u64 v[222:223], s[42:43], 0, v[132:133]
	s_mov_b32 m0, s31
	s_nop 0
	global_load_lds_dwordx4 v[222:223], off
	s_waitcnt vmcnt(8)
	s_waitcnt lgkmcnt(0)
	s_barrier
	s_setprio 1
	s_waitcnt lgkmcnt(0)
	v_mfma_f32_16x16x32_bf16 v[124:127], v[144:147], v[184:187], v[124:127]
	v_mfma_f32_16x16x32_bf16 v[120:123], v[160:163], v[184:187], v[120:123]
	v_mfma_f32_16x16x32_bf16 v[108:111], v[144:147], v[192:195], v[108:111]
	v_mfma_f32_16x16x32_bf16 v[104:107], v[160:163], v[192:195], v[104:107]
	v_mfma_f32_16x16x32_bf16 v[92:95], v[144:147], v[200:203], v[92:95]
	v_mfma_f32_16x16x32_bf16 v[88:91], v[160:163], v[200:203], v[88:91]
	v_mfma_f32_16x16x32_bf16 v[76:79], v[144:147], v[208:211], v[76:79]
	v_mfma_f32_16x16x32_bf16 v[72:75], v[160:163], v[208:211], v[72:75]
	v_mfma_f32_16x16x32_bf16 v[124:127], v[156:159], v[188:191], v[124:127]
	v_mfma_f32_16x16x32_bf16 v[120:123], v[164:167], v[188:191], v[120:123]
	v_mfma_f32_16x16x32_bf16 v[108:111], v[156:159], v[196:199], v[108:111]
	v_mfma_f32_16x16x32_bf16 v[104:107], v[164:167], v[196:199], v[104:107]
	v_mfma_f32_16x16x32_bf16 v[92:95], v[156:159], v[204:207], v[92:95]
	v_mfma_f32_16x16x32_bf16 v[88:91], v[164:167], v[204:207], v[88:91]
	v_mfma_f32_16x16x32_bf16 v[76:79], v[156:159], v[212:215], v[76:79]
	v_mfma_f32_16x16x32_bf16 v[72:75], v[164:167], v[212:215], v[72:75]
	v_mfma_f32_16x16x32_bf16 v[116:119], v[168:171], v[184:187], v[116:119]
	v_mfma_f32_16x16x32_bf16 v[112:115], v[176:179], v[184:187], v[112:115]
	v_mfma_f32_16x16x32_bf16 v[100:103], v[168:171], v[192:195], v[100:103]
	v_mfma_f32_16x16x32_bf16 v[96:99], v[176:179], v[192:195], v[96:99]
	v_mfma_f32_16x16x32_bf16 v[84:87], v[168:171], v[200:203], v[84:87]
	v_mfma_f32_16x16x32_bf16 v[80:83], v[176:179], v[200:203], v[80:83]
	v_mfma_f32_16x16x32_bf16 v[68:71], v[168:171], v[208:211], v[68:71]
	v_mfma_f32_16x16x32_bf16 v[64:67], v[176:179], v[208:211], v[64:67]
	v_mfma_f32_16x16x32_bf16 v[116:119], v[172:175], v[188:191], v[116:119]
	v_mfma_f32_16x16x32_bf16 v[112:115], v[180:183], v[188:191], v[112:115]
	v_mfma_f32_16x16x32_bf16 v[100:103], v[172:175], v[196:199], v[100:103]
	v_mfma_f32_16x16x32_bf16 v[96:99], v[180:183], v[196:199], v[96:99]
	v_mfma_f32_16x16x32_bf16 v[84:87], v[172:175], v[204:207], v[84:87]
	v_mfma_f32_16x16x32_bf16 v[80:83], v[180:183], v[204:207], v[80:83]
	v_mfma_f32_16x16x32_bf16 v[68:71], v[172:175], v[212:215], v[68:71]
	v_mfma_f32_16x16x32_bf16 v[64:67], v[180:183], v[212:215], v[64:67]
	s_setprio 0
	s_barrier
	s_add_i32 s3, s3, s18
	s_add_u32 s42, s88, 0x80
	s_addc_u32 s43, s89, 0
	s_mov_b32 m0, s3
	ds_read_b128 v[184:187], v155 offset:49152
	ds_read_b128 v[188:191], v155 offset:50176
	ds_read_b128 v[192:195], v155 offset:51200
	ds_read_b128 v[196:199], v155 offset:52224
	ds_read_b128 v[200:203], v155 offset:53248
	ds_read_b128 v[204:207], v155 offset:54272
	ds_read_b128 v[208:211], v155 offset:55296
	ds_read_b128 v[212:215], v155 offset:56320
	global_load_lds_dwordx4 v130, s[42:43]
	s_add_i32 m0, s3, 0x2000
	s_add_i32 s3, s37, s18
	global_load_lds_dwordx4 v134, s[42:43]
	s_add_u32 s42, s42, 0x40000
	s_addc_u32 s43, s43, 0
	s_mov_b32 m0, s3
	s_nop 0
	global_load_lds_dwordx4 v130, s[42:43]
	s_add_i32 m0, s3, 0x2000
	s_nop 0
	global_load_lds_dwordx4 v134, s[42:43]
	s_add_u32 s90, s90, 0x80
	s_addc_u32 s91, s91, 0
	s_mov_b32 m0, s49
	s_nop 0
	global_load_lds_dwordx4 v128, s[90:91]
	s_mov_b32 m0, s56
	s_nop 0
	global_load_lds_dwordx4 v132, s[90:91]
	s_waitcnt vmcnt(8)
	s_waitcnt lgkmcnt(0)
	s_barrier
	s_setprio 1
	s_waitcnt lgkmcnt(0)
	v_mfma_f32_16x16x32_bf16 v[60:63], v[144:147], v[184:187], v[60:63]
	v_mfma_f32_16x16x32_bf16 v[56:59], v[160:163], v[184:187], v[56:59]
	v_mfma_f32_16x16x32_bf16 v[44:47], v[144:147], v[192:195], v[44:47]
	v_mfma_f32_16x16x32_bf16 v[40:43], v[160:163], v[192:195], v[40:43]
	v_mfma_f32_16x16x32_bf16 v[28:31], v[144:147], v[200:203], v[28:31]
	v_mfma_f32_16x16x32_bf16 v[24:27], v[160:163], v[200:203], v[24:27]
	v_mfma_f32_16x16x32_bf16 v[12:15], v[144:147], v[208:211], v[12:15]
	v_mfma_f32_16x16x32_bf16 v[8:11], v[160:163], v[208:211], v[8:11]
	v_mfma_f32_16x16x32_bf16 v[60:63], v[156:159], v[188:191], v[60:63]
	v_mfma_f32_16x16x32_bf16 v[56:59], v[164:167], v[188:191], v[56:59]
	v_mfma_f32_16x16x32_bf16 v[44:47], v[156:159], v[196:199], v[44:47]
	v_mfma_f32_16x16x32_bf16 v[40:43], v[164:167], v[196:199], v[40:43]
	v_mfma_f32_16x16x32_bf16 v[28:31], v[156:159], v[204:207], v[28:31]
	v_mfma_f32_16x16x32_bf16 v[24:27], v[164:167], v[204:207], v[24:27]
	v_mfma_f32_16x16x32_bf16 v[12:15], v[156:159], v[212:215], v[12:15]
	v_mfma_f32_16x16x32_bf16 v[8:11], v[164:167], v[212:215], v[8:11]
	v_mfma_f32_16x16x32_bf16 v[52:55], v[168:171], v[184:187], v[52:55]
	v_mfma_f32_16x16x32_bf16 v[48:51], v[176:179], v[184:187], v[48:51]
	v_mfma_f32_16x16x32_bf16 v[36:39], v[168:171], v[192:195], v[36:39]
	v_mfma_f32_16x16x32_bf16 v[32:35], v[176:179], v[192:195], v[32:35]
	v_mfma_f32_16x16x32_bf16 v[20:23], v[168:171], v[200:203], v[20:23]
	v_mfma_f32_16x16x32_bf16 v[16:19], v[176:179], v[200:203], v[16:19]
	v_mfma_f32_16x16x32_bf16 v[4:7], v[168:171], v[208:211], v[4:7]
	v_mfma_f32_16x16x32_bf16 v[0:3], v[176:179], v[208:211], v[0:3]
	v_mfma_f32_16x16x32_bf16 v[52:55], v[172:175], v[188:191], v[52:55]
	v_mfma_f32_16x16x32_bf16 v[48:51], v[180:183], v[188:191], v[48:51]
	v_mfma_f32_16x16x32_bf16 v[36:39], v[172:175], v[196:199], v[36:39]
	v_mfma_f32_16x16x32_bf16 v[32:35], v[180:183], v[196:199], v[32:35]
	v_mfma_f32_16x16x32_bf16 v[20:23], v[172:175], v[204:207], v[20:23]
	v_mfma_f32_16x16x32_bf16 v[16:19], v[180:183], v[204:207], v[16:19]
	v_mfma_f32_16x16x32_bf16 v[4:7], v[172:175], v[212:215], v[4:7]
	v_mfma_f32_16x16x32_bf16 v[0:3], v[180:183], v[212:215], v[0:3]
	s_setprio 0
	s_barrier
	s_add_i32 s36, s36, 2
	s_add_u32 s86, s86, 0x100
	s_addc_u32 s87, s87, 0
	s_add_u32 s33, s33, 0x100
	s_addc_u32 s35, s35, 0
	s_cmp_gt_u32 s36, 13
	s_cbranch_scc0 .LBB0_539
	s_and_b64 vcc, exec, s[12:13]
	s_cbranch_vccz .LBB0_542
	s_barrier

.LBB0_563:
	ds_read_b128 v[144:147], v157
	ds_read_b128 v[148:151], v157 offset:1024
	ds_read_b128 v[160:163], v157 offset:2048
	ds_read_b128 v[164:167], v157 offset:3072
	ds_read_b128 v[168:171], v158
	ds_read_b128 v[172:175], v158 offset:1024
	ds_read_b128 v[176:179], v158 offset:2048
	ds_read_b128 v[180:183], v158 offset:3072
	s_add_u32 s3, s34, 0xfffe0080
	s_addc_u32 s42, s35, -1
	s_cmp_eq_u32 s37, 4
	s_cselect_b32 s91, s0, s42
	s_cselect_b32 s90, s1, s3
	s_cselect_b32 s89, s24, s36
	s_cselect_b32 s88, s27, s33
	s_add_i32 m0, s19, 0xc000
	ds_read_b128 v[184:187], v159
	ds_read_b128 v[188:191], v159 offset:1024
	ds_read_b128 v[192:195], v159 offset:2048
	ds_read_b128 v[196:199], v159 offset:3072
	ds_read_b128 v[200:203], v159 offset:4096
	ds_read_b128 v[204:207], v159 offset:5120
	ds_read_b128 v[208:211], v159 offset:6144
	ds_read_b128 v[212:215], v159 offset:7168
	global_load_lds_dwordx4 v136, s[34:35]
	s_add_i32 m0, s19, 0xe000
	s_nop 0
	global_load_lds_dwordx4 v138, s[34:35]
	s_waitcnt vmcnt(8)
	s_waitcnt lgkmcnt(0)
	s_barrier
	s_setprio 1
	s_waitcnt lgkmcnt(0)
	v_mfma_f32_16x16x32_bf16 v[124:127], v[144:147], v[184:187], v[124:127]
	v_mfma_f32_16x16x32_bf16 v[120:123], v[160:163], v[184:187], v[120:123]
	v_mfma_f32_16x16x32_bf16 v[108:111], v[144:147], v[192:195], v[108:111]
	v_mfma_f32_16x16x32_bf16 v[104:107], v[160:163], v[192:195], v[104:107]
	v_mfma_f32_16x16x32_bf16 v[92:95], v[144:147], v[200:203], v[92:95]
	v_mfma_f32_16x16x32_bf16 v[88:91], v[160:163], v[200:203], v[88:91]
	v_mfma_f32_16x16x32_bf16 v[76:79], v[144:147], v[208:211], v[76:79]
	v_mfma_f32_16x16x32_bf16 v[72:75], v[160:163], v[208:211], v[72:75]
	v_mfma_f32_16x16x32_bf16 v[124:127], v[148:151], v[188:191], v[124:127]
	v_mfma_f32_16x16x32_bf16 v[120:123], v[164:167], v[188:191], v[120:123]
	v_mfma_f32_16x16x32_bf16 v[108:111], v[148:151], v[196:199], v[108:111]
	v_mfma_f32_16x16x32_bf16 v[104:107], v[164:167], v[196:199], v[104:107]
	v_mfma_f32_16x16x32_bf16 v[92:95], v[148:151], v[204:207], v[92:95]
	v_mfma_f32_16x16x32_bf16 v[88:91], v[164:167], v[204:207], v[88:91]
	v_mfma_f32_16x16x32_bf16 v[76:79], v[148:151], v[212:215], v[76:79]
	v_mfma_f32_16x16x32_bf16 v[72:75], v[164:167], v[212:215], v[72:75]
	v_mfma_f32_16x16x32_bf16 v[116:119], v[168:171], v[184:187], v[116:119]
	v_mfma_f32_16x16x32_bf16 v[112:115], v[176:179], v[184:187], v[112:115]
	v_mfma_f32_16x16x32_bf16 v[100:103], v[168:171], v[192:195], v[100:103]
	v_mfma_f32_16x16x32_bf16 v[96:99], v[176:179], v[192:195], v[96:99]
	v_mfma_f32_16x16x32_bf16 v[84:87], v[168:171], v[200:203], v[84:87]
	v_mfma_f32_16x16x32_bf16 v[80:83], v[176:179], v[200:203], v[80:83]
	v_mfma_f32_16x16x32_bf16 v[68:71], v[168:171], v[208:211], v[68:71]
	v_mfma_f32_16x16x32_bf16 v[64:67], v[176:179], v[208:211], v[64:67]
	v_mfma_f32_16x16x32_bf16 v[116:119], v[172:175], v[188:191], v[116:119]
	v_mfma_f32_16x16x32_bf16 v[112:115], v[180:183], v[188:191], v[112:115]
	v_mfma_f32_16x16x32_bf16 v[100:103], v[172:175], v[196:199], v[100:103]
	v_mfma_f32_16x16x32_bf16 v[96:99], v[180:183], v[196:199], v[96:99]
	v_mfma_f32_16x16x32_bf16 v[84:87], v[172:175], v[204:207], v[84:87]
	v_mfma_f32_16x16x32_bf16 v[80:83], v[180:183], v[204:207], v[80:83]
	v_mfma_f32_16x16x32_bf16 v[68:71], v[172:175], v[212:215], v[68:71]
	v_mfma_f32_16x16x32_bf16 v[64:67], v[180:183], v[212:215], v[64:67]
	s_setprio 0
	s_barrier
	s_add_i32 s3, s78, s18
	s_mov_b32 m0, s3
	ds_read_b128 v[184:187], v159 offset:16384
	ds_read_b128 v[188:191], v159 offset:17408
	ds_read_b128 v[192:195], v159 offset:18432
	ds_read_b128 v[196:199], v159 offset:19456
	ds_read_b128 v[200:203], v159 offset:20480
	ds_read_b128 v[204:207], v159 offset:21504
	ds_read_b128 v[208:211], v159 offset:22528
	ds_read_b128 v[212:215], v159 offset:23552
	global_load_lds_dwordx4 v130, s[88:89]
	s_add_i32 m0, s3, 0x2000
	s_add_u32 s42, s88, 0x20000
	s_addc_u32 s43, s89, 0
	s_add_i32 s3, s79, s18
	global_load_lds_dwordx4 v134, s[88:89]
	s_mov_b32 m0, s3
	s_nop 0
	global_load_lds_dwordx4 v130, s[42:43]
	s_add_i32 m0, s3, 0x2000
	s_nop 0
	global_load_lds_dwordx4 v134, s[42:43]
	s_mov_b32 m0, s19
	s_nop 0
	global_load_lds_dwordx4 v128, s[90:91]
	s_mov_b32 m0, s25
	s_nop 0
	global_load_lds_dwordx4 v132, s[90:91]
	s_waitcnt vmcnt(8)
	s_waitcnt lgkmcnt(0)
	s_barrier
	s_setprio 1
	s_waitcnt lgkmcnt(0)
	v_mfma_f32_16x16x32_bf16 v[60:63], v[144:147], v[184:187], v[60:63]
	v_mfma_f32_16x16x32_bf16 v[56:59], v[160:163], v[184:187], v[56:59]
	v_mfma_f32_16x16x32_bf16 v[44:47], v[144:147], v[192:195], v[44:47]
	v_mfma_f32_16x16x32_bf16 v[40:43], v[160:163], v[192:195], v[40:43]
	v_mfma_f32_16x16x32_bf16 v[28:31], v[144:147], v[200:203], v[28:31]
	v_mfma_f32_16x16x32_bf16 v[24:27], v[160:163], v[200:203], v[24:27]
	v_mfma_f32_16x16x32_bf16 v[12:15], v[144:147], v[208:211], v[12:15]
	v_mfma_f32_16x16x32_bf16 v[8:11], v[160:163], v[208:211], v[8:11]
	v_mfma_f32_16x16x32_bf16 v[60:63], v[148:151], v[188:191], v[60:63]
	v_mfma_f32_16x16x32_bf16 v[56:59], v[164:167], v[188:191], v[56:59]
	v_mfma_f32_16x16x32_bf16 v[44:47], v[148:151], v[196:199], v[44:47]
	v_mfma_f32_16x16x32_bf16 v[40:43], v[164:167], v[196:199], v[40:43]
	v_mfma_f32_16x16x32_bf16 v[28:31], v[148:151], v[204:207], v[28:31]
	v_mfma_f32_16x16x32_bf16 v[24:27], v[164:167], v[204:207], v[24:27]
	v_mfma_f32_16x16x32_bf16 v[12:15], v[148:151], v[212:215], v[12:15]
	v_mfma_f32_16x16x32_bf16 v[8:11], v[164:167], v[212:215], v[8:11]
	v_mfma_f32_16x16x32_bf16 v[52:55], v[168:171], v[184:187], v[52:55]
	v_mfma_f32_16x16x32_bf16 v[48:51], v[176:179], v[184:187], v[48:51]
	v_mfma_f32_16x16x32_bf16 v[36:39], v[168:171], v[192:195], v[36:39]
	v_mfma_f32_16x16x32_bf16 v[32:35], v[176:179], v[192:195], v[32:35]
	v_mfma_f32_16x16x32_bf16 v[20:23], v[168:171], v[200:203], v[20:23]
	v_mfma_f32_16x16x32_bf16 v[16:19], v[176:179], v[200:203], v[16:19]
	v_mfma_f32_16x16x32_bf16 v[4:7], v[168:171], v[208:211], v[4:7]
	v_mfma_f32_16x16x32_bf16 v[0:3], v[176:179], v[208:211], v[0:3]
	v_mfma_f32_16x16x32_bf16 v[52:55], v[172:175], v[188:191], v[52:55]
	v_mfma_f32_16x16x32_bf16 v[48:51], v[180:183], v[188:191], v[48:51]
	v_mfma_f32_16x16x32_bf16 v[36:39], v[172:175], v[196:199], v[36:39]
	v_mfma_f32_16x16x32_bf16 v[32:35], v[180:183], v[196:199], v[32:35]
	v_mfma_f32_16x16x32_bf16 v[20:23], v[172:175], v[204:207], v[20:23]
	v_mfma_f32_16x16x32_bf16 v[16:19], v[180:183], v[204:207], v[16:19]
	v_mfma_f32_16x16x32_bf16 v[4:7], v[172:175], v[212:215], v[4:7]
	v_mfma_f32_16x16x32_bf16 v[0:3], v[180:183], v[212:215], v[0:3]
	s_setprio 0
	s_barrier
	s_add_i32 s3, 0, 0x18000
	s_add_i32 s44, 0, 0x1c000
	v_add_u32_e32 v164, s3, v155
	v_add_u32_e32 v180, s44, v155
	ds_read_b128 v[144:147], v164
	ds_read_b128 v[148:151], v164 offset:1024
	ds_read_b128 v[160:163], v164 offset:2048
	ds_read_b128 v[164:167], v164 offset:3072
	ds_read_b128 v[168:171], v180
	ds_read_b128 v[172:175], v180 offset:1024
	ds_read_b128 v[176:179], v180 offset:2048
	ds_read_b128 v[180:183], v180 offset:3072
	s_add_u32 s42, s90, 0x20000
	s_addc_u32 s43, s91, 0
	s_mov_b32 m0, s30
	ds_read_b128 v[184:187], v159 offset:32768
	ds_read_b128 v[188:191], v159 offset:33792
	ds_read_b128 v[192:195], v159 offset:34816
	ds_read_b128 v[196:199], v159 offset:35840
	ds_read_b128 v[200:203], v159 offset:36864
	ds_read_b128 v[204:207], v159 offset:37888
	ds_read_b128 v[208:211], v159 offset:38912
	ds_read_b128 v[212:215], v159 offset:39936
	global_load_lds_dwordx4 v128, s[42:43]
	v_lshl_add_u64 v[222:223], s[42:43], 0, v[132:133]
	s_mov_b32 m0, s31
	s_nop 0
	global_load_lds_dwordx4 v[222:223], off
	s_waitcnt vmcnt(8)
	s_waitcnt lgkmcnt(0)
	s_barrier
	s_setprio 1
	s_waitcnt lgkmcnt(0)
	v_mfma_f32_16x16x32_bf16 v[124:127], v[144:147], v[184:187], v[124:127]
	v_mfma_f32_16x16x32_bf16 v[120:123], v[160:163], v[184:187], v[120:123]
	v_mfma_f32_16x16x32_bf16 v[108:111], v[144:147], v[192:195], v[108:111]
	v_mfma_f32_16x16x32_bf16 v[104:107], v[160:163], v[192:195], v[104:107]
	v_mfma_f32_16x16x32_bf16 v[92:95], v[144:147], v[200:203], v[92:95]
	v_mfma_f32_16x16x32_bf16 v[88:91], v[160:163], v[200:203], v[88:91]
	v_mfma_f32_16x16x32_bf16 v[76:79], v[144:147], v[208:211], v[76:79]
	v_mfma_f32_16x16x32_bf16 v[72:75], v[160:163], v[208:211], v[72:75]
	v_mfma_f32_16x16x32_bf16 v[124:127], v[148:151], v[188:191], v[124:127]
	v_mfma_f32_16x16x32_bf16 v[120:123], v[164:167], v[188:191], v[120:123]
	v_mfma_f32_16x16x32_bf16 v[108:111], v[148:151], v[196:199], v[108:111]
	v_mfma_f32_16x16x32_bf16 v[104:107], v[164:167], v[196:199], v[104:107]
	v_mfma_f32_16x16x32_bf16 v[92:95], v[148:151], v[204:207], v[92:95]
	v_mfma_f32_16x16x32_bf16 v[88:91], v[164:167], v[204:207], v[88:91]
	v_mfma_f32_16x16x32_bf16 v[76:79], v[148:151], v[212:215], v[76:79]
	v_mfma_f32_16x16x32_bf16 v[72:75], v[164:167], v[212:215], v[72:75]
	v_mfma_f32_16x16x32_bf16 v[116:119], v[168:171], v[184:187], v[116:119]
	v_mfma_f32_16x16x32_bf16 v[112:115], v[176:179], v[184:187], v[112:115]
	v_mfma_f32_16x16x32_bf16 v[100:103], v[168:171], v[192:195], v[100:103]
	v_mfma_f32_16x16x32_bf16 v[96:99], v[176:179], v[192:195], v[96:99]
	v_mfma_f32_16x16x32_bf16 v[84:87], v[168:171], v[200:203], v[84:87]
	v_mfma_f32_16x16x32_bf16 v[80:83], v[176:179], v[200:203], v[80:83]
	v_mfma_f32_16x16x32_bf16 v[68:71], v[168:171], v[208:211], v[68:71]
	v_mfma_f32_16x16x32_bf16 v[64:67], v[176:179], v[208:211], v[64:67]
	v_mfma_f32_16x16x32_bf16 v[116:119], v[172:175], v[188:191], v[116:119]
	v_mfma_f32_16x16x32_bf16 v[112:115], v[180:183], v[188:191], v[112:115]
	v_mfma_f32_16x16x32_bf16 v[100:103], v[172:175], v[196:199], v[100:103]
	v_mfma_f32_16x16x32_bf16 v[96:99], v[180:183], v[196:199], v[96:99]
	v_mfma_f32_16x16x32_bf16 v[84:87], v[172:175], v[204:207], v[84:87]
	v_mfma_f32_16x16x32_bf16 v[80:83], v[180:183], v[204:207], v[80:83]
	v_mfma_f32_16x16x32_bf16 v[68:71], v[172:175], v[212:215], v[68:71]
	v_mfma_f32_16x16x32_bf16 v[64:67], v[180:183], v[212:215], v[64:67]
	s_setprio 0
	s_barrier
	s_add_i32 s3, s3, s18
	s_add_u32 s42, s88, 0x80
	s_addc_u32 s43, s89, 0
	s_mov_b32 m0, s3
	ds_read_b128 v[184:187], v159 offset:49152
	ds_read_b128 v[188:191], v159 offset:50176
	ds_read_b128 v[192:195], v159 offset:51200
	ds_read_b128 v[196:199], v159 offset:52224
	ds_read_b128 v[200:203], v159 offset:53248
	ds_read_b128 v[204:207], v159 offset:54272
	ds_read_b128 v[208:211], v159 offset:55296
	ds_read_b128 v[212:215], v159 offset:56320
	global_load_lds_dwordx4 v130, s[42:43]
	s_add_i32 m0, s3, 0x2000
	s_add_i32 s3, s44, s18
	global_load_lds_dwordx4 v134, s[42:43]
	s_add_u32 s42, s42, 0x20000
	s_addc_u32 s43, s43, 0
	s_mov_b32 m0, s3
	s_nop 0
	global_load_lds_dwordx4 v130, s[42:43]
	s_add_i32 m0, s3, 0x2000
	s_nop 0
	global_load_lds_dwordx4 v134, s[42:43]
	s_add_u32 s90, s90, 0x80
	s_addc_u32 s91, s91, 0
	s_mov_b32 m0, s58
	s_nop 0
	global_load_lds_dwordx4 v128, s[90:91]
	s_mov_b32 m0, s59
	s_nop 0
	global_load_lds_dwordx4 v132, s[90:91]
	s_waitcnt vmcnt(8)
	s_waitcnt lgkmcnt(0)
	s_barrier
	s_setprio 1
	s_waitcnt lgkmcnt(0)
	v_mfma_f32_16x16x32_bf16 v[60:63], v[144:147], v[184:187], v[60:63]
	v_mfma_f32_16x16x32_bf16 v[56:59], v[160:163], v[184:187], v[56:59]
	v_mfma_f32_16x16x32_bf16 v[44:47], v[144:147], v[192:195], v[44:47]
	v_mfma_f32_16x16x32_bf16 v[40:43], v[160:163], v[192:195], v[40:43]
	v_mfma_f32_16x16x32_bf16 v[28:31], v[144:147], v[200:203], v[28:31]
	v_mfma_f32_16x16x32_bf16 v[24:27], v[160:163], v[200:203], v[24:27]
	v_mfma_f32_16x16x32_bf16 v[12:15], v[144:147], v[208:211], v[12:15]
	v_mfma_f32_16x16x32_bf16 v[8:11], v[160:163], v[208:211], v[8:11]
	v_mfma_f32_16x16x32_bf16 v[60:63], v[148:151], v[188:191], v[60:63]
	v_mfma_f32_16x16x32_bf16 v[56:59], v[164:167], v[188:191], v[56:59]
	v_mfma_f32_16x16x32_bf16 v[44:47], v[148:151], v[196:199], v[44:47]
	v_mfma_f32_16x16x32_bf16 v[40:43], v[164:167], v[196:199], v[40:43]
	v_mfma_f32_16x16x32_bf16 v[28:31], v[148:151], v[204:207], v[28:31]
	v_mfma_f32_16x16x32_bf16 v[24:27], v[164:167], v[204:207], v[24:27]
	v_mfma_f32_16x16x32_bf16 v[12:15], v[148:151], v[212:215], v[12:15]
	v_mfma_f32_16x16x32_bf16 v[8:11], v[164:167], v[212:215], v[8:11]
	v_mfma_f32_16x16x32_bf16 v[52:55], v[168:171], v[184:187], v[52:55]
	v_mfma_f32_16x16x32_bf16 v[48:51], v[176:179], v[184:187], v[48:51]
	v_mfma_f32_16x16x32_bf16 v[36:39], v[168:171], v[192:195], v[36:39]
	v_mfma_f32_16x16x32_bf16 v[32:35], v[176:179], v[192:195], v[32:35]
	v_mfma_f32_16x16x32_bf16 v[20:23], v[168:171], v[200:203], v[20:23]
	v_mfma_f32_16x16x32_bf16 v[16:19], v[176:179], v[200:203], v[16:19]
	v_mfma_f32_16x16x32_bf16 v[4:7], v[168:171], v[208:211], v[4:7]
	v_mfma_f32_16x16x32_bf16 v[0:3], v[176:179], v[208:211], v[0:3]
	v_mfma_f32_16x16x32_bf16 v[52:55], v[172:175], v[188:191], v[52:55]
	v_mfma_f32_16x16x32_bf16 v[48:51], v[180:183], v[188:191], v[48:51]
	v_mfma_f32_16x16x32_bf16 v[36:39], v[172:175], v[196:199], v[36:39]
	v_mfma_f32_16x16x32_bf16 v[32:35], v[180:183], v[196:199], v[32:35]
	v_mfma_f32_16x16x32_bf16 v[20:23], v[172:175], v[204:207], v[20:23]
	v_mfma_f32_16x16x32_bf16 v[16:19], v[180:183], v[204:207], v[16:19]
	v_mfma_f32_16x16x32_bf16 v[4:7], v[172:175], v[212:215], v[4:7]
	v_mfma_f32_16x16x32_bf16 v[0:3], v[180:183], v[212:215], v[0:3]
	s_setprio 0
	s_barrier
	s_add_i32 s37, s37, 2
	s_add_u32 s34, s34, 0x100
	s_addc_u32 s35, s35, 0
	s_add_u32 s33, s33, 0x100
	s_addc_u32 s36, s36, 0
	s_cmp_gt_u32 s37, 5
	s_cbranch_scc0 .LBB0_563
	s_and_b64 vcc, exec, s[14:15]
	s_cbranch_vccz .LBB0_566
	s_barrier

.LBB0_639:
	ds_read_b128 v[140:143], v149
	ds_read_b128 v[152:155], v149 offset:1024
	ds_read_b128 v[156:159], v149 offset:2048
	ds_read_b128 v[160:163], v149 offset:3072
	ds_read_b128 v[164:167], v150
	ds_read_b128 v[168:171], v150 offset:1024
	ds_read_b128 v[172:175], v150 offset:2048
	ds_read_b128 v[176:179], v150 offset:3072
	s_add_u32 s3, s86, 0xfff80080
	s_addc_u32 s33, s87, -1
	s_cmp_eq_u32 s27, 28
	s_cselect_b32 s91, s0, s33
	s_cselect_b32 s90, s1, s3
	s_cselect_b32 s89, s15, s24
	s_cselect_b32 s88, s17, s19
	s_add_i32 m0, s30, 0xc000
	ds_read_b128 v[180:183], v151
	ds_read_b128 v[184:187], v151 offset:1024
	ds_read_b128 v[188:191], v151 offset:2048
	ds_read_b128 v[192:195], v151 offset:3072
	ds_read_b128 v[196:199], v151 offset:4096
	ds_read_b128 v[200:203], v151 offset:5120
	ds_read_b128 v[204:207], v151 offset:6144
	ds_read_b128 v[208:211], v151 offset:7168
	global_load_lds_dwordx4 v132, s[86:87]
	s_add_i32 m0, s30, 0xe000
	s_nop 0
	global_load_lds_dwordx4 v134, s[86:87]
	s_waitcnt vmcnt(8)
	s_waitcnt lgkmcnt(0)
	s_barrier
	s_setprio 1
	s_waitcnt lgkmcnt(0)
	v_mfma_f32_16x16x32_bf16 v[124:127], v[140:143], v[180:183], v[124:127]
	v_mfma_f32_16x16x32_bf16 v[120:123], v[156:159], v[180:183], v[120:123]
	v_mfma_f32_16x16x32_bf16 v[108:111], v[140:143], v[188:191], v[108:111]
	v_mfma_f32_16x16x32_bf16 v[104:107], v[156:159], v[188:191], v[104:107]
	v_mfma_f32_16x16x32_bf16 v[92:95], v[140:143], v[196:199], v[92:95]
	v_mfma_f32_16x16x32_bf16 v[88:91], v[156:159], v[196:199], v[88:91]
	v_mfma_f32_16x16x32_bf16 v[76:79], v[140:143], v[204:207], v[76:79]
	v_mfma_f32_16x16x32_bf16 v[72:75], v[156:159], v[204:207], v[72:75]
	v_mfma_f32_16x16x32_bf16 v[124:127], v[152:155], v[184:187], v[124:127]
	v_mfma_f32_16x16x32_bf16 v[120:123], v[160:163], v[184:187], v[120:123]
	v_mfma_f32_16x16x32_bf16 v[108:111], v[152:155], v[192:195], v[108:111]
	v_mfma_f32_16x16x32_bf16 v[104:107], v[160:163], v[192:195], v[104:107]
	v_mfma_f32_16x16x32_bf16 v[92:95], v[152:155], v[200:203], v[92:95]
	v_mfma_f32_16x16x32_bf16 v[88:91], v[160:163], v[200:203], v[88:91]
	v_mfma_f32_16x16x32_bf16 v[76:79], v[152:155], v[208:211], v[76:79]
	v_mfma_f32_16x16x32_bf16 v[72:75], v[160:163], v[208:211], v[72:75]
	v_mfma_f32_16x16x32_bf16 v[116:119], v[164:167], v[180:183], v[116:119]
	v_mfma_f32_16x16x32_bf16 v[112:115], v[172:175], v[180:183], v[112:115]
	v_mfma_f32_16x16x32_bf16 v[100:103], v[164:167], v[188:191], v[100:103]
	v_mfma_f32_16x16x32_bf16 v[96:99], v[172:175], v[188:191], v[96:99]
	v_mfma_f32_16x16x32_bf16 v[84:87], v[164:167], v[196:199], v[84:87]
	v_mfma_f32_16x16x32_bf16 v[80:83], v[172:175], v[196:199], v[80:83]
	v_mfma_f32_16x16x32_bf16 v[68:71], v[164:167], v[204:207], v[68:71]
	v_mfma_f32_16x16x32_bf16 v[64:67], v[172:175], v[204:207], v[64:67]
	v_mfma_f32_16x16x32_bf16 v[116:119], v[168:171], v[184:187], v[116:119]
	v_mfma_f32_16x16x32_bf16 v[112:115], v[176:179], v[184:187], v[112:115]
	v_mfma_f32_16x16x32_bf16 v[100:103], v[168:171], v[192:195], v[100:103]
	v_mfma_f32_16x16x32_bf16 v[96:99], v[176:179], v[192:195], v[96:99]
	v_mfma_f32_16x16x32_bf16 v[84:87], v[168:171], v[200:203], v[84:87]
	v_mfma_f32_16x16x32_bf16 v[80:83], v[176:179], v[200:203], v[80:83]
	v_mfma_f32_16x16x32_bf16 v[68:71], v[168:171], v[208:211], v[68:71]
	v_mfma_f32_16x16x32_bf16 v[64:67], v[176:179], v[208:211], v[64:67]
	s_setprio 0
	s_barrier
	s_add_i32 s3, s59, s25
	s_mov_b32 m0, s3
	ds_read_b128 v[180:183], v151 offset:16384
	ds_read_b128 v[184:187], v151 offset:17408
	ds_read_b128 v[188:191], v151 offset:18432
	ds_read_b128 v[192:195], v151 offset:19456
	ds_read_b128 v[196:199], v151 offset:20480
	ds_read_b128 v[200:203], v151 offset:21504
	ds_read_b128 v[204:207], v151 offset:22528
	ds_read_b128 v[208:211], v151 offset:23552
	global_load_lds_dwordx4 v128, s[88:89]
	s_add_i32 m0, s3, 0x2000
	s_add_u32 s36, s88, 0x80000
	s_addc_u32 s37, s89, 0
	s_add_i32 s3, s68, s25
	global_load_lds_dwordx4 v130, s[88:89]
	s_mov_b32 m0, s3
	s_nop 0
	global_load_lds_dwordx4 v128, s[36:37]
	s_add_i32 m0, s3, 0x2000
	s_nop 0
	global_load_lds_dwordx4 v130, s[36:37]
	s_mov_b32 m0, s30
	s_nop 0
	global_load_lds_dwordx4 v128, s[90:91]
	s_mov_b32 m0, s31
	s_nop 0
	global_load_lds_dwordx4 v130, s[90:91]
	s_waitcnt vmcnt(8)
	s_waitcnt lgkmcnt(0)
	s_barrier
	s_setprio 1
	s_waitcnt lgkmcnt(0)
	v_mfma_f32_16x16x32_bf16 v[60:63], v[140:143], v[180:183], v[60:63]
	v_mfma_f32_16x16x32_bf16 v[56:59], v[156:159], v[180:183], v[56:59]
	v_mfma_f32_16x16x32_bf16 v[44:47], v[140:143], v[188:191], v[44:47]
	v_mfma_f32_16x16x32_bf16 v[40:43], v[156:159], v[188:191], v[40:43]
	v_mfma_f32_16x16x32_bf16 v[28:31], v[140:143], v[196:199], v[28:31]
	v_mfma_f32_16x16x32_bf16 v[24:27], v[156:159], v[196:199], v[24:27]
	v_mfma_f32_16x16x32_bf16 v[12:15], v[140:143], v[204:207], v[12:15]
	v_mfma_f32_16x16x32_bf16 v[8:11], v[156:159], v[204:207], v[8:11]
	v_mfma_f32_16x16x32_bf16 v[60:63], v[152:155], v[184:187], v[60:63]
	v_mfma_f32_16x16x32_bf16 v[56:59], v[160:163], v[184:187], v[56:59]
	v_mfma_f32_16x16x32_bf16 v[44:47], v[152:155], v[192:195], v[44:47]
	v_mfma_f32_16x16x32_bf16 v[40:43], v[160:163], v[192:195], v[40:43]
	v_mfma_f32_16x16x32_bf16 v[28:31], v[152:155], v[200:203], v[28:31]
	v_mfma_f32_16x16x32_bf16 v[24:27], v[160:163], v[200:203], v[24:27]
	v_mfma_f32_16x16x32_bf16 v[12:15], v[152:155], v[208:211], v[12:15]
	v_mfma_f32_16x16x32_bf16 v[8:11], v[160:163], v[208:211], v[8:11]
	v_mfma_f32_16x16x32_bf16 v[52:55], v[164:167], v[180:183], v[52:55]
	v_mfma_f32_16x16x32_bf16 v[48:51], v[172:175], v[180:183], v[48:51]
	v_mfma_f32_16x16x32_bf16 v[36:39], v[164:167], v[188:191], v[36:39]
	v_mfma_f32_16x16x32_bf16 v[32:35], v[172:175], v[188:191], v[32:35]
	v_mfma_f32_16x16x32_bf16 v[20:23], v[164:167], v[196:199], v[20:23]
	v_mfma_f32_16x16x32_bf16 v[16:19], v[172:175], v[196:199], v[16:19]
	v_mfma_f32_16x16x32_bf16 v[4:7], v[164:167], v[204:207], v[4:7]
	v_mfma_f32_16x16x32_bf16 v[0:3], v[172:175], v[204:207], v[0:3]
	v_mfma_f32_16x16x32_bf16 v[52:55], v[168:171], v[184:187], v[52:55]
	v_mfma_f32_16x16x32_bf16 v[48:51], v[176:179], v[184:187], v[48:51]
	v_mfma_f32_16x16x32_bf16 v[36:39], v[168:171], v[192:195], v[36:39]
	v_mfma_f32_16x16x32_bf16 v[32:35], v[176:179], v[192:195], v[32:35]
	v_mfma_f32_16x16x32_bf16 v[20:23], v[168:171], v[200:203], v[20:23]
	v_mfma_f32_16x16x32_bf16 v[16:19], v[176:179], v[200:203], v[16:19]
	v_mfma_f32_16x16x32_bf16 v[4:7], v[168:171], v[208:211], v[4:7]
	v_mfma_f32_16x16x32_bf16 v[0:3], v[176:179], v[208:211], v[0:3]
	s_setprio 0
	s_barrier
	s_add_i32 s3, 0, 0x18000
	s_add_i32 s33, 0, 0x1c000
	v_add_u32_e32 v160, s3, v147
	v_add_u32_e32 v176, s33, v147
	ds_read_b128 v[140:143], v160
	ds_read_b128 v[152:155], v160 offset:1024
	ds_read_b128 v[156:159], v160 offset:2048
	ds_read_b128 v[160:163], v160 offset:3072
	ds_read_b128 v[164:167], v176
	ds_read_b128 v[168:171], v176 offset:1024
	ds_read_b128 v[172:175], v176 offset:2048
	ds_read_b128 v[176:179], v176 offset:3072
	s_add_u32 s36, s90, 0x80000
	s_addc_u32 s37, s91, 0
	s_mov_b32 m0, s48
	ds_read_b128 v[180:183], v151 offset:32768
	ds_read_b128 v[184:187], v151 offset:33792
	ds_read_b128 v[188:191], v151 offset:34816
	ds_read_b128 v[192:195], v151 offset:35840
	ds_read_b128 v[196:199], v151 offset:36864
	ds_read_b128 v[200:203], v151 offset:37888
	ds_read_b128 v[204:207], v151 offset:38912
	ds_read_b128 v[208:211], v151 offset:39936
	global_load_lds_dwordx4 v128, s[36:37]
	v_lshl_add_u64 v[218:219], s[36:37], 0, v[130:131]
	s_mov_b32 m0, s49
	s_nop 0
	global_load_lds_dwordx4 v[218:219], off
	s_waitcnt vmcnt(8)
	s_waitcnt lgkmcnt(0)
	s_barrier
	s_setprio 1
	s_waitcnt lgkmcnt(0)
	v_mfma_f32_16x16x32_bf16 v[124:127], v[140:143], v[180:183], v[124:127]
	v_mfma_f32_16x16x32_bf16 v[120:123], v[156:159], v[180:183], v[120:123]
	v_mfma_f32_16x16x32_bf16 v[108:111], v[140:143], v[188:191], v[108:111]
	v_mfma_f32_16x16x32_bf16 v[104:107], v[156:159], v[188:191], v[104:107]
	v_mfma_f32_16x16x32_bf16 v[92:95], v[140:143], v[196:199], v[92:95]
	v_mfma_f32_16x16x32_bf16 v[88:91], v[156:159], v[196:199], v[88:91]
	v_mfma_f32_16x16x32_bf16 v[76:79], v[140:143], v[204:207], v[76:79]
	v_mfma_f32_16x16x32_bf16 v[72:75], v[156:159], v[204:207], v[72:75]
	v_mfma_f32_16x16x32_bf16 v[124:127], v[152:155], v[184:187], v[124:127]
	v_mfma_f32_16x16x32_bf16 v[120:123], v[160:163], v[184:187], v[120:123]
	v_mfma_f32_16x16x32_bf16 v[108:111], v[152:155], v[192:195], v[108:111]
	v_mfma_f32_16x16x32_bf16 v[104:107], v[160:163], v[192:195], v[104:107]
	v_mfma_f32_16x16x32_bf16 v[92:95], v[152:155], v[200:203], v[92:95]
	v_mfma_f32_16x16x32_bf16 v[88:91], v[160:163], v[200:203], v[88:91]
	v_mfma_f32_16x16x32_bf16 v[76:79], v[152:155], v[208:211], v[76:79]
	v_mfma_f32_16x16x32_bf16 v[72:75], v[160:163], v[208:211], v[72:75]
	v_mfma_f32_16x16x32_bf16 v[116:119], v[164:167], v[180:183], v[116:119]
	v_mfma_f32_16x16x32_bf16 v[112:115], v[172:175], v[180:183], v[112:115]
	v_mfma_f32_16x16x32_bf16 v[100:103], v[164:167], v[188:191], v[100:103]
	v_mfma_f32_16x16x32_bf16 v[96:99], v[172:175], v[188:191], v[96:99]
	v_mfma_f32_16x16x32_bf16 v[84:87], v[164:167], v[196:199], v[84:87]
	v_mfma_f32_16x16x32_bf16 v[80:83], v[172:175], v[196:199], v[80:83]
	v_mfma_f32_16x16x32_bf16 v[68:71], v[164:167], v[204:207], v[68:71]
	v_mfma_f32_16x16x32_bf16 v[64:67], v[172:175], v[204:207], v[64:67]
	v_mfma_f32_16x16x32_bf16 v[116:119], v[168:171], v[184:187], v[116:119]
	v_mfma_f32_16x16x32_bf16 v[112:115], v[176:179], v[184:187], v[112:115]
	v_mfma_f32_16x16x32_bf16 v[100:103], v[168:171], v[192:195], v[100:103]
	v_mfma_f32_16x16x32_bf16 v[96:99], v[176:179], v[192:195], v[96:99]
	v_mfma_f32_16x16x32_bf16 v[84:87], v[168:171], v[200:203], v[84:87]
	v_mfma_f32_16x16x32_bf16 v[80:83], v[176:179], v[200:203], v[80:83]
	v_mfma_f32_16x16x32_bf16 v[68:71], v[168:171], v[208:211], v[68:71]
	v_mfma_f32_16x16x32_bf16 v[64:67], v[176:179], v[208:211], v[64:67]
	s_setprio 0
	s_barrier
	s_add_i32 s3, s3, s25
	s_add_u32 s36, s88, 0x80
	s_addc_u32 s37, s89, 0
	s_mov_b32 m0, s3
	ds_read_b128 v[180:183], v151 offset:49152
	ds_read_b128 v[184:187], v151 offset:50176
	ds_read_b128 v[188:191], v151 offset:51200
	ds_read_b128 v[192:195], v151 offset:52224
	ds_read_b128 v[196:199], v151 offset:53248
	ds_read_b128 v[200:203], v151 offset:54272
	ds_read_b128 v[204:207], v151 offset:55296
	ds_read_b128 v[208:211], v151 offset:56320
	global_load_lds_dwordx4 v128, s[36:37]
	s_add_i32 m0, s3, 0x2000
	s_add_i32 s3, s33, s25
	global_load_lds_dwordx4 v130, s[36:37]
	s_add_u32 s36, s36, 0x80000
	s_addc_u32 s37, s37, 0
	s_mov_b32 m0, s3
	s_nop 0
	global_load_lds_dwordx4 v128, s[36:37]
	s_add_i32 m0, s3, 0x2000
	s_nop 0
	global_load_lds_dwordx4 v130, s[36:37]
	s_add_u32 s90, s90, 0x80
	s_addc_u32 s91, s91, 0
	s_mov_b32 m0, s57
	s_nop 0
	global_load_lds_dwordx4 v128, s[90:91]
	s_mov_b32 m0, s58
	s_nop 0
	global_load_lds_dwordx4 v130, s[90:91]
	s_waitcnt vmcnt(8)
	s_waitcnt lgkmcnt(0)
	s_barrier
	s_setprio 1
	s_waitcnt lgkmcnt(0)
	v_mfma_f32_16x16x32_bf16 v[60:63], v[140:143], v[180:183], v[60:63]
	v_mfma_f32_16x16x32_bf16 v[56:59], v[156:159], v[180:183], v[56:59]
	v_mfma_f32_16x16x32_bf16 v[44:47], v[140:143], v[188:191], v[44:47]
	v_mfma_f32_16x16x32_bf16 v[40:43], v[156:159], v[188:191], v[40:43]
	v_mfma_f32_16x16x32_bf16 v[28:31], v[140:143], v[196:199], v[28:31]
	v_mfma_f32_16x16x32_bf16 v[24:27], v[156:159], v[196:199], v[24:27]
	v_mfma_f32_16x16x32_bf16 v[12:15], v[140:143], v[204:207], v[12:15]
	v_mfma_f32_16x16x32_bf16 v[8:11], v[156:159], v[204:207], v[8:11]
	v_mfma_f32_16x16x32_bf16 v[60:63], v[152:155], v[184:187], v[60:63]
	v_mfma_f32_16x16x32_bf16 v[56:59], v[160:163], v[184:187], v[56:59]
	v_mfma_f32_16x16x32_bf16 v[44:47], v[152:155], v[192:195], v[44:47]
	v_mfma_f32_16x16x32_bf16 v[40:43], v[160:163], v[192:195], v[40:43]
	v_mfma_f32_16x16x32_bf16 v[28:31], v[152:155], v[200:203], v[28:31]
	v_mfma_f32_16x16x32_bf16 v[24:27], v[160:163], v[200:203], v[24:27]
	v_mfma_f32_16x16x32_bf16 v[12:15], v[152:155], v[208:211], v[12:15]
	v_mfma_f32_16x16x32_bf16 v[8:11], v[160:163], v[208:211], v[8:11]
	v_mfma_f32_16x16x32_bf16 v[52:55], v[164:167], v[180:183], v[52:55]
	v_mfma_f32_16x16x32_bf16 v[48:51], v[172:175], v[180:183], v[48:51]
	v_mfma_f32_16x16x32_bf16 v[36:39], v[164:167], v[188:191], v[36:39]
	v_mfma_f32_16x16x32_bf16 v[32:35], v[172:175], v[188:191], v[32:35]
	v_mfma_f32_16x16x32_bf16 v[20:23], v[164:167], v[196:199], v[20:23]
	v_mfma_f32_16x16x32_bf16 v[16:19], v[172:175], v[196:199], v[16:19]
	v_mfma_f32_16x16x32_bf16 v[4:7], v[164:167], v[204:207], v[4:7]
	v_mfma_f32_16x16x32_bf16 v[0:3], v[172:175], v[204:207], v[0:3]
	v_mfma_f32_16x16x32_bf16 v[52:55], v[168:171], v[184:187], v[52:55]
	v_mfma_f32_16x16x32_bf16 v[48:51], v[176:179], v[184:187], v[48:51]
	v_mfma_f32_16x16x32_bf16 v[36:39], v[168:171], v[192:195], v[36:39]
	v_mfma_f32_16x16x32_bf16 v[32:35], v[176:179], v[192:195], v[32:35]
	v_mfma_f32_16x16x32_bf16 v[20:23], v[168:171], v[200:203], v[20:23]
	v_mfma_f32_16x16x32_bf16 v[16:19], v[176:179], v[200:203], v[16:19]
	v_mfma_f32_16x16x32_bf16 v[4:7], v[168:171], v[208:211], v[4:7]
	v_mfma_f32_16x16x32_bf16 v[0:3], v[176:179], v[208:211], v[0:3]
	s_setprio 0
	s_barrier
	s_add_i32 s27, s27, 2
	s_add_u32 s86, s86, 0x100
	s_addc_u32 s87, s87, 0
	s_add_u32 s19, s19, 0x100
	s_addc_u32 s24, s24, 0
	s_cmp_gt_u32 s27, 29
	s_cbranch_scc0 .LBB0_639
	s_and_b64 vcc, exec, s[12:13]
	s_cbranch_vccz .LBB0_642
	s_barrier

.LBB0_770:
	ds_read_b128 v[154:157], v150
	ds_read_b128 v[158:161], v150 offset:1024
	ds_read_b128 v[162:165], v150 offset:2048
	ds_read_b128 v[166:169], v150 offset:3072
	ds_read_b128 v[170:173], v151
	ds_read_b128 v[174:177], v151 offset:1024
	ds_read_b128 v[178:181], v151 offset:2048
	ds_read_b128 v[182:185], v151 offset:3072
	s_add_u32 s3, s88, 0xfff80080
	s_addc_u32 s37, s89, -1
	s_cmp_eq_u32 s36, 28
	s_cselect_b32 s91, s0, s37
	s_cselect_b32 s90, s1, s3
	s_cselect_b32 s81, s17, s35
	s_cselect_b32 s80, s27, s33
	s_add_i32 m0, s19, 0xc000
	ds_read_b128 v[186:189], v152
	ds_read_b128 v[190:193], v152 offset:1024
	ds_read_b128 v[194:197], v152 offset:2048
	ds_read_b128 v[198:201], v152 offset:3072
	ds_read_b128 v[202:205], v152 offset:4096
	ds_read_b128 v[206:209], v152 offset:5120
	ds_read_b128 v[210:213], v152 offset:6144
	ds_read_b128 v[214:217], v152 offset:7168
	global_load_lds_dwordx4 v138, s[88:89]
	s_add_i32 m0, s19, 0xe000
	s_nop 0
	global_load_lds_dwordx4 v140, s[88:89]
	s_waitcnt vmcnt(8)
	s_waitcnt lgkmcnt(0)
	s_barrier
	s_setprio 1
	s_waitcnt lgkmcnt(0)
	v_mfma_f32_16x16x32_bf16 v[124:127], v[154:157], v[186:189], v[124:127]
	v_mfma_f32_16x16x32_bf16 v[120:123], v[162:165], v[186:189], v[120:123]
	v_mfma_f32_16x16x32_bf16 v[108:111], v[154:157], v[194:197], v[108:111]
	v_mfma_f32_16x16x32_bf16 v[104:107], v[162:165], v[194:197], v[104:107]
	v_mfma_f32_16x16x32_bf16 v[92:95], v[154:157], v[202:205], v[92:95]
	v_mfma_f32_16x16x32_bf16 v[88:91], v[162:165], v[202:205], v[88:91]
	v_mfma_f32_16x16x32_bf16 v[76:79], v[154:157], v[210:213], v[76:79]
	v_mfma_f32_16x16x32_bf16 v[72:75], v[162:165], v[210:213], v[72:75]
	v_mfma_f32_16x16x32_bf16 v[124:127], v[158:161], v[190:193], v[124:127]
	v_mfma_f32_16x16x32_bf16 v[120:123], v[166:169], v[190:193], v[120:123]
	v_mfma_f32_16x16x32_bf16 v[108:111], v[158:161], v[198:201], v[108:111]
	v_mfma_f32_16x16x32_bf16 v[104:107], v[166:169], v[198:201], v[104:107]
	v_mfma_f32_16x16x32_bf16 v[92:95], v[158:161], v[206:209], v[92:95]
	v_mfma_f32_16x16x32_bf16 v[88:91], v[166:169], v[206:209], v[88:91]
	v_mfma_f32_16x16x32_bf16 v[76:79], v[158:161], v[214:217], v[76:79]
	v_mfma_f32_16x16x32_bf16 v[72:75], v[166:169], v[214:217], v[72:75]
	v_mfma_f32_16x16x32_bf16 v[116:119], v[170:173], v[186:189], v[116:119]
	v_mfma_f32_16x16x32_bf16 v[112:115], v[178:181], v[186:189], v[112:115]
	v_mfma_f32_16x16x32_bf16 v[100:103], v[170:173], v[194:197], v[100:103]
	v_mfma_f32_16x16x32_bf16 v[96:99], v[178:181], v[194:197], v[96:99]
	v_mfma_f32_16x16x32_bf16 v[84:87], v[170:173], v[202:205], v[84:87]
	v_mfma_f32_16x16x32_bf16 v[80:83], v[178:181], v[202:205], v[80:83]
	v_mfma_f32_16x16x32_bf16 v[68:71], v[170:173], v[210:213], v[68:71]
	v_mfma_f32_16x16x32_bf16 v[64:67], v[178:181], v[210:213], v[64:67]
	v_mfma_f32_16x16x32_bf16 v[116:119], v[174:177], v[190:193], v[116:119]
	v_mfma_f32_16x16x32_bf16 v[112:115], v[182:185], v[190:193], v[112:115]
	v_mfma_f32_16x16x32_bf16 v[100:103], v[174:177], v[198:201], v[100:103]
	v_mfma_f32_16x16x32_bf16 v[96:99], v[182:185], v[198:201], v[96:99]
	v_mfma_f32_16x16x32_bf16 v[84:87], v[174:177], v[206:209], v[84:87]
	v_mfma_f32_16x16x32_bf16 v[80:83], v[182:185], v[206:209], v[80:83]
	v_mfma_f32_16x16x32_bf16 v[68:71], v[174:177], v[214:217], v[68:71]
	v_mfma_f32_16x16x32_bf16 v[64:67], v[182:185], v[214:217], v[64:67]
	s_setprio 0
	s_barrier
	s_add_i32 s3, s56, s18
	s_mov_b32 m0, s3
	ds_read_b128 v[186:189], v152 offset:16384
	ds_read_b128 v[190:193], v152 offset:17408
	ds_read_b128 v[194:197], v152 offset:18432
	ds_read_b128 v[198:201], v152 offset:19456
	ds_read_b128 v[202:205], v152 offset:20480
	ds_read_b128 v[206:209], v152 offset:21504
	ds_read_b128 v[210:213], v152 offset:22528
	ds_read_b128 v[214:217], v152 offset:23552
	global_load_lds_dwordx4 v130, s[80:81]
	s_add_i32 m0, s3, 0x2000
	s_add_u32 s42, s80, 0x80000
	s_addc_u32 s43, s81, 0
	s_add_i32 s3, s57, s18
	global_load_lds_dwordx4 v134, s[80:81]
	s_mov_b32 m0, s3
	s_nop 0
	global_load_lds_dwordx4 v130, s[42:43]
	s_add_i32 m0, s3, 0x2000
	s_nop 0
	global_load_lds_dwordx4 v134, s[42:43]
	s_mov_b32 m0, s19
	s_nop 0
	global_load_lds_dwordx4 v128, s[90:91]
	s_mov_b32 m0, s25
	s_nop 0
	global_load_lds_dwordx4 v132, s[90:91]
	s_waitcnt vmcnt(8)
	s_waitcnt lgkmcnt(0)
	s_barrier
	s_setprio 1
	s_waitcnt lgkmcnt(0)
	v_mfma_f32_16x16x32_bf16 v[60:63], v[154:157], v[186:189], v[60:63]
	v_mfma_f32_16x16x32_bf16 v[56:59], v[162:165], v[186:189], v[56:59]
	v_mfma_f32_16x16x32_bf16 v[44:47], v[154:157], v[194:197], v[44:47]
	v_mfma_f32_16x16x32_bf16 v[40:43], v[162:165], v[194:197], v[40:43]
	v_mfma_f32_16x16x32_bf16 v[28:31], v[154:157], v[202:205], v[28:31]
	v_mfma_f32_16x16x32_bf16 v[24:27], v[162:165], v[202:205], v[24:27]
	v_mfma_f32_16x16x32_bf16 v[12:15], v[154:157], v[210:213], v[12:15]
	v_mfma_f32_16x16x32_bf16 v[8:11], v[162:165], v[210:213], v[8:11]
	v_mfma_f32_16x16x32_bf16 v[60:63], v[158:161], v[190:193], v[60:63]
	v_mfma_f32_16x16x32_bf16 v[56:59], v[166:169], v[190:193], v[56:59]
	v_mfma_f32_16x16x32_bf16 v[44:47], v[158:161], v[198:201], v[44:47]
	v_mfma_f32_16x16x32_bf16 v[40:43], v[166:169], v[198:201], v[40:43]
	v_mfma_f32_16x16x32_bf16 v[28:31], v[158:161], v[206:209], v[28:31]
	v_mfma_f32_16x16x32_bf16 v[24:27], v[166:169], v[206:209], v[24:27]
	v_mfma_f32_16x16x32_bf16 v[12:15], v[158:161], v[214:217], v[12:15]
	v_mfma_f32_16x16x32_bf16 v[8:11], v[166:169], v[214:217], v[8:11]
	v_mfma_f32_16x16x32_bf16 v[52:55], v[170:173], v[186:189], v[52:55]
	v_mfma_f32_16x16x32_bf16 v[48:51], v[178:181], v[186:189], v[48:51]
	v_mfma_f32_16x16x32_bf16 v[36:39], v[170:173], v[194:197], v[36:39]
	v_mfma_f32_16x16x32_bf16 v[32:35], v[178:181], v[194:197], v[32:35]
	v_mfma_f32_16x16x32_bf16 v[20:23], v[170:173], v[202:205], v[20:23]
	v_mfma_f32_16x16x32_bf16 v[16:19], v[178:181], v[202:205], v[16:19]
	v_mfma_f32_16x16x32_bf16 v[4:7], v[170:173], v[210:213], v[4:7]
	v_mfma_f32_16x16x32_bf16 v[0:3], v[178:181], v[210:213], v[0:3]
	v_mfma_f32_16x16x32_bf16 v[52:55], v[174:177], v[190:193], v[52:55]
	v_mfma_f32_16x16x32_bf16 v[48:51], v[182:185], v[190:193], v[48:51]
	v_mfma_f32_16x16x32_bf16 v[36:39], v[174:177], v[198:201], v[36:39]
	v_mfma_f32_16x16x32_bf16 v[32:35], v[182:185], v[198:201], v[32:35]
	v_mfma_f32_16x16x32_bf16 v[20:23], v[174:177], v[206:209], v[20:23]
	v_mfma_f32_16x16x32_bf16 v[16:19], v[182:185], v[206:209], v[16:19]
	v_mfma_f32_16x16x32_bf16 v[4:7], v[174:177], v[214:217], v[4:7]
	v_mfma_f32_16x16x32_bf16 v[0:3], v[182:185], v[214:217], v[0:3]
	s_setprio 0
	s_barrier
	s_add_i32 s3, 0, 0x18000
	v_add_u32_e32 v153, s3, v149
	s_add_i32 s37, 0, 0x1c000
	ds_read_b128 v[154:157], v153
	ds_read_b128 v[158:161], v153 offset:1024
	ds_read_b128 v[162:165], v153 offset:2048
	ds_read_b128 v[166:169], v153 offset:3072
	v_add_u32_e32 v153, s37, v149
	ds_read_b128 v[170:173], v153
	ds_read_b128 v[174:177], v153 offset:1024
	ds_read_b128 v[178:181], v153 offset:2048
	ds_read_b128 v[182:185], v153 offset:3072
	s_add_u32 s42, s90, 0x80000
	s_addc_u32 s43, s91, 0
	s_mov_b32 m0, s30
	ds_read_b128 v[186:189], v152 offset:32768
	ds_read_b128 v[190:193], v152 offset:33792
	ds_read_b128 v[194:197], v152 offset:34816
	ds_read_b128 v[198:201], v152 offset:35840
	ds_read_b128 v[202:205], v152 offset:36864
	ds_read_b128 v[206:209], v152 offset:37888
	ds_read_b128 v[210:213], v152 offset:38912
	ds_read_b128 v[214:217], v152 offset:39936
	global_load_lds_dwordx4 v128, s[42:43]
	v_lshl_add_u64 v[224:225], s[42:43], 0, v[132:133]
	s_mov_b32 m0, s31
	s_nop 0
	global_load_lds_dwordx4 v[224:225], off
	s_waitcnt vmcnt(8)
	s_waitcnt lgkmcnt(0)
	s_barrier
	s_setprio 1
	s_waitcnt lgkmcnt(0)
	v_mfma_f32_16x16x32_bf16 v[124:127], v[154:157], v[186:189], v[124:127]
	v_mfma_f32_16x16x32_bf16 v[120:123], v[162:165], v[186:189], v[120:123]
	v_mfma_f32_16x16x32_bf16 v[108:111], v[154:157], v[194:197], v[108:111]
	v_mfma_f32_16x16x32_bf16 v[104:107], v[162:165], v[194:197], v[104:107]
	v_mfma_f32_16x16x32_bf16 v[92:95], v[154:157], v[202:205], v[92:95]
	v_mfma_f32_16x16x32_bf16 v[88:91], v[162:165], v[202:205], v[88:91]
	v_mfma_f32_16x16x32_bf16 v[76:79], v[154:157], v[210:213], v[76:79]
	v_mfma_f32_16x16x32_bf16 v[72:75], v[162:165], v[210:213], v[72:75]
	v_mfma_f32_16x16x32_bf16 v[124:127], v[158:161], v[190:193], v[124:127]
	v_mfma_f32_16x16x32_bf16 v[120:123], v[166:169], v[190:193], v[120:123]
	v_mfma_f32_16x16x32_bf16 v[108:111], v[158:161], v[198:201], v[108:111]
	v_mfma_f32_16x16x32_bf16 v[104:107], v[166:169], v[198:201], v[104:107]
	v_mfma_f32_16x16x32_bf16 v[92:95], v[158:161], v[206:209], v[92:95]
	v_mfma_f32_16x16x32_bf16 v[88:91], v[166:169], v[206:209], v[88:91]
	v_mfma_f32_16x16x32_bf16 v[76:79], v[158:161], v[214:217], v[76:79]
	v_mfma_f32_16x16x32_bf16 v[72:75], v[166:169], v[214:217], v[72:75]
	v_mfma_f32_16x16x32_bf16 v[116:119], v[170:173], v[186:189], v[116:119]
	v_mfma_f32_16x16x32_bf16 v[112:115], v[178:181], v[186:189], v[112:115]
	v_mfma_f32_16x16x32_bf16 v[100:103], v[170:173], v[194:197], v[100:103]
	v_mfma_f32_16x16x32_bf16 v[96:99], v[178:181], v[194:197], v[96:99]
	v_mfma_f32_16x16x32_bf16 v[84:87], v[170:173], v[202:205], v[84:87]
	v_mfma_f32_16x16x32_bf16 v[80:83], v[178:181], v[202:205], v[80:83]
	v_mfma_f32_16x16x32_bf16 v[68:71], v[170:173], v[210:213], v[68:71]
	v_mfma_f32_16x16x32_bf16 v[64:67], v[178:181], v[210:213], v[64:67]
	v_mfma_f32_16x16x32_bf16 v[116:119], v[174:177], v[190:193], v[116:119]
	v_mfma_f32_16x16x32_bf16 v[112:115], v[182:185], v[190:193], v[112:115]
	v_mfma_f32_16x16x32_bf16 v[100:103], v[174:177], v[198:201], v[100:103]
	v_mfma_f32_16x16x32_bf16 v[96:99], v[182:185], v[198:201], v[96:99]
	v_mfma_f32_16x16x32_bf16 v[84:87], v[174:177], v[206:209], v[84:87]
	v_mfma_f32_16x16x32_bf16 v[80:83], v[182:185], v[206:209], v[80:83]
	v_mfma_f32_16x16x32_bf16 v[68:71], v[174:177], v[214:217], v[68:71]
	v_mfma_f32_16x16x32_bf16 v[64:67], v[182:185], v[214:217], v[64:67]
	s_setprio 0
	s_barrier
	s_add_i32 s3, s3, s18
	s_add_u32 s42, s80, 0x80
	s_addc_u32 s43, s81, 0
	s_mov_b32 m0, s3
	ds_read_b128 v[186:189], v152 offset:49152
	ds_read_b128 v[190:193], v152 offset:50176
	ds_read_b128 v[194:197], v152 offset:51200
	ds_read_b128 v[198:201], v152 offset:52224
	ds_read_b128 v[202:205], v152 offset:53248
	ds_read_b128 v[206:209], v152 offset:54272
	ds_read_b128 v[210:213], v152 offset:55296
	ds_read_b128 v[214:217], v152 offset:56320
	global_load_lds_dwordx4 v130, s[42:43]
	s_add_i32 m0, s3, 0x2000
	s_add_i32 s3, s37, s18
	global_load_lds_dwordx4 v134, s[42:43]
	s_add_u32 s42, s42, 0x80000
	s_addc_u32 s43, s43, 0
	s_mov_b32 m0, s3
	s_nop 0
	global_load_lds_dwordx4 v130, s[42:43]
	s_add_i32 m0, s3, 0x2000
	s_nop 0
	global_load_lds_dwordx4 v134, s[42:43]
	s_add_u32 s90, s90, 0x80
	s_addc_u32 s91, s91, 0
	s_mov_b32 m0, s48
	s_nop 0
	global_load_lds_dwordx4 v128, s[90:91]
	s_mov_b32 m0, s49
	s_nop 0
	global_load_lds_dwordx4 v132, s[90:91]
	s_waitcnt vmcnt(8)
	s_waitcnt lgkmcnt(0)
	s_barrier
	s_setprio 1
	s_waitcnt lgkmcnt(0)
	v_mfma_f32_16x16x32_bf16 v[60:63], v[154:157], v[186:189], v[60:63]
	v_mfma_f32_16x16x32_bf16 v[56:59], v[162:165], v[186:189], v[56:59]
	v_mfma_f32_16x16x32_bf16 v[44:47], v[154:157], v[194:197], v[44:47]
	v_mfma_f32_16x16x32_bf16 v[40:43], v[162:165], v[194:197], v[40:43]
	v_mfma_f32_16x16x32_bf16 v[28:31], v[154:157], v[202:205], v[28:31]
	v_mfma_f32_16x16x32_bf16 v[24:27], v[162:165], v[202:205], v[24:27]
	v_mfma_f32_16x16x32_bf16 v[12:15], v[154:157], v[210:213], v[12:15]
	v_mfma_f32_16x16x32_bf16 v[8:11], v[162:165], v[210:213], v[8:11]
	v_mfma_f32_16x16x32_bf16 v[60:63], v[158:161], v[190:193], v[60:63]
	v_mfma_f32_16x16x32_bf16 v[56:59], v[166:169], v[190:193], v[56:59]
	v_mfma_f32_16x16x32_bf16 v[44:47], v[158:161], v[198:201], v[44:47]
	v_mfma_f32_16x16x32_bf16 v[40:43], v[166:169], v[198:201], v[40:43]
	v_mfma_f32_16x16x32_bf16 v[28:31], v[158:161], v[206:209], v[28:31]
	v_mfma_f32_16x16x32_bf16 v[24:27], v[166:169], v[206:209], v[24:27]
	v_mfma_f32_16x16x32_bf16 v[12:15], v[158:161], v[214:217], v[12:15]
	v_mfma_f32_16x16x32_bf16 v[8:11], v[166:169], v[214:217], v[8:11]
	v_mfma_f32_16x16x32_bf16 v[52:55], v[170:173], v[186:189], v[52:55]
	v_mfma_f32_16x16x32_bf16 v[48:51], v[178:181], v[186:189], v[48:51]
	v_mfma_f32_16x16x32_bf16 v[36:39], v[170:173], v[194:197], v[36:39]
	v_mfma_f32_16x16x32_bf16 v[32:35], v[178:181], v[194:197], v[32:35]
	v_mfma_f32_16x16x32_bf16 v[20:23], v[170:173], v[202:205], v[20:23]
	v_mfma_f32_16x16x32_bf16 v[16:19], v[178:181], v[202:205], v[16:19]
	v_mfma_f32_16x16x32_bf16 v[4:7], v[170:173], v[210:213], v[4:7]
	v_mfma_f32_16x16x32_bf16 v[0:3], v[178:181], v[210:213], v[0:3]
	v_mfma_f32_16x16x32_bf16 v[52:55], v[174:177], v[190:193], v[52:55]
	v_mfma_f32_16x16x32_bf16 v[48:51], v[182:185], v[190:193], v[48:51]
	v_mfma_f32_16x16x32_bf16 v[36:39], v[174:177], v[198:201], v[36:39]
	v_mfma_f32_16x16x32_bf16 v[32:35], v[182:185], v[198:201], v[32:35]
	v_mfma_f32_16x16x32_bf16 v[20:23], v[174:177], v[206:209], v[20:23]
	v_mfma_f32_16x16x32_bf16 v[16:19], v[182:185], v[206:209], v[16:19]
	v_mfma_f32_16x16x32_bf16 v[4:7], v[174:177], v[214:217], v[4:7]
	v_mfma_f32_16x16x32_bf16 v[0:3], v[182:185], v[214:217], v[0:3]
	s_setprio 0
	s_barrier
	s_add_i32 s36, s36, 2
	s_add_u32 s88, s88, 0x100
	s_addc_u32 s89, s89, 0
	s_add_u32 s33, s33, 0x100
	s_addc_u32 s35, s35, 0
	s_cmp_gt_u32 s36, 29
	s_cbranch_scc0 .LBB0_770
	s_and_b64 vcc, exec, s[14:15]
	s_cbranch_vccz .LBB0_773
	s_barrier

.LBB0_846:
	ds_read_b128 v[140:143], v149
	ds_read_b128 v[152:155], v149 offset:1024
	ds_read_b128 v[156:159], v149 offset:2048
	ds_read_b128 v[160:163], v149 offset:3072
	ds_read_b128 v[164:167], v150
	ds_read_b128 v[168:171], v150 offset:1024
	ds_read_b128 v[172:175], v150 offset:2048
	ds_read_b128 v[176:179], v150 offset:3072
	s_add_u32 s3, s84, 0xffe00080
	s_addc_u32 s37, s85, -1
	s_cmpk_eq_i32 s36, 0x7c
	s_cselect_b32 s87, s0, s37
	s_cselect_b32 s86, s1, s3
	s_cselect_b32 s81, s15, s33
	s_cselect_b32 s80, s17, s27
	s_add_i32 m0, s19, 0xc000
	ds_read_b128 v[180:183], v151
	ds_read_b128 v[184:187], v151 offset:1024
	ds_read_b128 v[188:191], v151 offset:2048
	ds_read_b128 v[192:195], v151 offset:3072
	ds_read_b128 v[196:199], v151 offset:4096
	ds_read_b128 v[200:203], v151 offset:5120
	ds_read_b128 v[204:207], v151 offset:6144
	ds_read_b128 v[208:211], v151 offset:7168
	global_load_lds_dwordx4 v132, s[84:85]
	s_add_i32 m0, s19, 0xe000
	s_nop 0
	global_load_lds_dwordx4 v134, s[84:85]
	s_waitcnt vmcnt(8)
	s_waitcnt lgkmcnt(0)
	s_barrier
	s_setprio 1
	s_waitcnt lgkmcnt(0)
	v_mfma_f32_16x16x32_bf16 v[124:127], v[140:143], v[180:183], v[124:127]
	v_mfma_f32_16x16x32_bf16 v[120:123], v[156:159], v[180:183], v[120:123]
	v_mfma_f32_16x16x32_bf16 v[112:115], v[140:143], v[188:191], v[112:115]
	v_mfma_f32_16x16x32_bf16 v[104:107], v[156:159], v[188:191], v[104:107]
	v_mfma_f32_16x16x32_bf16 v[96:99], v[140:143], v[196:199], v[96:99]
	v_mfma_f32_16x16x32_bf16 v[88:91], v[156:159], v[196:199], v[88:91]
	v_mfma_f32_16x16x32_bf16 v[80:83], v[140:143], v[204:207], v[80:83]
	v_mfma_f32_16x16x32_bf16 v[72:75], v[156:159], v[204:207], v[72:75]
	v_mfma_f32_16x16x32_bf16 v[124:127], v[152:155], v[184:187], v[124:127]
	v_mfma_f32_16x16x32_bf16 v[120:123], v[160:163], v[184:187], v[120:123]
	v_mfma_f32_16x16x32_bf16 v[112:115], v[152:155], v[192:195], v[112:115]
	v_mfma_f32_16x16x32_bf16 v[104:107], v[160:163], v[192:195], v[104:107]
	v_mfma_f32_16x16x32_bf16 v[96:99], v[152:155], v[200:203], v[96:99]
	v_mfma_f32_16x16x32_bf16 v[88:91], v[160:163], v[200:203], v[88:91]
	v_mfma_f32_16x16x32_bf16 v[80:83], v[152:155], v[208:211], v[80:83]
	v_mfma_f32_16x16x32_bf16 v[72:75], v[160:163], v[208:211], v[72:75]
	v_mfma_f32_16x16x32_bf16 v[116:119], v[164:167], v[180:183], v[116:119]
	v_mfma_f32_16x16x32_bf16 v[108:111], v[172:175], v[180:183], v[108:111]
	v_mfma_f32_16x16x32_bf16 v[100:103], v[164:167], v[188:191], v[100:103]
	v_mfma_f32_16x16x32_bf16 v[92:95], v[172:175], v[188:191], v[92:95]
	v_mfma_f32_16x16x32_bf16 v[84:87], v[164:167], v[196:199], v[84:87]
	v_mfma_f32_16x16x32_bf16 v[76:79], v[172:175], v[196:199], v[76:79]
	v_mfma_f32_16x16x32_bf16 v[68:71], v[164:167], v[204:207], v[68:71]
	v_mfma_f32_16x16x32_bf16 v[64:67], v[172:175], v[204:207], v[64:67]
	v_mfma_f32_16x16x32_bf16 v[116:119], v[168:171], v[184:187], v[116:119]
	v_mfma_f32_16x16x32_bf16 v[108:111], v[176:179], v[184:187], v[108:111]
	v_mfma_f32_16x16x32_bf16 v[100:103], v[168:171], v[192:195], v[100:103]
	v_mfma_f32_16x16x32_bf16 v[92:95], v[176:179], v[192:195], v[92:95]
	v_mfma_f32_16x16x32_bf16 v[84:87], v[168:171], v[200:203], v[84:87]
	v_mfma_f32_16x16x32_bf16 v[76:79], v[176:179], v[200:203], v[76:79]
	v_mfma_f32_16x16x32_bf16 v[68:71], v[168:171], v[208:211], v[68:71]
	v_mfma_f32_16x16x32_bf16 v[64:67], v[176:179], v[208:211], v[64:67]
	s_setprio 0
	s_barrier
	s_add_i32 s3, s57, s18
	s_mov_b32 m0, s3
	ds_read_b128 v[180:183], v151 offset:16384
	ds_read_b128 v[184:187], v151 offset:17408
	ds_read_b128 v[188:191], v151 offset:18432
	ds_read_b128 v[192:195], v151 offset:19456
	ds_read_b128 v[196:199], v151 offset:20480
	ds_read_b128 v[200:203], v151 offset:21504
	ds_read_b128 v[204:207], v151 offset:22528
	ds_read_b128 v[208:211], v151 offset:23552
	global_load_lds_dwordx4 v128, s[80:81]
	s_add_i32 m0, s3, 0x2000
	s_add_u32 s42, s80, 0x200000
	s_addc_u32 s43, s81, 0
	s_add_i32 s3, s58, s18
	global_load_lds_dwordx4 v130, s[80:81]
	s_mov_b32 m0, s3
	s_nop 0
	global_load_lds_dwordx4 v128, s[42:43]
	s_add_i32 m0, s3, 0x2000
	s_nop 0
	global_load_lds_dwordx4 v130, s[42:43]
	s_mov_b32 m0, s19
	s_nop 0
	global_load_lds_dwordx4 v128, s[86:87]
	s_mov_b32 m0, s25
	s_nop 0
	global_load_lds_dwordx4 v130, s[86:87]
	s_waitcnt vmcnt(8)
	s_waitcnt lgkmcnt(0)
	s_barrier
	s_setprio 1
	s_waitcnt lgkmcnt(0)
	v_mfma_f32_16x16x32_bf16 v[60:63], v[140:143], v[180:183], v[60:63]
	v_mfma_f32_16x16x32_bf16 v[56:59], v[156:159], v[180:183], v[56:59]
	v_mfma_f32_16x16x32_bf16 v[48:51], v[140:143], v[188:191], v[48:51]
	v_mfma_f32_16x16x32_bf16 v[40:43], v[156:159], v[188:191], v[40:43]
	v_mfma_f32_16x16x32_bf16 v[32:35], v[140:143], v[196:199], v[32:35]
	v_mfma_f32_16x16x32_bf16 v[24:27], v[156:159], v[196:199], v[24:27]
	v_mfma_f32_16x16x32_bf16 v[16:19], v[140:143], v[204:207], v[16:19]
	v_mfma_f32_16x16x32_bf16 v[8:11], v[156:159], v[204:207], v[8:11]
	v_mfma_f32_16x16x32_bf16 v[60:63], v[152:155], v[184:187], v[60:63]
	v_mfma_f32_16x16x32_bf16 v[56:59], v[160:163], v[184:187], v[56:59]
	v_mfma_f32_16x16x32_bf16 v[48:51], v[152:155], v[192:195], v[48:51]
	v_mfma_f32_16x16x32_bf16 v[40:43], v[160:163], v[192:195], v[40:43]
	v_mfma_f32_16x16x32_bf16 v[32:35], v[152:155], v[200:203], v[32:35]
	v_mfma_f32_16x16x32_bf16 v[24:27], v[160:163], v[200:203], v[24:27]
	v_mfma_f32_16x16x32_bf16 v[16:19], v[152:155], v[208:211], v[16:19]
	v_mfma_f32_16x16x32_bf16 v[8:11], v[160:163], v[208:211], v[8:11]
	v_mfma_f32_16x16x32_bf16 v[52:55], v[164:167], v[180:183], v[52:55]
	v_mfma_f32_16x16x32_bf16 v[44:47], v[172:175], v[180:183], v[44:47]
	v_mfma_f32_16x16x32_bf16 v[36:39], v[164:167], v[188:191], v[36:39]
	v_mfma_f32_16x16x32_bf16 v[28:31], v[172:175], v[188:191], v[28:31]
	v_mfma_f32_16x16x32_bf16 v[20:23], v[164:167], v[196:199], v[20:23]
	v_mfma_f32_16x16x32_bf16 v[12:15], v[172:175], v[196:199], v[12:15]
	v_mfma_f32_16x16x32_bf16 v[4:7], v[164:167], v[204:207], v[4:7]
	v_mfma_f32_16x16x32_bf16 v[0:3], v[172:175], v[204:207], v[0:3]
	v_mfma_f32_16x16x32_bf16 v[52:55], v[168:171], v[184:187], v[52:55]
	v_mfma_f32_16x16x32_bf16 v[44:47], v[176:179], v[184:187], v[44:47]
	v_mfma_f32_16x16x32_bf16 v[36:39], v[168:171], v[192:195], v[36:39]
	v_mfma_f32_16x16x32_bf16 v[28:31], v[176:179], v[192:195], v[28:31]
	v_mfma_f32_16x16x32_bf16 v[20:23], v[168:171], v[200:203], v[20:23]
	v_mfma_f32_16x16x32_bf16 v[12:15], v[176:179], v[200:203], v[12:15]
	v_mfma_f32_16x16x32_bf16 v[4:7], v[168:171], v[208:211], v[4:7]
	v_mfma_f32_16x16x32_bf16 v[0:3], v[176:179], v[208:211], v[0:3]
	s_setprio 0
	s_barrier
	s_add_i32 s3, 0, 0x18000
	s_add_i32 s37, 0, 0x1c000
	v_add_u32_e32 v160, s3, v147
	v_add_u32_e32 v176, s37, v147
	ds_read_b128 v[140:143], v160
	ds_read_b128 v[152:155], v160 offset:1024
	ds_read_b128 v[156:159], v160 offset:2048
	ds_read_b128 v[160:163], v160 offset:3072
	ds_read_b128 v[164:167], v176
	ds_read_b128 v[168:171], v176 offset:1024
	ds_read_b128 v[172:175], v176 offset:2048
	ds_read_b128 v[176:179], v176 offset:3072
	s_add_u32 s42, s86, 0x200000
	s_addc_u32 s43, s87, 0
	s_mov_b32 m0, s30
	ds_read_b128 v[180:183], v151 offset:32768
	ds_read_b128 v[184:187], v151 offset:33792
	ds_read_b128 v[188:191], v151 offset:34816
	ds_read_b128 v[192:195], v151 offset:35840
	ds_read_b128 v[196:199], v151 offset:36864
	ds_read_b128 v[200:203], v151 offset:37888
	ds_read_b128 v[204:207], v151 offset:38912
	ds_read_b128 v[208:211], v151 offset:39936
	global_load_lds_dwordx4 v128, s[42:43]
	v_lshl_add_u64 v[218:219], s[42:43], 0, v[130:131]
	s_mov_b32 m0, s31
	s_nop 0
	global_load_lds_dwordx4 v[218:219], off
	s_waitcnt vmcnt(8)
	s_waitcnt lgkmcnt(0)
	s_barrier
	s_setprio 1
	s_waitcnt lgkmcnt(0)
	v_mfma_f32_16x16x32_bf16 v[124:127], v[140:143], v[180:183], v[124:127]
	v_mfma_f32_16x16x32_bf16 v[120:123], v[156:159], v[180:183], v[120:123]
	v_mfma_f32_16x16x32_bf16 v[112:115], v[140:143], v[188:191], v[112:115]
	v_mfma_f32_16x16x32_bf16 v[104:107], v[156:159], v[188:191], v[104:107]
	v_mfma_f32_16x16x32_bf16 v[96:99], v[140:143], v[196:199], v[96:99]
	v_mfma_f32_16x16x32_bf16 v[88:91], v[156:159], v[196:199], v[88:91]
	v_mfma_f32_16x16x32_bf16 v[80:83], v[140:143], v[204:207], v[80:83]
	v_mfma_f32_16x16x32_bf16 v[72:75], v[156:159], v[204:207], v[72:75]
	v_mfma_f32_16x16x32_bf16 v[124:127], v[152:155], v[184:187], v[124:127]
	v_mfma_f32_16x16x32_bf16 v[120:123], v[160:163], v[184:187], v[120:123]
	v_mfma_f32_16x16x32_bf16 v[112:115], v[152:155], v[192:195], v[112:115]
	v_mfma_f32_16x16x32_bf16 v[104:107], v[160:163], v[192:195], v[104:107]
	v_mfma_f32_16x16x32_bf16 v[96:99], v[152:155], v[200:203], v[96:99]
	v_mfma_f32_16x16x32_bf16 v[88:91], v[160:163], v[200:203], v[88:91]
	v_mfma_f32_16x16x32_bf16 v[80:83], v[152:155], v[208:211], v[80:83]
	v_mfma_f32_16x16x32_bf16 v[72:75], v[160:163], v[208:211], v[72:75]
	v_mfma_f32_16x16x32_bf16 v[116:119], v[164:167], v[180:183], v[116:119]
	v_mfma_f32_16x16x32_bf16 v[108:111], v[172:175], v[180:183], v[108:111]
	v_mfma_f32_16x16x32_bf16 v[100:103], v[164:167], v[188:191], v[100:103]
	v_mfma_f32_16x16x32_bf16 v[92:95], v[172:175], v[188:191], v[92:95]
	v_mfma_f32_16x16x32_bf16 v[84:87], v[164:167], v[196:199], v[84:87]
	v_mfma_f32_16x16x32_bf16 v[76:79], v[172:175], v[196:199], v[76:79]
	v_mfma_f32_16x16x32_bf16 v[68:71], v[164:167], v[204:207], v[68:71]
	v_mfma_f32_16x16x32_bf16 v[64:67], v[172:175], v[204:207], v[64:67]
	v_mfma_f32_16x16x32_bf16 v[116:119], v[168:171], v[184:187], v[116:119]
	v_mfma_f32_16x16x32_bf16 v[108:111], v[176:179], v[184:187], v[108:111]
	v_mfma_f32_16x16x32_bf16 v[100:103], v[168:171], v[192:195], v[100:103]
	v_mfma_f32_16x16x32_bf16 v[92:95], v[176:179], v[192:195], v[92:95]
	v_mfma_f32_16x16x32_bf16 v[84:87], v[168:171], v[200:203], v[84:87]
	v_mfma_f32_16x16x32_bf16 v[76:79], v[176:179], v[200:203], v[76:79]
	v_mfma_f32_16x16x32_bf16 v[68:71], v[168:171], v[208:211], v[68:71]
	v_mfma_f32_16x16x32_bf16 v[64:67], v[176:179], v[208:211], v[64:67]
	s_setprio 0
	s_barrier
	s_add_i32 s3, s3, s18
	s_add_u32 s42, s80, 0x80
	s_addc_u32 s43, s81, 0
	s_mov_b32 m0, s3
	ds_read_b128 v[180:183], v151 offset:49152
	ds_read_b128 v[184:187], v151 offset:50176
	ds_read_b128 v[188:191], v151 offset:51200
	ds_read_b128 v[192:195], v151 offset:52224
	ds_read_b128 v[196:199], v151 offset:53248
	ds_read_b128 v[200:203], v151 offset:54272
	ds_read_b128 v[204:207], v151 offset:55296
	ds_read_b128 v[208:211], v151 offset:56320
	global_load_lds_dwordx4 v128, s[42:43]
	s_add_i32 m0, s3, 0x2000
	s_add_i32 s3, s37, s18
	global_load_lds_dwordx4 v130, s[42:43]
	s_add_u32 s42, s42, 0x200000
	s_addc_u32 s43, s43, 0
	s_mov_b32 m0, s3
	s_nop 0
	global_load_lds_dwordx4 v128, s[42:43]
	s_add_i32 m0, s3, 0x2000
	s_nop 0
	global_load_lds_dwordx4 v130, s[42:43]
	s_add_u32 s86, s86, 0x80
	s_addc_u32 s87, s87, 0
	s_mov_b32 m0, s49
	s_nop 0
	global_load_lds_dwordx4 v128, s[86:87]
	s_mov_b32 m0, s56
	s_nop 0
	global_load_lds_dwordx4 v130, s[86:87]
	s_waitcnt vmcnt(8)
	s_waitcnt lgkmcnt(0)
	s_barrier
	s_setprio 1
	s_waitcnt lgkmcnt(0)
	v_mfma_f32_16x16x32_bf16 v[60:63], v[140:143], v[180:183], v[60:63]
	v_mfma_f32_16x16x32_bf16 v[56:59], v[156:159], v[180:183], v[56:59]
	v_mfma_f32_16x16x32_bf16 v[48:51], v[140:143], v[188:191], v[48:51]
	v_mfma_f32_16x16x32_bf16 v[40:43], v[156:159], v[188:191], v[40:43]
	v_mfma_f32_16x16x32_bf16 v[32:35], v[140:143], v[196:199], v[32:35]
	v_mfma_f32_16x16x32_bf16 v[24:27], v[156:159], v[196:199], v[24:27]
	v_mfma_f32_16x16x32_bf16 v[16:19], v[140:143], v[204:207], v[16:19]
	v_mfma_f32_16x16x32_bf16 v[8:11], v[156:159], v[204:207], v[8:11]
	v_mfma_f32_16x16x32_bf16 v[60:63], v[152:155], v[184:187], v[60:63]
	v_mfma_f32_16x16x32_bf16 v[56:59], v[160:163], v[184:187], v[56:59]
	v_mfma_f32_16x16x32_bf16 v[48:51], v[152:155], v[192:195], v[48:51]
	v_mfma_f32_16x16x32_bf16 v[40:43], v[160:163], v[192:195], v[40:43]
	v_mfma_f32_16x16x32_bf16 v[32:35], v[152:155], v[200:203], v[32:35]
	v_mfma_f32_16x16x32_bf16 v[24:27], v[160:163], v[200:203], v[24:27]
	v_mfma_f32_16x16x32_bf16 v[16:19], v[152:155], v[208:211], v[16:19]
	v_mfma_f32_16x16x32_bf16 v[8:11], v[160:163], v[208:211], v[8:11]
	v_mfma_f32_16x16x32_bf16 v[52:55], v[164:167], v[180:183], v[52:55]
	v_mfma_f32_16x16x32_bf16 v[44:47], v[172:175], v[180:183], v[44:47]
	v_mfma_f32_16x16x32_bf16 v[36:39], v[164:167], v[188:191], v[36:39]
	v_mfma_f32_16x16x32_bf16 v[28:31], v[172:175], v[188:191], v[28:31]
	v_mfma_f32_16x16x32_bf16 v[20:23], v[164:167], v[196:199], v[20:23]
	v_mfma_f32_16x16x32_bf16 v[12:15], v[172:175], v[196:199], v[12:15]
	v_mfma_f32_16x16x32_bf16 v[4:7], v[164:167], v[204:207], v[4:7]
	v_mfma_f32_16x16x32_bf16 v[0:3], v[172:175], v[204:207], v[0:3]
	v_mfma_f32_16x16x32_bf16 v[52:55], v[168:171], v[184:187], v[52:55]
	v_mfma_f32_16x16x32_bf16 v[44:47], v[176:179], v[184:187], v[44:47]
	v_mfma_f32_16x16x32_bf16 v[36:39], v[168:171], v[192:195], v[36:39]
	v_mfma_f32_16x16x32_bf16 v[28:31], v[176:179], v[192:195], v[28:31]
	v_mfma_f32_16x16x32_bf16 v[20:23], v[168:171], v[200:203], v[20:23]
	v_mfma_f32_16x16x32_bf16 v[12:15], v[176:179], v[200:203], v[12:15]
	v_mfma_f32_16x16x32_bf16 v[4:7], v[168:171], v[208:211], v[4:7]
	v_mfma_f32_16x16x32_bf16 v[0:3], v[176:179], v[208:211], v[0:3]
	s_setprio 0
	s_barrier
	s_add_i32 s36, s36, 2
	s_add_u32 s84, s84, 0x100
	s_addc_u32 s85, s85, 0
	s_add_u32 s27, s27, 0x100
	s_addc_u32 s33, s33, 0
	s_cmpk_gt_u32 s36, 0x7d
	s_cbranch_scc0 .LBB0_846
	s_and_b64 vcc, exec, s[12:13]
	s_cbranch_vccz .LBB0_849
	s_barrier

.LBB0_919:
	ds_read_b128 v[128:131], v173
	ds_read_b128 v[132:135], v173 offset:1024
	ds_read_b128 v[158:161], v173 offset:2048
	ds_read_b128 v[178:181], v173 offset:3072
	ds_read_b128 v[182:185], v174
	ds_read_b128 v[186:189], v174 offset:1024
	ds_read_b128 v[190:193], v174 offset:2048
	ds_read_b128 v[194:197], v174 offset:3072
	s_add_u32 s3, s34, 0xfff80080
	s_addc_u32 s27, s35, -1
	s_cmp_eq_u32 s24, 28
	s_cselect_b32 vcc_hi, s0, s27
	s_cselect_b32 vcc_lo, s1, s3
	s_cselect_b32 s81, s15, s19
	s_cselect_b32 s80, s17, s18
	s_add_i32 m0, s30, 0xc000
	ds_read_b128 v[198:201], v175
	ds_read_b128 v[202:205], v175 offset:1024
	ds_read_b128 v[206:209], v175 offset:2048
	ds_read_b128 v[210:213], v175 offset:3072
	ds_read_b128 v[214:217], v175 offset:4096
	ds_read_b128 v[218:221], v175 offset:5120
	ds_read_b128 v[222:225], v175 offset:6144
	ds_read_b128 v[230:233], v175 offset:7168
	global_load_lds_dwordx4 v148, s[34:35]
	s_add_i32 m0, s30, 0xe000
	s_nop 0
	global_load_lds_dwordx4 v150, s[34:35]
	s_waitcnt vmcnt(8)
	s_waitcnt lgkmcnt(0)
	s_barrier
	s_setprio 1
	s_waitcnt lgkmcnt(0)
	v_mfma_f32_16x16x32_bf16 v[124:127], v[128:131], v[198:201], v[124:127]
	v_mfma_f32_16x16x32_bf16 v[120:123], v[158:161], v[198:201], v[120:123]
	v_mfma_f32_16x16x32_bf16 v[108:111], v[128:131], v[206:209], v[108:111]
	v_mfma_f32_16x16x32_bf16 v[104:107], v[158:161], v[206:209], v[104:107]
	v_mfma_f32_16x16x32_bf16 v[92:95], v[128:131], v[214:217], v[92:95]
	v_mfma_f32_16x16x32_bf16 v[88:91], v[158:161], v[214:217], v[88:91]
	v_mfma_f32_16x16x32_bf16 v[76:79], v[128:131], v[222:225], v[76:79]
	v_mfma_f32_16x16x32_bf16 v[72:75], v[158:161], v[222:225], v[72:75]
	v_mfma_f32_16x16x32_bf16 v[124:127], v[132:135], v[202:205], v[124:127]
	v_mfma_f32_16x16x32_bf16 v[120:123], v[178:181], v[202:205], v[120:123]
	v_mfma_f32_16x16x32_bf16 v[108:111], v[132:135], v[210:213], v[108:111]
	v_mfma_f32_16x16x32_bf16 v[104:107], v[178:181], v[210:213], v[104:107]
	v_mfma_f32_16x16x32_bf16 v[92:95], v[132:135], v[218:221], v[92:95]
	v_mfma_f32_16x16x32_bf16 v[88:91], v[178:181], v[218:221], v[88:91]
	v_mfma_f32_16x16x32_bf16 v[76:79], v[132:135], v[230:233], v[76:79]
	v_mfma_f32_16x16x32_bf16 v[72:75], v[178:181], v[230:233], v[72:75]
	v_mfma_f32_16x16x32_bf16 v[116:119], v[182:185], v[198:201], v[116:119]
	v_mfma_f32_16x16x32_bf16 v[112:115], v[190:193], v[198:201], v[112:115]
	v_mfma_f32_16x16x32_bf16 v[100:103], v[182:185], v[206:209], v[100:103]
	v_mfma_f32_16x16x32_bf16 v[96:99], v[190:193], v[206:209], v[96:99]
	v_mfma_f32_16x16x32_bf16 v[84:87], v[182:185], v[214:217], v[84:87]
	v_mfma_f32_16x16x32_bf16 v[80:83], v[190:193], v[214:217], v[80:83]
	v_mfma_f32_16x16x32_bf16 v[68:71], v[182:185], v[222:225], v[68:71]
	v_mfma_f32_16x16x32_bf16 v[64:67], v[190:193], v[222:225], v[64:67]
	v_mfma_f32_16x16x32_bf16 v[116:119], v[186:189], v[202:205], v[116:119]
	v_mfma_f32_16x16x32_bf16 v[112:115], v[194:197], v[202:205], v[112:115]
	v_mfma_f32_16x16x32_bf16 v[100:103], v[186:189], v[210:213], v[100:103]
	v_mfma_f32_16x16x32_bf16 v[96:99], v[194:197], v[210:213], v[96:99]
	v_mfma_f32_16x16x32_bf16 v[84:87], v[186:189], v[218:221], v[84:87]
	v_mfma_f32_16x16x32_bf16 v[80:83], v[194:197], v[218:221], v[80:83]
	v_mfma_f32_16x16x32_bf16 v[68:71], v[186:189], v[230:233], v[68:71]
	v_mfma_f32_16x16x32_bf16 v[64:67], v[194:197], v[230:233], v[64:67]
	s_setprio 0
	s_barrier
	s_add_i32 s3, s57, s25
	s_mov_b32 m0, s3
	ds_read_b128 v[198:201], v175 offset:16384
	ds_read_b128 v[202:205], v175 offset:17408
	ds_read_b128 v[206:209], v175 offset:18432
	ds_read_b128 v[210:213], v175 offset:19456
	ds_read_b128 v[214:217], v175 offset:20480
	ds_read_b128 v[218:221], v175 offset:21504
	ds_read_b128 v[222:225], v175 offset:22528
	ds_read_b128 v[230:233], v175 offset:23552
	global_load_lds_dwordx4 v138, s[80:81]
	s_add_i32 m0, s3, 0x2000
	s_add_u32 s36, s80, 0x80000
	s_addc_u32 s37, s81, 0
	s_add_i32 s3, s76, s25
	global_load_lds_dwordx4 v142, s[80:81]
	s_mov_b32 m0, s3
	s_nop 0
	global_load_lds_dwordx4 v138, s[36:37]
	s_add_i32 m0, s3, 0x2000
	s_nop 0
	global_load_lds_dwordx4 v142, s[36:37]
	s_mov_b32 m0, s30
	s_nop 0
	global_load_lds_dwordx4 v136, vcc
	s_mov_b32 m0, s31
	s_nop 0
	global_load_lds_dwordx4 v140, vcc
	s_waitcnt vmcnt(8)
	s_waitcnt lgkmcnt(0)
	s_barrier
	s_setprio 1
	s_waitcnt lgkmcnt(0)
	v_mfma_f32_16x16x32_bf16 v[60:63], v[128:131], v[198:201], v[60:63]
	v_mfma_f32_16x16x32_bf16 v[56:59], v[158:161], v[198:201], v[56:59]
	v_mfma_f32_16x16x32_bf16 v[44:47], v[128:131], v[206:209], v[44:47]
	v_mfma_f32_16x16x32_bf16 v[40:43], v[158:161], v[206:209], v[40:43]
	v_mfma_f32_16x16x32_bf16 v[28:31], v[128:131], v[214:217], v[28:31]
	v_mfma_f32_16x16x32_bf16 v[24:27], v[158:161], v[214:217], v[24:27]
	v_mfma_f32_16x16x32_bf16 v[12:15], v[128:131], v[222:225], v[12:15]
	v_mfma_f32_16x16x32_bf16 v[8:11], v[158:161], v[222:225], v[8:11]
	v_mfma_f32_16x16x32_bf16 v[60:63], v[132:135], v[202:205], v[60:63]
	v_mfma_f32_16x16x32_bf16 v[56:59], v[178:181], v[202:205], v[56:59]
	v_mfma_f32_16x16x32_bf16 v[44:47], v[132:135], v[210:213], v[44:47]
	v_mfma_f32_16x16x32_bf16 v[40:43], v[178:181], v[210:213], v[40:43]
	v_mfma_f32_16x16x32_bf16 v[28:31], v[132:135], v[218:221], v[28:31]
	v_mfma_f32_16x16x32_bf16 v[24:27], v[178:181], v[218:221], v[24:27]
	v_mfma_f32_16x16x32_bf16 v[12:15], v[132:135], v[230:233], v[12:15]
	v_mfma_f32_16x16x32_bf16 v[8:11], v[178:181], v[230:233], v[8:11]
	v_mfma_f32_16x16x32_bf16 v[52:55], v[182:185], v[198:201], v[52:55]
	v_mfma_f32_16x16x32_bf16 v[48:51], v[190:193], v[198:201], v[48:51]
	v_mfma_f32_16x16x32_bf16 v[36:39], v[182:185], v[206:209], v[36:39]
	v_mfma_f32_16x16x32_bf16 v[32:35], v[190:193], v[206:209], v[32:35]
	v_mfma_f32_16x16x32_bf16 v[20:23], v[182:185], v[214:217], v[20:23]
	v_mfma_f32_16x16x32_bf16 v[16:19], v[190:193], v[214:217], v[16:19]
	v_mfma_f32_16x16x32_bf16 v[4:7], v[182:185], v[222:225], v[4:7]
	v_mfma_f32_16x16x32_bf16 v[0:3], v[190:193], v[222:225], v[0:3]
	v_mfma_f32_16x16x32_bf16 v[52:55], v[186:189], v[202:205], v[52:55]
	v_mfma_f32_16x16x32_bf16 v[48:51], v[194:197], v[202:205], v[48:51]
	v_mfma_f32_16x16x32_bf16 v[36:39], v[186:189], v[210:213], v[36:39]
	v_mfma_f32_16x16x32_bf16 v[32:35], v[194:197], v[210:213], v[32:35]
	v_mfma_f32_16x16x32_bf16 v[20:23], v[186:189], v[218:221], v[20:23]
	v_mfma_f32_16x16x32_bf16 v[16:19], v[194:197], v[218:221], v[16:19]
	v_mfma_f32_16x16x32_bf16 v[4:7], v[186:189], v[230:233], v[4:7]
	v_mfma_f32_16x16x32_bf16 v[0:3], v[194:197], v[230:233], v[0:3]
	s_setprio 0
	s_barrier
	s_add_i32 s3, 0, 0x18000
	v_add_u32_e32 v144, s3, v165
	s_add_i32 s27, 0, 0x1c000
	ds_read_b128 v[128:131], v144
	ds_read_b128 v[132:135], v144 offset:1024
	ds_read_b128 v[158:161], v144 offset:2048
	ds_read_b128 v[178:181], v144 offset:3072
	v_add_u32_e32 v144, s27, v165
	ds_read_b128 v[182:185], v144
	ds_read_b128 v[186:189], v144 offset:1024
	ds_read_b128 v[190:193], v144 offset:2048
	ds_read_b128 v[194:197], v144 offset:3072
	s_add_u32 s36, vcc_lo, 0x80000
	s_addc_u32 s37, vcc_hi, 0
	s_mov_b32 m0, s58
	ds_read_b128 v[198:201], v175 offset:32768
	ds_read_b128 v[202:205], v175 offset:33792
	ds_read_b128 v[206:209], v175 offset:34816
	ds_read_b128 v[210:213], v175 offset:35840
	ds_read_b128 v[214:217], v175 offset:36864
	ds_read_b128 v[218:221], v175 offset:37888
	ds_read_b128 v[222:225], v175 offset:38912
	ds_read_b128 v[230:233], v175 offset:39936
	global_load_lds_dwordx4 v136, s[36:37]
	s_mov_b32 m0, s59
	s_nop 0
	global_load_lds_dwordx4 v140, s[36:37]
	s_waitcnt vmcnt(8)
	s_waitcnt lgkmcnt(0)
	s_barrier
	s_setprio 1
	s_waitcnt lgkmcnt(0)
	v_mfma_f32_16x16x32_bf16 v[124:127], v[128:131], v[198:201], v[124:127]
	v_mfma_f32_16x16x32_bf16 v[120:123], v[158:161], v[198:201], v[120:123]
	v_mfma_f32_16x16x32_bf16 v[108:111], v[128:131], v[206:209], v[108:111]
	v_mfma_f32_16x16x32_bf16 v[104:107], v[158:161], v[206:209], v[104:107]
	v_mfma_f32_16x16x32_bf16 v[92:95], v[128:131], v[214:217], v[92:95]
	v_mfma_f32_16x16x32_bf16 v[88:91], v[158:161], v[214:217], v[88:91]
	v_mfma_f32_16x16x32_bf16 v[76:79], v[128:131], v[222:225], v[76:79]
	v_mfma_f32_16x16x32_bf16 v[72:75], v[158:161], v[222:225], v[72:75]
	v_mfma_f32_16x16x32_bf16 v[124:127], v[132:135], v[202:205], v[124:127]
	v_mfma_f32_16x16x32_bf16 v[120:123], v[178:181], v[202:205], v[120:123]
	v_mfma_f32_16x16x32_bf16 v[108:111], v[132:135], v[210:213], v[108:111]
	v_mfma_f32_16x16x32_bf16 v[104:107], v[178:181], v[210:213], v[104:107]
	v_mfma_f32_16x16x32_bf16 v[92:95], v[132:135], v[218:221], v[92:95]
	v_mfma_f32_16x16x32_bf16 v[88:91], v[178:181], v[218:221], v[88:91]
	v_mfma_f32_16x16x32_bf16 v[76:79], v[132:135], v[230:233], v[76:79]
	v_mfma_f32_16x16x32_bf16 v[72:75], v[178:181], v[230:233], v[72:75]
	v_mfma_f32_16x16x32_bf16 v[116:119], v[182:185], v[198:201], v[116:119]
	v_mfma_f32_16x16x32_bf16 v[112:115], v[190:193], v[198:201], v[112:115]
	v_mfma_f32_16x16x32_bf16 v[100:103], v[182:185], v[206:209], v[100:103]
	v_mfma_f32_16x16x32_bf16 v[96:99], v[190:193], v[206:209], v[96:99]
	v_mfma_f32_16x16x32_bf16 v[84:87], v[182:185], v[214:217], v[84:87]
	v_mfma_f32_16x16x32_bf16 v[80:83], v[190:193], v[214:217], v[80:83]
	v_mfma_f32_16x16x32_bf16 v[68:71], v[182:185], v[222:225], v[68:71]
	v_mfma_f32_16x16x32_bf16 v[64:67], v[190:193], v[222:225], v[64:67]
	v_mfma_f32_16x16x32_bf16 v[116:119], v[186:189], v[202:205], v[116:119]
	v_mfma_f32_16x16x32_bf16 v[112:115], v[194:197], v[202:205], v[112:115]
	v_mfma_f32_16x16x32_bf16 v[100:103], v[186:189], v[210:213], v[100:103]
	v_mfma_f32_16x16x32_bf16 v[96:99], v[194:197], v[210:213], v[96:99]
	v_mfma_f32_16x16x32_bf16 v[84:87], v[186:189], v[218:221], v[84:87]
	v_mfma_f32_16x16x32_bf16 v[80:83], v[194:197], v[218:221], v[80:83]
	v_mfma_f32_16x16x32_bf16 v[68:71], v[186:189], v[230:233], v[68:71]
	v_mfma_f32_16x16x32_bf16 v[64:67], v[194:197], v[230:233], v[64:67]
	s_setprio 0
	s_barrier
	s_add_i32 s3, s3, s25
	s_add_u32 s36, s80, 0x80
	s_addc_u32 s37, s81, 0
	s_mov_b32 m0, s3
	ds_read_b128 v[198:201], v175 offset:49152
	ds_read_b128 v[202:205], v175 offset:50176
	ds_read_b128 v[206:209], v175 offset:51200
	ds_read_b128 v[210:213], v175 offset:52224
	ds_read_b128 v[214:217], v175 offset:53248
	ds_read_b128 v[218:221], v175 offset:54272
	ds_read_b128 v[222:225], v175 offset:55296
	ds_read_b128 v[230:233], v175 offset:56320
	global_load_lds_dwordx4 v138, s[36:37]
	s_add_i32 m0, s3, 0x2000
	s_add_i32 s3, s27, s25
	global_load_lds_dwordx4 v142, s[36:37]
	s_add_u32 s36, s36, 0x80000
	s_addc_u32 s37, s37, 0
	s_mov_b32 m0, s3
	s_nop 0
	global_load_lds_dwordx4 v138, s[36:37]
	s_add_i32 m0, s3, 0x2000
	s_nop 0
	global_load_lds_dwordx4 v142, s[36:37]
	s_add_u32 vcc_lo, vcc_lo, 0x80
	s_addc_u32 vcc_hi, vcc_hi, 0
	s_mov_b32 m0, s78
	s_nop 0
	global_load_lds_dwordx4 v136, vcc
	s_mov_b32 m0, s56
	s_nop 0
	global_load_lds_dwordx4 v140, vcc
	s_waitcnt vmcnt(8)
	s_waitcnt lgkmcnt(0)
	s_barrier
	s_setprio 1
	s_waitcnt lgkmcnt(0)
	v_mfma_f32_16x16x32_bf16 v[60:63], v[128:131], v[198:201], v[60:63]
	v_mfma_f32_16x16x32_bf16 v[56:59], v[158:161], v[198:201], v[56:59]
	v_mfma_f32_16x16x32_bf16 v[44:47], v[128:131], v[206:209], v[44:47]
	v_mfma_f32_16x16x32_bf16 v[40:43], v[158:161], v[206:209], v[40:43]
	v_mfma_f32_16x16x32_bf16 v[28:31], v[128:131], v[214:217], v[28:31]
	v_mfma_f32_16x16x32_bf16 v[24:27], v[158:161], v[214:217], v[24:27]
	v_mfma_f32_16x16x32_bf16 v[12:15], v[128:131], v[222:225], v[12:15]
	v_mfma_f32_16x16x32_bf16 v[8:11], v[158:161], v[222:225], v[8:11]
	v_mfma_f32_16x16x32_bf16 v[60:63], v[132:135], v[202:205], v[60:63]
	v_mfma_f32_16x16x32_bf16 v[56:59], v[178:181], v[202:205], v[56:59]
	v_mfma_f32_16x16x32_bf16 v[44:47], v[132:135], v[210:213], v[44:47]
	v_mfma_f32_16x16x32_bf16 v[40:43], v[178:181], v[210:213], v[40:43]
	v_mfma_f32_16x16x32_bf16 v[28:31], v[132:135], v[218:221], v[28:31]
	v_mfma_f32_16x16x32_bf16 v[24:27], v[178:181], v[218:221], v[24:27]
	v_mfma_f32_16x16x32_bf16 v[12:15], v[132:135], v[230:233], v[12:15]
	v_mfma_f32_16x16x32_bf16 v[8:11], v[178:181], v[230:233], v[8:11]
	v_mfma_f32_16x16x32_bf16 v[52:55], v[182:185], v[198:201], v[52:55]
	v_mfma_f32_16x16x32_bf16 v[48:51], v[190:193], v[198:201], v[48:51]
	v_mfma_f32_16x16x32_bf16 v[36:39], v[182:185], v[206:209], v[36:39]
	v_mfma_f32_16x16x32_bf16 v[32:35], v[190:193], v[206:209], v[32:35]
	v_mfma_f32_16x16x32_bf16 v[20:23], v[182:185], v[214:217], v[20:23]
	v_mfma_f32_16x16x32_bf16 v[16:19], v[190:193], v[214:217], v[16:19]
	v_mfma_f32_16x16x32_bf16 v[4:7], v[182:185], v[222:225], v[4:7]
	v_mfma_f32_16x16x32_bf16 v[0:3], v[190:193], v[222:225], v[0:3]
	v_mfma_f32_16x16x32_bf16 v[52:55], v[186:189], v[202:205], v[52:55]
	v_mfma_f32_16x16x32_bf16 v[48:51], v[194:197], v[202:205], v[48:51]
	v_mfma_f32_16x16x32_bf16 v[36:39], v[186:189], v[210:213], v[36:39]
	v_mfma_f32_16x16x32_bf16 v[32:35], v[194:197], v[210:213], v[32:35]
	v_mfma_f32_16x16x32_bf16 v[20:23], v[186:189], v[218:221], v[20:23]
	v_mfma_f32_16x16x32_bf16 v[16:19], v[194:197], v[218:221], v[16:19]
	v_mfma_f32_16x16x32_bf16 v[4:7], v[186:189], v[230:233], v[4:7]
	v_mfma_f32_16x16x32_bf16 v[0:3], v[194:197], v[230:233], v[0:3]
	s_setprio 0
	s_barrier
	s_add_i32 s24, s24, 2
	s_add_u32 s34, s34, 0x100
	s_addc_u32 s35, s35, 0
	s_add_u32 s18, s18, 0x100
	s_addc_u32 s19, s19, 0
	s_cmp_gt_u32 s24, 29
	s_cbranch_scc0 .LBB0_919
	s_and_b64 vcc, exec, s[86:87]
	s_cbranch_vccz .LBB0_922
	s_barrier

.LBB0_1393:
	ds_read_b128 v[144:147], v153
	ds_read_b128 v[156:159], v153 offset:1024
	ds_read_b128 v[160:163], v153 offset:2048
	ds_read_b128 v[164:167], v153 offset:3072
	ds_read_b128 v[168:171], v154
	ds_read_b128 v[172:175], v154 offset:1024
	ds_read_b128 v[176:179], v154 offset:2048
	ds_read_b128 v[180:183], v154 offset:3072
	s_add_u32 s3, s88, 0xfffc0080
	s_addc_u32 s37, s89, -1
	s_cmp_eq_u32 s36, 12
	s_cselect_b32 s91, s0, s37
	s_cselect_b32 s90, s1, s3
	s_cselect_b32 s81, s17, s35
	s_cselect_b32 s80, s27, s33
	s_add_i32 m0, s19, 0xc000
	ds_read_b128 v[184:187], v155
	ds_read_b128 v[188:191], v155 offset:1024
	ds_read_b128 v[192:195], v155 offset:2048
	ds_read_b128 v[196:199], v155 offset:3072
	ds_read_b128 v[200:203], v155 offset:4096
	ds_read_b128 v[204:207], v155 offset:5120
	ds_read_b128 v[208:211], v155 offset:6144
	ds_read_b128 v[212:215], v155 offset:7168
	global_load_lds_dwordx4 v136, s[88:89]
	s_add_i32 m0, s19, 0xe000
	s_nop 0
	global_load_lds_dwordx4 v138, s[88:89]
	s_waitcnt vmcnt(8)
	s_waitcnt lgkmcnt(0)
	s_barrier
	s_setprio 1
	s_waitcnt lgkmcnt(0)
	v_mfma_f32_16x16x32_bf16 v[124:127], v[144:147], v[184:187], v[124:127]
	v_mfma_f32_16x16x32_bf16 v[120:123], v[160:163], v[184:187], v[120:123]
	v_mfma_f32_16x16x32_bf16 v[108:111], v[144:147], v[192:195], v[108:111]
	v_mfma_f32_16x16x32_bf16 v[104:107], v[160:163], v[192:195], v[104:107]
	v_mfma_f32_16x16x32_bf16 v[92:95], v[144:147], v[200:203], v[92:95]
	v_mfma_f32_16x16x32_bf16 v[88:91], v[160:163], v[200:203], v[88:91]
	v_mfma_f32_16x16x32_bf16 v[76:79], v[144:147], v[208:211], v[76:79]
	v_mfma_f32_16x16x32_bf16 v[72:75], v[160:163], v[208:211], v[72:75]
	v_mfma_f32_16x16x32_bf16 v[124:127], v[156:159], v[188:191], v[124:127]
	v_mfma_f32_16x16x32_bf16 v[120:123], v[164:167], v[188:191], v[120:123]
	v_mfma_f32_16x16x32_bf16 v[108:111], v[156:159], v[196:199], v[108:111]
	v_mfma_f32_16x16x32_bf16 v[104:107], v[164:167], v[196:199], v[104:107]
	v_mfma_f32_16x16x32_bf16 v[92:95], v[156:159], v[204:207], v[92:95]
	v_mfma_f32_16x16x32_bf16 v[88:91], v[164:167], v[204:207], v[88:91]
	v_mfma_f32_16x16x32_bf16 v[76:79], v[156:159], v[212:215], v[76:79]
	v_mfma_f32_16x16x32_bf16 v[72:75], v[164:167], v[212:215], v[72:75]
	v_mfma_f32_16x16x32_bf16 v[116:119], v[168:171], v[184:187], v[116:119]
	v_mfma_f32_16x16x32_bf16 v[112:115], v[176:179], v[184:187], v[112:115]
	v_mfma_f32_16x16x32_bf16 v[100:103], v[168:171], v[192:195], v[100:103]
	v_mfma_f32_16x16x32_bf16 v[96:99], v[176:179], v[192:195], v[96:99]
	v_mfma_f32_16x16x32_bf16 v[84:87], v[168:171], v[200:203], v[84:87]
	v_mfma_f32_16x16x32_bf16 v[80:83], v[176:179], v[200:203], v[80:83]
	v_mfma_f32_16x16x32_bf16 v[68:71], v[168:171], v[208:211], v[68:71]
	v_mfma_f32_16x16x32_bf16 v[64:67], v[176:179], v[208:211], v[64:67]
	v_mfma_f32_16x16x32_bf16 v[116:119], v[172:175], v[188:191], v[116:119]
	v_mfma_f32_16x16x32_bf16 v[112:115], v[180:183], v[188:191], v[112:115]
	v_mfma_f32_16x16x32_bf16 v[100:103], v[172:175], v[196:199], v[100:103]
	v_mfma_f32_16x16x32_bf16 v[96:99], v[180:183], v[196:199], v[96:99]
	v_mfma_f32_16x16x32_bf16 v[84:87], v[172:175], v[204:207], v[84:87]
	v_mfma_f32_16x16x32_bf16 v[80:83], v[180:183], v[204:207], v[80:83]
	v_mfma_f32_16x16x32_bf16 v[68:71], v[172:175], v[212:215], v[68:71]
	v_mfma_f32_16x16x32_bf16 v[64:67], v[180:183], v[212:215], v[64:67]
	s_setprio 0
	s_barrier
	s_add_i32 s3, s57, s18
	s_mov_b32 m0, s3
	ds_read_b128 v[184:187], v155 offset:16384
	ds_read_b128 v[188:191], v155 offset:17408
	ds_read_b128 v[192:195], v155 offset:18432
	ds_read_b128 v[196:199], v155 offset:19456
	ds_read_b128 v[200:203], v155 offset:20480
	ds_read_b128 v[204:207], v155 offset:21504
	ds_read_b128 v[208:211], v155 offset:22528
	ds_read_b128 v[212:215], v155 offset:23552
	global_load_lds_dwordx4 v130, s[80:81]
	s_add_i32 m0, s3, 0x2000
	s_add_u32 s42, s80, 0x40000
	s_addc_u32 s43, s81, 0
	s_add_i32 s3, s58, s18
	global_load_lds_dwordx4 v134, s[80:81]
	s_mov_b32 m0, s3
	s_nop 0
	global_load_lds_dwordx4 v130, s[42:43]
	s_add_i32 m0, s3, 0x2000
	s_nop 0
	global_load_lds_dwordx4 v134, s[42:43]
	s_mov_b32 m0, s19
	s_nop 0
	global_load_lds_dwordx4 v128, s[90:91]
	s_mov_b32 m0, s25
	s_nop 0
	global_load_lds_dwordx4 v132, s[90:91]
	s_waitcnt vmcnt(8)
	s_waitcnt lgkmcnt(0)
	s_barrier
	s_setprio 1
	s_waitcnt lgkmcnt(0)
	v_mfma_f32_16x16x32_bf16 v[60:63], v[144:147], v[184:187], v[60:63]
	v_mfma_f32_16x16x32_bf16 v[56:59], v[160:163], v[184:187], v[56:59]
	v_mfma_f32_16x16x32_bf16 v[44:47], v[144:147], v[192:195], v[44:47]
	v_mfma_f32_16x16x32_bf16 v[40:43], v[160:163], v[192:195], v[40:43]
	v_mfma_f32_16x16x32_bf16 v[28:31], v[144:147], v[200:203], v[28:31]
	v_mfma_f32_16x16x32_bf16 v[24:27], v[160:163], v[200:203], v[24:27]
	v_mfma_f32_16x16x32_bf16 v[12:15], v[144:147], v[208:211], v[12:15]
	v_mfma_f32_16x16x32_bf16 v[8:11], v[160:163], v[208:211], v[8:11]
	v_mfma_f32_16x16x32_bf16 v[60:63], v[156:159], v[188:191], v[60:63]
	v_mfma_f32_16x16x32_bf16 v[56:59], v[164:167], v[188:191], v[56:59]
	v_mfma_f32_16x16x32_bf16 v[44:47], v[156:159], v[196:199], v[44:47]
	v_mfma_f32_16x16x32_bf16 v[40:43], v[164:167], v[196:199], v[40:43]
	v_mfma_f32_16x16x32_bf16 v[28:31], v[156:159], v[204:207], v[28:31]
	v_mfma_f32_16x16x32_bf16 v[24:27], v[164:167], v[204:207], v[24:27]
	v_mfma_f32_16x16x32_bf16 v[12:15], v[156:159], v[212:215], v[12:15]
	v_mfma_f32_16x16x32_bf16 v[8:11], v[164:167], v[212:215], v[8:11]
	v_mfma_f32_16x16x32_bf16 v[52:55], v[168:171], v[184:187], v[52:55]
	v_mfma_f32_16x16x32_bf16 v[48:51], v[176:179], v[184:187], v[48:51]
	v_mfma_f32_16x16x32_bf16 v[36:39], v[168:171], v[192:195], v[36:39]
	v_mfma_f32_16x16x32_bf16 v[32:35], v[176:179], v[192:195], v[32:35]
	v_mfma_f32_16x16x32_bf16 v[20:23], v[168:171], v[200:203], v[20:23]
	v_mfma_f32_16x16x32_bf16 v[16:19], v[176:179], v[200:203], v[16:19]
	v_mfma_f32_16x16x32_bf16 v[4:7], v[168:171], v[208:211], v[4:7]
	v_mfma_f32_16x16x32_bf16 v[0:3], v[176:179], v[208:211], v[0:3]
	v_mfma_f32_16x16x32_bf16 v[52:55], v[172:175], v[188:191], v[52:55]
	v_mfma_f32_16x16x32_bf16 v[48:51], v[180:183], v[188:191], v[48:51]
	v_mfma_f32_16x16x32_bf16 v[36:39], v[172:175], v[196:199], v[36:39]
	v_mfma_f32_16x16x32_bf16 v[32:35], v[180:183], v[196:199], v[32:35]
	v_mfma_f32_16x16x32_bf16 v[20:23], v[172:175], v[204:207], v[20:23]
	v_mfma_f32_16x16x32_bf16 v[16:19], v[180:183], v[204:207], v[16:19]
	v_mfma_f32_16x16x32_bf16 v[4:7], v[172:175], v[212:215], v[4:7]
	v_mfma_f32_16x16x32_bf16 v[0:3], v[180:183], v[212:215], v[0:3]
	s_setprio 0
	s_barrier
	s_add_i32 s3, 0, 0x18000
	s_add_i32 s37, 0, 0x1c000
	v_add_u32_e32 v164, s3, v151
	v_add_u32_e32 v180, s37, v151
	ds_read_b128 v[144:147], v164
	ds_read_b128 v[156:159], v164 offset:1024
	ds_read_b128 v[160:163], v164 offset:2048
	ds_read_b128 v[164:167], v164 offset:3072
	ds_read_b128 v[168:171], v180
	ds_read_b128 v[172:175], v180 offset:1024
	ds_read_b128 v[176:179], v180 offset:2048
	ds_read_b128 v[180:183], v180 offset:3072
	s_add_u32 s42, s90, 0x40000
	s_addc_u32 s43, s91, 0
	s_mov_b32 m0, s30
	ds_read_b128 v[184:187], v155 offset:32768
	ds_read_b128 v[188:191], v155 offset:33792
	ds_read_b128 v[192:195], v155 offset:34816
	ds_read_b128 v[196:199], v155 offset:35840
	ds_read_b128 v[200:203], v155 offset:36864
	ds_read_b128 v[204:207], v155 offset:37888
	ds_read_b128 v[208:211], v155 offset:38912
	ds_read_b128 v[212:215], v155 offset:39936
	global_load_lds_dwordx4 v128, s[42:43]
	v_lshl_add_u64 v[222:223], s[42:43], 0, v[132:133]
	s_mov_b32 m0, s31
	s_nop 0
	global_load_lds_dwordx4 v[222:223], off
	s_waitcnt vmcnt(8)
	s_waitcnt lgkmcnt(0)
	s_barrier
	s_setprio 1
	s_waitcnt lgkmcnt(0)
	v_mfma_f32_16x16x32_bf16 v[124:127], v[144:147], v[184:187], v[124:127]
	v_mfma_f32_16x16x32_bf16 v[120:123], v[160:163], v[184:187], v[120:123]
	v_mfma_f32_16x16x32_bf16 v[108:111], v[144:147], v[192:195], v[108:111]
	v_mfma_f32_16x16x32_bf16 v[104:107], v[160:163], v[192:195], v[104:107]
	v_mfma_f32_16x16x32_bf16 v[92:95], v[144:147], v[200:203], v[92:95]
	v_mfma_f32_16x16x32_bf16 v[88:91], v[160:163], v[200:203], v[88:91]
	v_mfma_f32_16x16x32_bf16 v[76:79], v[144:147], v[208:211], v[76:79]
	v_mfma_f32_16x16x32_bf16 v[72:75], v[160:163], v[208:211], v[72:75]
	v_mfma_f32_16x16x32_bf16 v[124:127], v[156:159], v[188:191], v[124:127]
	v_mfma_f32_16x16x32_bf16 v[120:123], v[164:167], v[188:191], v[120:123]
	v_mfma_f32_16x16x32_bf16 v[108:111], v[156:159], v[196:199], v[108:111]
	v_mfma_f32_16x16x32_bf16 v[104:107], v[164:167], v[196:199], v[104:107]
	v_mfma_f32_16x16x32_bf16 v[92:95], v[156:159], v[204:207], v[92:95]
	v_mfma_f32_16x16x32_bf16 v[88:91], v[164:167], v[204:207], v[88:91]
	v_mfma_f32_16x16x32_bf16 v[76:79], v[156:159], v[212:215], v[76:79]
	v_mfma_f32_16x16x32_bf16 v[72:75], v[164:167], v[212:215], v[72:75]
	v_mfma_f32_16x16x32_bf16 v[116:119], v[168:171], v[184:187], v[116:119]
	v_mfma_f32_16x16x32_bf16 v[112:115], v[176:179], v[184:187], v[112:115]
	v_mfma_f32_16x16x32_bf16 v[100:103], v[168:171], v[192:195], v[100:103]
	v_mfma_f32_16x16x32_bf16 v[96:99], v[176:179], v[192:195], v[96:99]
	v_mfma_f32_16x16x32_bf16 v[84:87], v[168:171], v[200:203], v[84:87]
	v_mfma_f32_16x16x32_bf16 v[80:83], v[176:179], v[200:203], v[80:83]
	v_mfma_f32_16x16x32_bf16 v[68:71], v[168:171], v[208:211], v[68:71]
	v_mfma_f32_16x16x32_bf16 v[64:67], v[176:179], v[208:211], v[64:67]
	v_mfma_f32_16x16x32_bf16 v[116:119], v[172:175], v[188:191], v[116:119]
	v_mfma_f32_16x16x32_bf16 v[112:115], v[180:183], v[188:191], v[112:115]
	v_mfma_f32_16x16x32_bf16 v[100:103], v[172:175], v[196:199], v[100:103]
	v_mfma_f32_16x16x32_bf16 v[96:99], v[180:183], v[196:199], v[96:99]
	v_mfma_f32_16x16x32_bf16 v[84:87], v[172:175], v[204:207], v[84:87]
	v_mfma_f32_16x16x32_bf16 v[80:83], v[180:183], v[204:207], v[80:83]
	v_mfma_f32_16x16x32_bf16 v[68:71], v[172:175], v[212:215], v[68:71]
	v_mfma_f32_16x16x32_bf16 v[64:67], v[180:183], v[212:215], v[64:67]
	s_setprio 0
	s_barrier
	s_add_i32 s3, s3, s18
	s_add_u32 s42, s80, 0x80
	s_addc_u32 s43, s81, 0
	s_mov_b32 m0, s3
	ds_read_b128 v[184:187], v155 offset:49152
	ds_read_b128 v[188:191], v155 offset:50176
	ds_read_b128 v[192:195], v155 offset:51200
	ds_read_b128 v[196:199], v155 offset:52224
	ds_read_b128 v[200:203], v155 offset:53248
	ds_read_b128 v[204:207], v155 offset:54272
	ds_read_b128 v[208:211], v155 offset:55296
	ds_read_b128 v[212:215], v155 offset:56320
	global_load_lds_dwordx4 v130, s[42:43]
	s_add_i32 m0, s3, 0x2000
	s_add_i32 s3, s37, s18
	global_load_lds_dwordx4 v134, s[42:43]
	s_add_u32 s42, s42, 0x40000
	s_addc_u32 s43, s43, 0
	s_mov_b32 m0, s3
	s_nop 0
	global_load_lds_dwordx4 v130, s[42:43]
	s_add_i32 m0, s3, 0x2000
	s_nop 0
	global_load_lds_dwordx4 v134, s[42:43]
	s_add_u32 s90, s90, 0x80
	s_addc_u32 s91, s91, 0
	s_mov_b32 m0, s53
	s_nop 0
	global_load_lds_dwordx4 v128, s[90:91]
	s_mov_b32 m0, s56
	s_nop 0
	global_load_lds_dwordx4 v132, s[90:91]
	s_waitcnt vmcnt(8)
	s_waitcnt lgkmcnt(0)
	s_barrier
	s_setprio 1
	s_waitcnt lgkmcnt(0)
	v_mfma_f32_16x16x32_bf16 v[60:63], v[144:147], v[184:187], v[60:63]
	v_mfma_f32_16x16x32_bf16 v[56:59], v[160:163], v[184:187], v[56:59]
	v_mfma_f32_16x16x32_bf16 v[44:47], v[144:147], v[192:195], v[44:47]
	v_mfma_f32_16x16x32_bf16 v[40:43], v[160:163], v[192:195], v[40:43]
	v_mfma_f32_16x16x32_bf16 v[28:31], v[144:147], v[200:203], v[28:31]
	v_mfma_f32_16x16x32_bf16 v[24:27], v[160:163], v[200:203], v[24:27]
	v_mfma_f32_16x16x32_bf16 v[12:15], v[144:147], v[208:211], v[12:15]
	v_mfma_f32_16x16x32_bf16 v[8:11], v[160:163], v[208:211], v[8:11]
	v_mfma_f32_16x16x32_bf16 v[60:63], v[156:159], v[188:191], v[60:63]
	v_mfma_f32_16x16x32_bf16 v[56:59], v[164:167], v[188:191], v[56:59]
	v_mfma_f32_16x16x32_bf16 v[44:47], v[156:159], v[196:199], v[44:47]
	v_mfma_f32_16x16x32_bf16 v[40:43], v[164:167], v[196:199], v[40:43]
	v_mfma_f32_16x16x32_bf16 v[28:31], v[156:159], v[204:207], v[28:31]
	v_mfma_f32_16x16x32_bf16 v[24:27], v[164:167], v[204:207], v[24:27]
	v_mfma_f32_16x16x32_bf16 v[12:15], v[156:159], v[212:215], v[12:15]
	v_mfma_f32_16x16x32_bf16 v[8:11], v[164:167], v[212:215], v[8:11]
	v_mfma_f32_16x16x32_bf16 v[52:55], v[168:171], v[184:187], v[52:55]
	v_mfma_f32_16x16x32_bf16 v[48:51], v[176:179], v[184:187], v[48:51]
	v_mfma_f32_16x16x32_bf16 v[36:39], v[168:171], v[192:195], v[36:39]
	v_mfma_f32_16x16x32_bf16 v[32:35], v[176:179], v[192:195], v[32:35]
	v_mfma_f32_16x16x32_bf16 v[20:23], v[168:171], v[200:203], v[20:23]
	v_mfma_f32_16x16x32_bf16 v[16:19], v[176:179], v[200:203], v[16:19]
	v_mfma_f32_16x16x32_bf16 v[4:7], v[168:171], v[208:211], v[4:7]
	v_mfma_f32_16x16x32_bf16 v[0:3], v[176:179], v[208:211], v[0:3]
	v_mfma_f32_16x16x32_bf16 v[52:55], v[172:175], v[188:191], v[52:55]
	v_mfma_f32_16x16x32_bf16 v[48:51], v[180:183], v[188:191], v[48:51]
	v_mfma_f32_16x16x32_bf16 v[36:39], v[172:175], v[196:199], v[36:39]
	v_mfma_f32_16x16x32_bf16 v[32:35], v[180:183], v[196:199], v[32:35]
	v_mfma_f32_16x16x32_bf16 v[20:23], v[172:175], v[204:207], v[20:23]
	v_mfma_f32_16x16x32_bf16 v[16:19], v[180:183], v[204:207], v[16:19]
	v_mfma_f32_16x16x32_bf16 v[4:7], v[172:175], v[212:215], v[4:7]
	v_mfma_f32_16x16x32_bf16 v[0:3], v[180:183], v[212:215], v[0:3]
	s_setprio 0
	s_barrier
	s_add_i32 s36, s36, 2
	s_add_u32 s88, s88, 0x100
	s_addc_u32 s89, s89, 0
	s_add_u32 s33, s33, 0x100
	s_addc_u32 s35, s35, 0
	s_cmp_gt_u32 s36, 13
	s_cbranch_scc0 .LBB0_1393
	s_and_b64 vcc, exec, s[12:13]
	s_cbranch_vccz .LBB0_1396
	s_barrier

.LBB0_1417:
	ds_read_b128 v[144:147], v157
	ds_read_b128 v[148:151], v157 offset:1024
	ds_read_b128 v[160:163], v157 offset:2048
	ds_read_b128 v[164:167], v157 offset:3072
	ds_read_b128 v[168:171], v158
	ds_read_b128 v[172:175], v158 offset:1024
	ds_read_b128 v[176:179], v158 offset:2048
	ds_read_b128 v[180:183], v158 offset:3072
	s_add_u32 s3, s34, 0xfffe0080
	s_addc_u32 s42, s35, -1
	s_cmp_eq_u32 s37, 4
	s_cselect_b32 s91, s0, s42
	s_cselect_b32 s90, s1, s3
	s_cselect_b32 s81, s24, s36
	s_cselect_b32 s80, s27, s33
	s_add_i32 m0, s19, 0xc000
	ds_read_b128 v[184:187], v159
	ds_read_b128 v[188:191], v159 offset:1024
	ds_read_b128 v[192:195], v159 offset:2048
	ds_read_b128 v[196:199], v159 offset:3072
	ds_read_b128 v[200:203], v159 offset:4096
	ds_read_b128 v[204:207], v159 offset:5120
	ds_read_b128 v[208:211], v159 offset:6144
	ds_read_b128 v[212:215], v159 offset:7168
	global_load_lds_dwordx4 v136, s[34:35]
	s_add_i32 m0, s19, 0xe000
	s_nop 0
	global_load_lds_dwordx4 v138, s[34:35]
	s_waitcnt vmcnt(8)
	s_waitcnt lgkmcnt(0)
	s_barrier
	s_setprio 1
	s_waitcnt lgkmcnt(0)
	v_mfma_f32_16x16x32_bf16 v[124:127], v[144:147], v[184:187], v[124:127]
	v_mfma_f32_16x16x32_bf16 v[120:123], v[160:163], v[184:187], v[120:123]
	v_mfma_f32_16x16x32_bf16 v[108:111], v[144:147], v[192:195], v[108:111]
	v_mfma_f32_16x16x32_bf16 v[104:107], v[160:163], v[192:195], v[104:107]
	v_mfma_f32_16x16x32_bf16 v[92:95], v[144:147], v[200:203], v[92:95]
	v_mfma_f32_16x16x32_bf16 v[88:91], v[160:163], v[200:203], v[88:91]
	v_mfma_f32_16x16x32_bf16 v[76:79], v[144:147], v[208:211], v[76:79]
	v_mfma_f32_16x16x32_bf16 v[72:75], v[160:163], v[208:211], v[72:75]
	v_mfma_f32_16x16x32_bf16 v[124:127], v[148:151], v[188:191], v[124:127]
	v_mfma_f32_16x16x32_bf16 v[120:123], v[164:167], v[188:191], v[120:123]
	v_mfma_f32_16x16x32_bf16 v[108:111], v[148:151], v[196:199], v[108:111]
	v_mfma_f32_16x16x32_bf16 v[104:107], v[164:167], v[196:199], v[104:107]
	v_mfma_f32_16x16x32_bf16 v[92:95], v[148:151], v[204:207], v[92:95]
	v_mfma_f32_16x16x32_bf16 v[88:91], v[164:167], v[204:207], v[88:91]
	v_mfma_f32_16x16x32_bf16 v[76:79], v[148:151], v[212:215], v[76:79]
	v_mfma_f32_16x16x32_bf16 v[72:75], v[164:167], v[212:215], v[72:75]
	v_mfma_f32_16x16x32_bf16 v[116:119], v[168:171], v[184:187], v[116:119]
	v_mfma_f32_16x16x32_bf16 v[112:115], v[176:179], v[184:187], v[112:115]
	v_mfma_f32_16x16x32_bf16 v[100:103], v[168:171], v[192:195], v[100:103]
	v_mfma_f32_16x16x32_bf16 v[96:99], v[176:179], v[192:195], v[96:99]
	v_mfma_f32_16x16x32_bf16 v[84:87], v[168:171], v[200:203], v[84:87]
	v_mfma_f32_16x16x32_bf16 v[80:83], v[176:179], v[200:203], v[80:83]
	v_mfma_f32_16x16x32_bf16 v[68:71], v[168:171], v[208:211], v[68:71]
	v_mfma_f32_16x16x32_bf16 v[64:67], v[176:179], v[208:211], v[64:67]
	v_mfma_f32_16x16x32_bf16 v[116:119], v[172:175], v[188:191], v[116:119]
	v_mfma_f32_16x16x32_bf16 v[112:115], v[180:183], v[188:191], v[112:115]
	v_mfma_f32_16x16x32_bf16 v[100:103], v[172:175], v[196:199], v[100:103]
	v_mfma_f32_16x16x32_bf16 v[96:99], v[180:183], v[196:199], v[96:99]
	v_mfma_f32_16x16x32_bf16 v[84:87], v[172:175], v[204:207], v[84:87]
	v_mfma_f32_16x16x32_bf16 v[80:83], v[180:183], v[204:207], v[80:83]
	v_mfma_f32_16x16x32_bf16 v[68:71], v[172:175], v[212:215], v[68:71]
	v_mfma_f32_16x16x32_bf16 v[64:67], v[180:183], v[212:215], v[64:67]
	s_setprio 0
	s_barrier
	s_add_i32 s3, s78, s18
	s_mov_b32 m0, s3
	ds_read_b128 v[184:187], v159 offset:16384
	ds_read_b128 v[188:191], v159 offset:17408
	ds_read_b128 v[192:195], v159 offset:18432
	ds_read_b128 v[196:199], v159 offset:19456
	ds_read_b128 v[200:203], v159 offset:20480
	ds_read_b128 v[204:207], v159 offset:21504
	ds_read_b128 v[208:211], v159 offset:22528
	ds_read_b128 v[212:215], v159 offset:23552
	global_load_lds_dwordx4 v130, s[80:81]
	s_add_i32 m0, s3, 0x2000
	s_add_u32 s42, s80, 0x20000
	s_addc_u32 s43, s81, 0
	s_add_i32 s3, s79, s18
	global_load_lds_dwordx4 v134, s[80:81]
	s_mov_b32 m0, s3
	s_nop 0
	global_load_lds_dwordx4 v130, s[42:43]
	s_add_i32 m0, s3, 0x2000
	s_nop 0
	global_load_lds_dwordx4 v134, s[42:43]
	s_mov_b32 m0, s19
	s_nop 0
	global_load_lds_dwordx4 v128, s[90:91]
	s_mov_b32 m0, s25
	s_nop 0
	global_load_lds_dwordx4 v132, s[90:91]
	s_waitcnt vmcnt(8)
	s_waitcnt lgkmcnt(0)
	s_barrier
	s_setprio 1
	s_waitcnt lgkmcnt(0)
	v_mfma_f32_16x16x32_bf16 v[60:63], v[144:147], v[184:187], v[60:63]
	v_mfma_f32_16x16x32_bf16 v[56:59], v[160:163], v[184:187], v[56:59]
	v_mfma_f32_16x16x32_bf16 v[44:47], v[144:147], v[192:195], v[44:47]
	v_mfma_f32_16x16x32_bf16 v[40:43], v[160:163], v[192:195], v[40:43]
	v_mfma_f32_16x16x32_bf16 v[28:31], v[144:147], v[200:203], v[28:31]
	v_mfma_f32_16x16x32_bf16 v[24:27], v[160:163], v[200:203], v[24:27]
	v_mfma_f32_16x16x32_bf16 v[12:15], v[144:147], v[208:211], v[12:15]
	v_mfma_f32_16x16x32_bf16 v[8:11], v[160:163], v[208:211], v[8:11]
	v_mfma_f32_16x16x32_bf16 v[60:63], v[148:151], v[188:191], v[60:63]
	v_mfma_f32_16x16x32_bf16 v[56:59], v[164:167], v[188:191], v[56:59]
	v_mfma_f32_16x16x32_bf16 v[44:47], v[148:151], v[196:199], v[44:47]
	v_mfma_f32_16x16x32_bf16 v[40:43], v[164:167], v[196:199], v[40:43]
	v_mfma_f32_16x16x32_bf16 v[28:31], v[148:151], v[204:207], v[28:31]
	v_mfma_f32_16x16x32_bf16 v[24:27], v[164:167], v[204:207], v[24:27]
	v_mfma_f32_16x16x32_bf16 v[12:15], v[148:151], v[212:215], v[12:15]
	v_mfma_f32_16x16x32_bf16 v[8:11], v[164:167], v[212:215], v[8:11]
	v_mfma_f32_16x16x32_bf16 v[52:55], v[168:171], v[184:187], v[52:55]
	v_mfma_f32_16x16x32_bf16 v[48:51], v[176:179], v[184:187], v[48:51]
	v_mfma_f32_16x16x32_bf16 v[36:39], v[168:171], v[192:195], v[36:39]
	v_mfma_f32_16x16x32_bf16 v[32:35], v[176:179], v[192:195], v[32:35]
	v_mfma_f32_16x16x32_bf16 v[20:23], v[168:171], v[200:203], v[20:23]
	v_mfma_f32_16x16x32_bf16 v[16:19], v[176:179], v[200:203], v[16:19]
	v_mfma_f32_16x16x32_bf16 v[4:7], v[168:171], v[208:211], v[4:7]
	v_mfma_f32_16x16x32_bf16 v[0:3], v[176:179], v[208:211], v[0:3]
	v_mfma_f32_16x16x32_bf16 v[52:55], v[172:175], v[188:191], v[52:55]
	v_mfma_f32_16x16x32_bf16 v[48:51], v[180:183], v[188:191], v[48:51]
	v_mfma_f32_16x16x32_bf16 v[36:39], v[172:175], v[196:199], v[36:39]
	v_mfma_f32_16x16x32_bf16 v[32:35], v[180:183], v[196:199], v[32:35]
	v_mfma_f32_16x16x32_bf16 v[20:23], v[172:175], v[204:207], v[20:23]
	v_mfma_f32_16x16x32_bf16 v[16:19], v[180:183], v[204:207], v[16:19]
	v_mfma_f32_16x16x32_bf16 v[4:7], v[172:175], v[212:215], v[4:7]
	v_mfma_f32_16x16x32_bf16 v[0:3], v[180:183], v[212:215], v[0:3]
	s_setprio 0
	s_barrier
	s_add_i32 s3, 0, 0x18000
	s_add_i32 s44, 0, 0x1c000
	v_add_u32_e32 v164, s3, v155
	v_add_u32_e32 v180, s44, v155
	ds_read_b128 v[144:147], v164
	ds_read_b128 v[148:151], v164 offset:1024
	ds_read_b128 v[160:163], v164 offset:2048
	ds_read_b128 v[164:167], v164 offset:3072
	ds_read_b128 v[168:171], v180
	ds_read_b128 v[172:175], v180 offset:1024
	ds_read_b128 v[176:179], v180 offset:2048
	ds_read_b128 v[180:183], v180 offset:3072
	s_add_u32 s42, s90, 0x20000
	s_addc_u32 s43, s91, 0
	s_mov_b32 m0, s30
	ds_read_b128 v[184:187], v159 offset:32768
	ds_read_b128 v[188:191], v159 offset:33792
	ds_read_b128 v[192:195], v159 offset:34816
	ds_read_b128 v[196:199], v159 offset:35840
	ds_read_b128 v[200:203], v159 offset:36864
	ds_read_b128 v[204:207], v159 offset:37888
	ds_read_b128 v[208:211], v159 offset:38912
	ds_read_b128 v[212:215], v159 offset:39936
	global_load_lds_dwordx4 v128, s[42:43]
	v_lshl_add_u64 v[222:223], s[42:43], 0, v[132:133]
	s_mov_b32 m0, s31
	s_nop 0
	global_load_lds_dwordx4 v[222:223], off
	s_waitcnt vmcnt(8)
	s_waitcnt lgkmcnt(0)
	s_barrier
	s_setprio 1
	s_waitcnt lgkmcnt(0)
	v_mfma_f32_16x16x32_bf16 v[124:127], v[144:147], v[184:187], v[124:127]
	v_mfma_f32_16x16x32_bf16 v[120:123], v[160:163], v[184:187], v[120:123]
	v_mfma_f32_16x16x32_bf16 v[108:111], v[144:147], v[192:195], v[108:111]
	v_mfma_f32_16x16x32_bf16 v[104:107], v[160:163], v[192:195], v[104:107]
	v_mfma_f32_16x16x32_bf16 v[92:95], v[144:147], v[200:203], v[92:95]
	v_mfma_f32_16x16x32_bf16 v[88:91], v[160:163], v[200:203], v[88:91]
	v_mfma_f32_16x16x32_bf16 v[76:79], v[144:147], v[208:211], v[76:79]
	v_mfma_f32_16x16x32_bf16 v[72:75], v[160:163], v[208:211], v[72:75]
	v_mfma_f32_16x16x32_bf16 v[124:127], v[148:151], v[188:191], v[124:127]
	v_mfma_f32_16x16x32_bf16 v[120:123], v[164:167], v[188:191], v[120:123]
	v_mfma_f32_16x16x32_bf16 v[108:111], v[148:151], v[196:199], v[108:111]
	v_mfma_f32_16x16x32_bf16 v[104:107], v[164:167], v[196:199], v[104:107]
	v_mfma_f32_16x16x32_bf16 v[92:95], v[148:151], v[204:207], v[92:95]
	v_mfma_f32_16x16x32_bf16 v[88:91], v[164:167], v[204:207], v[88:91]
	v_mfma_f32_16x16x32_bf16 v[76:79], v[148:151], v[212:215], v[76:79]
	v_mfma_f32_16x16x32_bf16 v[72:75], v[164:167], v[212:215], v[72:75]
	v_mfma_f32_16x16x32_bf16 v[116:119], v[168:171], v[184:187], v[116:119]
	v_mfma_f32_16x16x32_bf16 v[112:115], v[176:179], v[184:187], v[112:115]
	v_mfma_f32_16x16x32_bf16 v[100:103], v[168:171], v[192:195], v[100:103]
	v_mfma_f32_16x16x32_bf16 v[96:99], v[176:179], v[192:195], v[96:99]
	v_mfma_f32_16x16x32_bf16 v[84:87], v[168:171], v[200:203], v[84:87]
	v_mfma_f32_16x16x32_bf16 v[80:83], v[176:179], v[200:203], v[80:83]
	v_mfma_f32_16x16x32_bf16 v[68:71], v[168:171], v[208:211], v[68:71]
	v_mfma_f32_16x16x32_bf16 v[64:67], v[176:179], v[208:211], v[64:67]
	v_mfma_f32_16x16x32_bf16 v[116:119], v[172:175], v[188:191], v[116:119]
	v_mfma_f32_16x16x32_bf16 v[112:115], v[180:183], v[188:191], v[112:115]
	v_mfma_f32_16x16x32_bf16 v[100:103], v[172:175], v[196:199], v[100:103]
	v_mfma_f32_16x16x32_bf16 v[96:99], v[180:183], v[196:199], v[96:99]
	v_mfma_f32_16x16x32_bf16 v[84:87], v[172:175], v[204:207], v[84:87]
	v_mfma_f32_16x16x32_bf16 v[80:83], v[180:183], v[204:207], v[80:83]
	v_mfma_f32_16x16x32_bf16 v[68:71], v[172:175], v[212:215], v[68:71]
	v_mfma_f32_16x16x32_bf16 v[64:67], v[180:183], v[212:215], v[64:67]
	s_setprio 0
	s_barrier
	s_add_i32 s3, s3, s18
	s_add_u32 s42, s80, 0x80
	s_addc_u32 s43, s81, 0
	s_mov_b32 m0, s3
	ds_read_b128 v[184:187], v159 offset:49152
	ds_read_b128 v[188:191], v159 offset:50176
	ds_read_b128 v[192:195], v159 offset:51200
	ds_read_b128 v[196:199], v159 offset:52224
	ds_read_b128 v[200:203], v159 offset:53248
	ds_read_b128 v[204:207], v159 offset:54272
	ds_read_b128 v[208:211], v159 offset:55296
	ds_read_b128 v[212:215], v159 offset:56320
	global_load_lds_dwordx4 v130, s[42:43]
	s_add_i32 m0, s3, 0x2000
	s_add_i32 s3, s44, s18
	global_load_lds_dwordx4 v134, s[42:43]
	s_add_u32 s42, s42, 0x20000
	s_addc_u32 s43, s43, 0
	s_mov_b32 m0, s3
	s_nop 0
	global_load_lds_dwordx4 v130, s[42:43]
	s_add_i32 m0, s3, 0x2000
	s_nop 0
	global_load_lds_dwordx4 v134, s[42:43]
	s_add_u32 s90, s90, 0x80
	s_addc_u32 s91, s91, 0
	s_mov_b32 m0, s58
	s_nop 0
	global_load_lds_dwordx4 v128, s[90:91]
	s_mov_b32 m0, s59
	s_nop 0
	global_load_lds_dwordx4 v132, s[90:91]
	s_waitcnt vmcnt(8)
	s_waitcnt lgkmcnt(0)
	s_barrier
	s_setprio 1
	s_waitcnt lgkmcnt(0)
	v_mfma_f32_16x16x32_bf16 v[60:63], v[144:147], v[184:187], v[60:63]
	v_mfma_f32_16x16x32_bf16 v[56:59], v[160:163], v[184:187], v[56:59]
	v_mfma_f32_16x16x32_bf16 v[44:47], v[144:147], v[192:195], v[44:47]
	v_mfma_f32_16x16x32_bf16 v[40:43], v[160:163], v[192:195], v[40:43]
	v_mfma_f32_16x16x32_bf16 v[28:31], v[144:147], v[200:203], v[28:31]
	v_mfma_f32_16x16x32_bf16 v[24:27], v[160:163], v[200:203], v[24:27]
	v_mfma_f32_16x16x32_bf16 v[12:15], v[144:147], v[208:211], v[12:15]
	v_mfma_f32_16x16x32_bf16 v[8:11], v[160:163], v[208:211], v[8:11]
	v_mfma_f32_16x16x32_bf16 v[60:63], v[148:151], v[188:191], v[60:63]
	v_mfma_f32_16x16x32_bf16 v[56:59], v[164:167], v[188:191], v[56:59]
	v_mfma_f32_16x16x32_bf16 v[44:47], v[148:151], v[196:199], v[44:47]
	v_mfma_f32_16x16x32_bf16 v[40:43], v[164:167], v[196:199], v[40:43]
	v_mfma_f32_16x16x32_bf16 v[28:31], v[148:151], v[204:207], v[28:31]
	v_mfma_f32_16x16x32_bf16 v[24:27], v[164:167], v[204:207], v[24:27]
	v_mfma_f32_16x16x32_bf16 v[12:15], v[148:151], v[212:215], v[12:15]
	v_mfma_f32_16x16x32_bf16 v[8:11], v[164:167], v[212:215], v[8:11]
	v_mfma_f32_16x16x32_bf16 v[52:55], v[168:171], v[184:187], v[52:55]
	v_mfma_f32_16x16x32_bf16 v[48:51], v[176:179], v[184:187], v[48:51]
	v_mfma_f32_16x16x32_bf16 v[36:39], v[168:171], v[192:195], v[36:39]
	v_mfma_f32_16x16x32_bf16 v[32:35], v[176:179], v[192:195], v[32:35]
	v_mfma_f32_16x16x32_bf16 v[20:23], v[168:171], v[200:203], v[20:23]
	v_mfma_f32_16x16x32_bf16 v[16:19], v[176:179], v[200:203], v[16:19]
	v_mfma_f32_16x16x32_bf16 v[4:7], v[168:171], v[208:211], v[4:7]
	v_mfma_f32_16x16x32_bf16 v[0:3], v[176:179], v[208:211], v[0:3]
	v_mfma_f32_16x16x32_bf16 v[52:55], v[172:175], v[188:191], v[52:55]
	v_mfma_f32_16x16x32_bf16 v[48:51], v[180:183], v[188:191], v[48:51]
	v_mfma_f32_16x16x32_bf16 v[36:39], v[172:175], v[196:199], v[36:39]
	v_mfma_f32_16x16x32_bf16 v[32:35], v[180:183], v[196:199], v[32:35]
	v_mfma_f32_16x16x32_bf16 v[20:23], v[172:175], v[204:207], v[20:23]
	v_mfma_f32_16x16x32_bf16 v[16:19], v[180:183], v[204:207], v[16:19]
	v_mfma_f32_16x16x32_bf16 v[4:7], v[172:175], v[212:215], v[4:7]
	v_mfma_f32_16x16x32_bf16 v[0:3], v[180:183], v[212:215], v[0:3]
	s_setprio 0
	s_barrier
	s_add_i32 s37, s37, 2
	s_add_u32 s34, s34, 0x100
	s_addc_u32 s35, s35, 0
	s_add_u32 s33, s33, 0x100
	s_addc_u32 s36, s36, 0
	s_cmp_gt_u32 s37, 5
	s_cbranch_scc0 .LBB0_1417
	s_and_b64 vcc, exec, s[14:15]
	s_cbranch_vccz .LBB0_1420
	s_barrier

.LBB0_1493:
	ds_read_b128 v[140:143], v149
	ds_read_b128 v[152:155], v149 offset:1024
	ds_read_b128 v[156:159], v149 offset:2048
	ds_read_b128 v[160:163], v149 offset:3072
	ds_read_b128 v[164:167], v150
	ds_read_b128 v[168:171], v150 offset:1024
	ds_read_b128 v[172:175], v150 offset:2048
	ds_read_b128 v[176:179], v150 offset:3072
	s_add_u32 s3, s86, 0xfff80080
	s_addc_u32 s33, s87, -1
	s_cmp_eq_u32 s27, 28
	s_cselect_b32 s89, s0, s33
	s_cselect_b32 s88, s1, s3
	s_cselect_b32 s81, s15, s24
	s_cselect_b32 s80, s17, s19
	s_add_i32 m0, s30, 0xc000
	ds_read_b128 v[180:183], v151
	ds_read_b128 v[184:187], v151 offset:1024
	ds_read_b128 v[188:191], v151 offset:2048
	ds_read_b128 v[192:195], v151 offset:3072
	ds_read_b128 v[196:199], v151 offset:4096
	ds_read_b128 v[200:203], v151 offset:5120
	ds_read_b128 v[204:207], v151 offset:6144
	ds_read_b128 v[208:211], v151 offset:7168
	global_load_lds_dwordx4 v132, s[86:87]
	s_add_i32 m0, s30, 0xe000
	s_nop 0
	global_load_lds_dwordx4 v134, s[86:87]
	s_waitcnt vmcnt(8)
	s_waitcnt lgkmcnt(0)
	s_barrier
	s_setprio 1
	s_waitcnt lgkmcnt(0)
	v_mfma_f32_16x16x32_bf16 v[124:127], v[140:143], v[180:183], v[124:127]
	v_mfma_f32_16x16x32_bf16 v[120:123], v[156:159], v[180:183], v[120:123]
	v_mfma_f32_16x16x32_bf16 v[108:111], v[140:143], v[188:191], v[108:111]
	v_mfma_f32_16x16x32_bf16 v[104:107], v[156:159], v[188:191], v[104:107]
	v_mfma_f32_16x16x32_bf16 v[92:95], v[140:143], v[196:199], v[92:95]
	v_mfma_f32_16x16x32_bf16 v[88:91], v[156:159], v[196:199], v[88:91]
	v_mfma_f32_16x16x32_bf16 v[76:79], v[140:143], v[204:207], v[76:79]
	v_mfma_f32_16x16x32_bf16 v[72:75], v[156:159], v[204:207], v[72:75]
	v_mfma_f32_16x16x32_bf16 v[124:127], v[152:155], v[184:187], v[124:127]
	v_mfma_f32_16x16x32_bf16 v[120:123], v[160:163], v[184:187], v[120:123]
	v_mfma_f32_16x16x32_bf16 v[108:111], v[152:155], v[192:195], v[108:111]
	v_mfma_f32_16x16x32_bf16 v[104:107], v[160:163], v[192:195], v[104:107]
	v_mfma_f32_16x16x32_bf16 v[92:95], v[152:155], v[200:203], v[92:95]
	v_mfma_f32_16x16x32_bf16 v[88:91], v[160:163], v[200:203], v[88:91]
	v_mfma_f32_16x16x32_bf16 v[76:79], v[152:155], v[208:211], v[76:79]
	v_mfma_f32_16x16x32_bf16 v[72:75], v[160:163], v[208:211], v[72:75]
	v_mfma_f32_16x16x32_bf16 v[116:119], v[164:167], v[180:183], v[116:119]
	v_mfma_f32_16x16x32_bf16 v[112:115], v[172:175], v[180:183], v[112:115]
	v_mfma_f32_16x16x32_bf16 v[100:103], v[164:167], v[188:191], v[100:103]
	v_mfma_f32_16x16x32_bf16 v[96:99], v[172:175], v[188:191], v[96:99]
	v_mfma_f32_16x16x32_bf16 v[84:87], v[164:167], v[196:199], v[84:87]
	v_mfma_f32_16x16x32_bf16 v[80:83], v[172:175], v[196:199], v[80:83]
	v_mfma_f32_16x16x32_bf16 v[68:71], v[164:167], v[204:207], v[68:71]
	v_mfma_f32_16x16x32_bf16 v[64:67], v[172:175], v[204:207], v[64:67]
	v_mfma_f32_16x16x32_bf16 v[116:119], v[168:171], v[184:187], v[116:119]
	v_mfma_f32_16x16x32_bf16 v[112:115], v[176:179], v[184:187], v[112:115]
	v_mfma_f32_16x16x32_bf16 v[100:103], v[168:171], v[192:195], v[100:103]
	v_mfma_f32_16x16x32_bf16 v[96:99], v[176:179], v[192:195], v[96:99]
	v_mfma_f32_16x16x32_bf16 v[84:87], v[168:171], v[200:203], v[84:87]
	v_mfma_f32_16x16x32_bf16 v[80:83], v[176:179], v[200:203], v[80:83]
	v_mfma_f32_16x16x32_bf16 v[68:71], v[168:171], v[208:211], v[68:71]
	v_mfma_f32_16x16x32_bf16 v[64:67], v[176:179], v[208:211], v[64:67]
	s_setprio 0
	s_barrier
	s_add_i32 s3, s59, s25
	s_mov_b32 m0, s3
	ds_read_b128 v[180:183], v151 offset:16384
	ds_read_b128 v[184:187], v151 offset:17408
	ds_read_b128 v[188:191], v151 offset:18432
	ds_read_b128 v[192:195], v151 offset:19456
	ds_read_b128 v[196:199], v151 offset:20480
	ds_read_b128 v[200:203], v151 offset:21504
	ds_read_b128 v[204:207], v151 offset:22528
	ds_read_b128 v[208:211], v151 offset:23552
	global_load_lds_dwordx4 v128, s[80:81]
	s_add_i32 m0, s3, 0x2000
	s_add_u32 s36, s80, 0x80000
	s_addc_u32 s37, s81, 0
	s_add_i32 s3, s68, s25
	global_load_lds_dwordx4 v130, s[80:81]
	s_mov_b32 m0, s3
	s_nop 0
	global_load_lds_dwordx4 v128, s[36:37]
	s_add_i32 m0, s3, 0x2000
	s_nop 0
	global_load_lds_dwordx4 v130, s[36:37]
	s_mov_b32 m0, s30
	s_nop 0
	global_load_lds_dwordx4 v128, s[88:89]
	s_mov_b32 m0, s31
	s_nop 0
	global_load_lds_dwordx4 v130, s[88:89]
	s_waitcnt vmcnt(8)
	s_waitcnt lgkmcnt(0)
	s_barrier
	s_setprio 1
	s_waitcnt lgkmcnt(0)
	v_mfma_f32_16x16x32_bf16 v[60:63], v[140:143], v[180:183], v[60:63]
	v_mfma_f32_16x16x32_bf16 v[56:59], v[156:159], v[180:183], v[56:59]
	v_mfma_f32_16x16x32_bf16 v[44:47], v[140:143], v[188:191], v[44:47]
	v_mfma_f32_16x16x32_bf16 v[40:43], v[156:159], v[188:191], v[40:43]
	v_mfma_f32_16x16x32_bf16 v[28:31], v[140:143], v[196:199], v[28:31]
	v_mfma_f32_16x16x32_bf16 v[24:27], v[156:159], v[196:199], v[24:27]
	v_mfma_f32_16x16x32_bf16 v[12:15], v[140:143], v[204:207], v[12:15]
	v_mfma_f32_16x16x32_bf16 v[8:11], v[156:159], v[204:207], v[8:11]
	v_mfma_f32_16x16x32_bf16 v[60:63], v[152:155], v[184:187], v[60:63]
	v_mfma_f32_16x16x32_bf16 v[56:59], v[160:163], v[184:187], v[56:59]
	v_mfma_f32_16x16x32_bf16 v[44:47], v[152:155], v[192:195], v[44:47]
	v_mfma_f32_16x16x32_bf16 v[40:43], v[160:163], v[192:195], v[40:43]
	v_mfma_f32_16x16x32_bf16 v[28:31], v[152:155], v[200:203], v[28:31]
	v_mfma_f32_16x16x32_bf16 v[24:27], v[160:163], v[200:203], v[24:27]
	v_mfma_f32_16x16x32_bf16 v[12:15], v[152:155], v[208:211], v[12:15]
	v_mfma_f32_16x16x32_bf16 v[8:11], v[160:163], v[208:211], v[8:11]
	v_mfma_f32_16x16x32_bf16 v[52:55], v[164:167], v[180:183], v[52:55]
	v_mfma_f32_16x16x32_bf16 v[48:51], v[172:175], v[180:183], v[48:51]
	v_mfma_f32_16x16x32_bf16 v[36:39], v[164:167], v[188:191], v[36:39]
	v_mfma_f32_16x16x32_bf16 v[32:35], v[172:175], v[188:191], v[32:35]
	v_mfma_f32_16x16x32_bf16 v[20:23], v[164:167], v[196:199], v[20:23]
	v_mfma_f32_16x16x32_bf16 v[16:19], v[172:175], v[196:199], v[16:19]
	v_mfma_f32_16x16x32_bf16 v[4:7], v[164:167], v[204:207], v[4:7]
	v_mfma_f32_16x16x32_bf16 v[0:3], v[172:175], v[204:207], v[0:3]
	v_mfma_f32_16x16x32_bf16 v[52:55], v[168:171], v[184:187], v[52:55]
	v_mfma_f32_16x16x32_bf16 v[48:51], v[176:179], v[184:187], v[48:51]
	v_mfma_f32_16x16x32_bf16 v[36:39], v[168:171], v[192:195], v[36:39]
	v_mfma_f32_16x16x32_bf16 v[32:35], v[176:179], v[192:195], v[32:35]
	v_mfma_f32_16x16x32_bf16 v[20:23], v[168:171], v[200:203], v[20:23]
	v_mfma_f32_16x16x32_bf16 v[16:19], v[176:179], v[200:203], v[16:19]
	v_mfma_f32_16x16x32_bf16 v[4:7], v[168:171], v[208:211], v[4:7]
	v_mfma_f32_16x16x32_bf16 v[0:3], v[176:179], v[208:211], v[0:3]
	s_setprio 0
	s_barrier
	s_add_i32 s3, 0, 0x18000
	s_add_i32 s33, 0, 0x1c000
	v_add_u32_e32 v160, s3, v147
	v_add_u32_e32 v176, s33, v147
	ds_read_b128 v[140:143], v160
	ds_read_b128 v[152:155], v160 offset:1024
	ds_read_b128 v[156:159], v160 offset:2048
	ds_read_b128 v[160:163], v160 offset:3072
	ds_read_b128 v[164:167], v176
	ds_read_b128 v[168:171], v176 offset:1024
	ds_read_b128 v[172:175], v176 offset:2048
	ds_read_b128 v[176:179], v176 offset:3072
	s_add_u32 s36, s88, 0x80000
	s_addc_u32 s37, s89, 0
	s_mov_b32 m0, s52
	ds_read_b128 v[180:183], v151 offset:32768
	ds_read_b128 v[184:187], v151 offset:33792
	ds_read_b128 v[188:191], v151 offset:34816
	ds_read_b128 v[192:195], v151 offset:35840
	ds_read_b128 v[196:199], v151 offset:36864
	ds_read_b128 v[200:203], v151 offset:37888
	ds_read_b128 v[204:207], v151 offset:38912
	ds_read_b128 v[208:211], v151 offset:39936
	global_load_lds_dwordx4 v128, s[36:37]
	v_lshl_add_u64 v[218:219], s[36:37], 0, v[130:131]
	s_mov_b32 m0, s53
	s_nop 0
	global_load_lds_dwordx4 v[218:219], off
	s_waitcnt vmcnt(8)
	s_waitcnt lgkmcnt(0)
	s_barrier
	s_setprio 1
	s_waitcnt lgkmcnt(0)
	v_mfma_f32_16x16x32_bf16 v[124:127], v[140:143], v[180:183], v[124:127]
	v_mfma_f32_16x16x32_bf16 v[120:123], v[156:159], v[180:183], v[120:123]
	v_mfma_f32_16x16x32_bf16 v[108:111], v[140:143], v[188:191], v[108:111]
	v_mfma_f32_16x16x32_bf16 v[104:107], v[156:159], v[188:191], v[104:107]
	v_mfma_f32_16x16x32_bf16 v[92:95], v[140:143], v[196:199], v[92:95]
	v_mfma_f32_16x16x32_bf16 v[88:91], v[156:159], v[196:199], v[88:91]
	v_mfma_f32_16x16x32_bf16 v[76:79], v[140:143], v[204:207], v[76:79]
	v_mfma_f32_16x16x32_bf16 v[72:75], v[156:159], v[204:207], v[72:75]
	v_mfma_f32_16x16x32_bf16 v[124:127], v[152:155], v[184:187], v[124:127]
	v_mfma_f32_16x16x32_bf16 v[120:123], v[160:163], v[184:187], v[120:123]
	v_mfma_f32_16x16x32_bf16 v[108:111], v[152:155], v[192:195], v[108:111]
	v_mfma_f32_16x16x32_bf16 v[104:107], v[160:163], v[192:195], v[104:107]
	v_mfma_f32_16x16x32_bf16 v[92:95], v[152:155], v[200:203], v[92:95]
	v_mfma_f32_16x16x32_bf16 v[88:91], v[160:163], v[200:203], v[88:91]
	v_mfma_f32_16x16x32_bf16 v[76:79], v[152:155], v[208:211], v[76:79]
	v_mfma_f32_16x16x32_bf16 v[72:75], v[160:163], v[208:211], v[72:75]
	v_mfma_f32_16x16x32_bf16 v[116:119], v[164:167], v[180:183], v[116:119]
	v_mfma_f32_16x16x32_bf16 v[112:115], v[172:175], v[180:183], v[112:115]
	v_mfma_f32_16x16x32_bf16 v[100:103], v[164:167], v[188:191], v[100:103]
	v_mfma_f32_16x16x32_bf16 v[96:99], v[172:175], v[188:191], v[96:99]
	v_mfma_f32_16x16x32_bf16 v[84:87], v[164:167], v[196:199], v[84:87]
	v_mfma_f32_16x16x32_bf16 v[80:83], v[172:175], v[196:199], v[80:83]
	v_mfma_f32_16x16x32_bf16 v[68:71], v[164:167], v[204:207], v[68:71]
	v_mfma_f32_16x16x32_bf16 v[64:67], v[172:175], v[204:207], v[64:67]
	v_mfma_f32_16x16x32_bf16 v[116:119], v[168:171], v[184:187], v[116:119]
	v_mfma_f32_16x16x32_bf16 v[112:115], v[176:179], v[184:187], v[112:115]
	v_mfma_f32_16x16x32_bf16 v[100:103], v[168:171], v[192:195], v[100:103]
	v_mfma_f32_16x16x32_bf16 v[96:99], v[176:179], v[192:195], v[96:99]
	v_mfma_f32_16x16x32_bf16 v[84:87], v[168:171], v[200:203], v[84:87]
	v_mfma_f32_16x16x32_bf16 v[80:83], v[176:179], v[200:203], v[80:83]
	v_mfma_f32_16x16x32_bf16 v[68:71], v[168:171], v[208:211], v[68:71]
	v_mfma_f32_16x16x32_bf16 v[64:67], v[176:179], v[208:211], v[64:67]
	s_setprio 0
	s_barrier
	s_add_i32 s3, s3, s25
	s_add_u32 s36, s80, 0x80
	s_addc_u32 s37, s81, 0
	s_mov_b32 m0, s3
	ds_read_b128 v[180:183], v151 offset:49152
	ds_read_b128 v[184:187], v151 offset:50176
	ds_read_b128 v[188:191], v151 offset:51200
	ds_read_b128 v[192:195], v151 offset:52224
	ds_read_b128 v[196:199], v151 offset:53248
	ds_read_b128 v[200:203], v151 offset:54272
	ds_read_b128 v[204:207], v151 offset:55296
	ds_read_b128 v[208:211], v151 offset:56320
	global_load_lds_dwordx4 v128, s[36:37]
	s_add_i32 m0, s3, 0x2000
	s_add_i32 s3, s33, s25
	global_load_lds_dwordx4 v130, s[36:37]
	s_add_u32 s36, s36, 0x80000
	s_addc_u32 s37, s37, 0
	s_mov_b32 m0, s3
	s_nop 0
	global_load_lds_dwordx4 v128, s[36:37]
	s_add_i32 m0, s3, 0x2000
	s_nop 0
	global_load_lds_dwordx4 v130, s[36:37]
	s_add_u32 s88, s88, 0x80
	s_addc_u32 s89, s89, 0
	s_mov_b32 m0, s57
	s_nop 0
	global_load_lds_dwordx4 v128, s[88:89]
	s_mov_b32 m0, s58
	s_nop 0
	global_load_lds_dwordx4 v130, s[88:89]
	s_waitcnt vmcnt(8)
	s_waitcnt lgkmcnt(0)
	s_barrier
	s_setprio 1
	s_waitcnt lgkmcnt(0)
	v_mfma_f32_16x16x32_bf16 v[60:63], v[140:143], v[180:183], v[60:63]
	v_mfma_f32_16x16x32_bf16 v[56:59], v[156:159], v[180:183], v[56:59]
	v_mfma_f32_16x16x32_bf16 v[44:47], v[140:143], v[188:191], v[44:47]
	v_mfma_f32_16x16x32_bf16 v[40:43], v[156:159], v[188:191], v[40:43]
	v_mfma_f32_16x16x32_bf16 v[28:31], v[140:143], v[196:199], v[28:31]
	v_mfma_f32_16x16x32_bf16 v[24:27], v[156:159], v[196:199], v[24:27]
	v_mfma_f32_16x16x32_bf16 v[12:15], v[140:143], v[204:207], v[12:15]
	v_mfma_f32_16x16x32_bf16 v[8:11], v[156:159], v[204:207], v[8:11]
	v_mfma_f32_16x16x32_bf16 v[60:63], v[152:155], v[184:187], v[60:63]
	v_mfma_f32_16x16x32_bf16 v[56:59], v[160:163], v[184:187], v[56:59]
	v_mfma_f32_16x16x32_bf16 v[44:47], v[152:155], v[192:195], v[44:47]
	v_mfma_f32_16x16x32_bf16 v[40:43], v[160:163], v[192:195], v[40:43]
	v_mfma_f32_16x16x32_bf16 v[28:31], v[152:155], v[200:203], v[28:31]
	v_mfma_f32_16x16x32_bf16 v[24:27], v[160:163], v[200:203], v[24:27]
	v_mfma_f32_16x16x32_bf16 v[12:15], v[152:155], v[208:211], v[12:15]
	v_mfma_f32_16x16x32_bf16 v[8:11], v[160:163], v[208:211], v[8:11]
	v_mfma_f32_16x16x32_bf16 v[52:55], v[164:167], v[180:183], v[52:55]
	v_mfma_f32_16x16x32_bf16 v[48:51], v[172:175], v[180:183], v[48:51]
	v_mfma_f32_16x16x32_bf16 v[36:39], v[164:167], v[188:191], v[36:39]
	v_mfma_f32_16x16x32_bf16 v[32:35], v[172:175], v[188:191], v[32:35]
	v_mfma_f32_16x16x32_bf16 v[20:23], v[164:167], v[196:199], v[20:23]
	v_mfma_f32_16x16x32_bf16 v[16:19], v[172:175], v[196:199], v[16:19]
	v_mfma_f32_16x16x32_bf16 v[4:7], v[164:167], v[204:207], v[4:7]
	v_mfma_f32_16x16x32_bf16 v[0:3], v[172:175], v[204:207], v[0:3]
	v_mfma_f32_16x16x32_bf16 v[52:55], v[168:171], v[184:187], v[52:55]
	v_mfma_f32_16x16x32_bf16 v[48:51], v[176:179], v[184:187], v[48:51]
	v_mfma_f32_16x16x32_bf16 v[36:39], v[168:171], v[192:195], v[36:39]
	v_mfma_f32_16x16x32_bf16 v[32:35], v[176:179], v[192:195], v[32:35]
	v_mfma_f32_16x16x32_bf16 v[20:23], v[168:171], v[200:203], v[20:23]
	v_mfma_f32_16x16x32_bf16 v[16:19], v[176:179], v[200:203], v[16:19]
	v_mfma_f32_16x16x32_bf16 v[4:7], v[168:171], v[208:211], v[4:7]
	v_mfma_f32_16x16x32_bf16 v[0:3], v[176:179], v[208:211], v[0:3]
	s_setprio 0
	s_barrier
	s_add_i32 s27, s27, 2
	s_add_u32 s86, s86, 0x100
	s_addc_u32 s87, s87, 0
	s_add_u32 s19, s19, 0x100
	s_addc_u32 s24, s24, 0
	s_cmp_gt_u32 s27, 29
	s_cbranch_scc0 .LBB0_1493
	s_and_b64 vcc, exec, s[12:13]
	s_cbranch_vccz .LBB0_1496
	s_barrier

.LBB0_1624:
	ds_read_b128 v[154:157], v150
	ds_read_b128 v[158:161], v150 offset:1024
	ds_read_b128 v[162:165], v150 offset:2048
	ds_read_b128 v[166:169], v150 offset:3072
	ds_read_b128 v[170:173], v151
	ds_read_b128 v[174:177], v151 offset:1024
	ds_read_b128 v[178:181], v151 offset:2048
	ds_read_b128 v[182:185], v151 offset:3072
	s_add_u32 s3, s88, 0xfff80080
	s_addc_u32 s42, s89, -1
	s_cmp_eq_u32 s37, 28
	s_cselect_b32 s93, s0, s42
	s_cselect_b32 s92, s1, s3
	s_cselect_b32 s91, s27, s36
	s_cselect_b32 s90, s33, s35
	s_add_i32 m0, s9, 0xc000
	ds_read_b128 v[186:189], v152
	ds_read_b128 v[190:193], v152 offset:1024
	ds_read_b128 v[194:197], v152 offset:2048
	ds_read_b128 v[198:201], v152 offset:3072
	ds_read_b128 v[202:205], v152 offset:4096
	ds_read_b128 v[206:209], v152 offset:5120
	ds_read_b128 v[210:213], v152 offset:6144
	ds_read_b128 v[214:217], v152 offset:7168
	global_load_lds_dwordx4 v138, s[88:89]
	s_add_i32 m0, s9, 0xe000
	s_nop 0
	global_load_lds_dwordx4 v140, s[88:89]
	s_waitcnt vmcnt(8)
	s_waitcnt lgkmcnt(0)
	s_barrier
	s_setprio 1
	s_waitcnt lgkmcnt(0)
	v_mfma_f32_16x16x32_bf16 v[124:127], v[154:157], v[186:189], v[124:127]
	v_mfma_f32_16x16x32_bf16 v[120:123], v[162:165], v[186:189], v[120:123]
	v_mfma_f32_16x16x32_bf16 v[108:111], v[154:157], v[194:197], v[108:111]
	v_mfma_f32_16x16x32_bf16 v[104:107], v[162:165], v[194:197], v[104:107]
	v_mfma_f32_16x16x32_bf16 v[92:95], v[154:157], v[202:205], v[92:95]
	v_mfma_f32_16x16x32_bf16 v[88:91], v[162:165], v[202:205], v[88:91]
	v_mfma_f32_16x16x32_bf16 v[76:79], v[154:157], v[210:213], v[76:79]
	v_mfma_f32_16x16x32_bf16 v[72:75], v[162:165], v[210:213], v[72:75]
	v_mfma_f32_16x16x32_bf16 v[124:127], v[158:161], v[190:193], v[124:127]
	v_mfma_f32_16x16x32_bf16 v[120:123], v[166:169], v[190:193], v[120:123]
	v_mfma_f32_16x16x32_bf16 v[108:111], v[158:161], v[198:201], v[108:111]
	v_mfma_f32_16x16x32_bf16 v[104:107], v[166:169], v[198:201], v[104:107]
	v_mfma_f32_16x16x32_bf16 v[92:95], v[158:161], v[206:209], v[92:95]
	v_mfma_f32_16x16x32_bf16 v[88:91], v[166:169], v[206:209], v[88:91]
	v_mfma_f32_16x16x32_bf16 v[76:79], v[158:161], v[214:217], v[76:79]
	v_mfma_f32_16x16x32_bf16 v[72:75], v[166:169], v[214:217], v[72:75]
	v_mfma_f32_16x16x32_bf16 v[116:119], v[170:173], v[186:189], v[116:119]
	v_mfma_f32_16x16x32_bf16 v[112:115], v[178:181], v[186:189], v[112:115]
	v_mfma_f32_16x16x32_bf16 v[100:103], v[170:173], v[194:197], v[100:103]
	v_mfma_f32_16x16x32_bf16 v[96:99], v[178:181], v[194:197], v[96:99]
	v_mfma_f32_16x16x32_bf16 v[84:87], v[170:173], v[202:205], v[84:87]
	v_mfma_f32_16x16x32_bf16 v[80:83], v[178:181], v[202:205], v[80:83]
	v_mfma_f32_16x16x32_bf16 v[68:71], v[170:173], v[210:213], v[68:71]
	v_mfma_f32_16x16x32_bf16 v[64:67], v[178:181], v[210:213], v[64:67]
	v_mfma_f32_16x16x32_bf16 v[116:119], v[174:177], v[190:193], v[116:119]
	v_mfma_f32_16x16x32_bf16 v[112:115], v[182:185], v[190:193], v[112:115]
	v_mfma_f32_16x16x32_bf16 v[100:103], v[174:177], v[198:201], v[100:103]
	v_mfma_f32_16x16x32_bf16 v[96:99], v[182:185], v[198:201], v[96:99]
	v_mfma_f32_16x16x32_bf16 v[84:87], v[174:177], v[206:209], v[84:87]
	v_mfma_f32_16x16x32_bf16 v[80:83], v[182:185], v[206:209], v[80:83]
	v_mfma_f32_16x16x32_bf16 v[68:71], v[174:177], v[214:217], v[68:71]
	v_mfma_f32_16x16x32_bf16 v[64:67], v[182:185], v[214:217], v[64:67]
	s_setprio 0
	s_barrier
	s_add_i32 s3, s48, s8
	s_mov_b32 m0, s3
	ds_read_b128 v[186:189], v152 offset:16384
	ds_read_b128 v[190:193], v152 offset:17408
	ds_read_b128 v[194:197], v152 offset:18432
	ds_read_b128 v[198:201], v152 offset:19456
	ds_read_b128 v[202:205], v152 offset:20480
	ds_read_b128 v[206:209], v152 offset:21504
	ds_read_b128 v[210:213], v152 offset:22528
	ds_read_b128 v[214:217], v152 offset:23552
	global_load_lds_dwordx4 v130, s[90:91]
	s_add_i32 m0, s3, 0x2000
	s_add_u32 s42, s90, 0x80000
	s_addc_u32 s43, s91, 0
	s_add_i32 s3, s49, s8
	global_load_lds_dwordx4 v134, s[90:91]
	s_mov_b32 m0, s3
	s_nop 0
	global_load_lds_dwordx4 v130, s[42:43]
	s_add_i32 m0, s3, 0x2000
	s_nop 0
	global_load_lds_dwordx4 v134, s[42:43]
	s_mov_b32 m0, s9
	s_nop 0
	global_load_lds_dwordx4 v128, s[92:93]
	s_mov_b32 m0, s18
	s_nop 0
	global_load_lds_dwordx4 v132, s[92:93]
	s_waitcnt vmcnt(8)
	s_waitcnt lgkmcnt(0)
	s_barrier
	s_setprio 1
	s_waitcnt lgkmcnt(0)
	v_mfma_f32_16x16x32_bf16 v[60:63], v[154:157], v[186:189], v[60:63]
	v_mfma_f32_16x16x32_bf16 v[56:59], v[162:165], v[186:189], v[56:59]
	v_mfma_f32_16x16x32_bf16 v[44:47], v[154:157], v[194:197], v[44:47]
	v_mfma_f32_16x16x32_bf16 v[40:43], v[162:165], v[194:197], v[40:43]
	v_mfma_f32_16x16x32_bf16 v[28:31], v[154:157], v[202:205], v[28:31]
	v_mfma_f32_16x16x32_bf16 v[24:27], v[162:165], v[202:205], v[24:27]
	v_mfma_f32_16x16x32_bf16 v[12:15], v[154:157], v[210:213], v[12:15]
	v_mfma_f32_16x16x32_bf16 v[8:11], v[162:165], v[210:213], v[8:11]
	v_mfma_f32_16x16x32_bf16 v[60:63], v[158:161], v[190:193], v[60:63]
	v_mfma_f32_16x16x32_bf16 v[56:59], v[166:169], v[190:193], v[56:59]
	v_mfma_f32_16x16x32_bf16 v[44:47], v[158:161], v[198:201], v[44:47]
	v_mfma_f32_16x16x32_bf16 v[40:43], v[166:169], v[198:201], v[40:43]
	v_mfma_f32_16x16x32_bf16 v[28:31], v[158:161], v[206:209], v[28:31]
	v_mfma_f32_16x16x32_bf16 v[24:27], v[166:169], v[206:209], v[24:27]
	v_mfma_f32_16x16x32_bf16 v[12:15], v[158:161], v[214:217], v[12:15]
	v_mfma_f32_16x16x32_bf16 v[8:11], v[166:169], v[214:217], v[8:11]
	v_mfma_f32_16x16x32_bf16 v[52:55], v[170:173], v[186:189], v[52:55]
	v_mfma_f32_16x16x32_bf16 v[48:51], v[178:181], v[186:189], v[48:51]
	v_mfma_f32_16x16x32_bf16 v[36:39], v[170:173], v[194:197], v[36:39]
	v_mfma_f32_16x16x32_bf16 v[32:35], v[178:181], v[194:197], v[32:35]
	v_mfma_f32_16x16x32_bf16 v[20:23], v[170:173], v[202:205], v[20:23]
	v_mfma_f32_16x16x32_bf16 v[16:19], v[178:181], v[202:205], v[16:19]
	v_mfma_f32_16x16x32_bf16 v[4:7], v[170:173], v[210:213], v[4:7]
	v_mfma_f32_16x16x32_bf16 v[0:3], v[178:181], v[210:213], v[0:3]
	v_mfma_f32_16x16x32_bf16 v[52:55], v[174:177], v[190:193], v[52:55]
	v_mfma_f32_16x16x32_bf16 v[48:51], v[182:185], v[190:193], v[48:51]
	v_mfma_f32_16x16x32_bf16 v[36:39], v[174:177], v[198:201], v[36:39]
	v_mfma_f32_16x16x32_bf16 v[32:35], v[182:185], v[198:201], v[32:35]
	v_mfma_f32_16x16x32_bf16 v[20:23], v[174:177], v[206:209], v[20:23]
	v_mfma_f32_16x16x32_bf16 v[16:19], v[182:185], v[206:209], v[16:19]
	v_mfma_f32_16x16x32_bf16 v[4:7], v[174:177], v[214:217], v[4:7]
	v_mfma_f32_16x16x32_bf16 v[0:3], v[182:185], v[214:217], v[0:3]
	s_setprio 0
	s_barrier
	s_add_i32 s3, 0, 0x18000
	v_add_u32_e32 v153, s3, v149
	s_add_i32 s44, 0, 0x1c000
	ds_read_b128 v[154:157], v153
	ds_read_b128 v[158:161], v153 offset:1024
	ds_read_b128 v[162:165], v153 offset:2048
	ds_read_b128 v[166:169], v153 offset:3072
	v_add_u32_e32 v153, s44, v149
	ds_read_b128 v[170:173], v153
	ds_read_b128 v[174:177], v153 offset:1024
	ds_read_b128 v[178:181], v153 offset:2048
	ds_read_b128 v[182:185], v153 offset:3072
	s_add_u32 s42, s92, 0x80000
	s_addc_u32 s43, s93, 0
	s_mov_b32 m0, s19
	ds_read_b128 v[186:189], v152 offset:32768
	ds_read_b128 v[190:193], v152 offset:33792
	ds_read_b128 v[194:197], v152 offset:34816
	ds_read_b128 v[198:201], v152 offset:35840
	ds_read_b128 v[202:205], v152 offset:36864
	ds_read_b128 v[206:209], v152 offset:37888
	ds_read_b128 v[210:213], v152 offset:38912
	ds_read_b128 v[214:217], v152 offset:39936
	global_load_lds_dwordx4 v128, s[42:43]
	v_lshl_add_u64 v[224:225], s[42:43], 0, v[132:133]
	s_mov_b32 m0, s25
	s_nop 0
	global_load_lds_dwordx4 v[224:225], off
	s_waitcnt vmcnt(8)
	s_waitcnt lgkmcnt(0)
	s_barrier
	s_setprio 1
	s_waitcnt lgkmcnt(0)
	v_mfma_f32_16x16x32_bf16 v[124:127], v[154:157], v[186:189], v[124:127]
	v_mfma_f32_16x16x32_bf16 v[120:123], v[162:165], v[186:189], v[120:123]
	v_mfma_f32_16x16x32_bf16 v[108:111], v[154:157], v[194:197], v[108:111]
	v_mfma_f32_16x16x32_bf16 v[104:107], v[162:165], v[194:197], v[104:107]
	v_mfma_f32_16x16x32_bf16 v[92:95], v[154:157], v[202:205], v[92:95]
	v_mfma_f32_16x16x32_bf16 v[88:91], v[162:165], v[202:205], v[88:91]
	v_mfma_f32_16x16x32_bf16 v[76:79], v[154:157], v[210:213], v[76:79]
	v_mfma_f32_16x16x32_bf16 v[72:75], v[162:165], v[210:213], v[72:75]
	v_mfma_f32_16x16x32_bf16 v[124:127], v[158:161], v[190:193], v[124:127]
	v_mfma_f32_16x16x32_bf16 v[120:123], v[166:169], v[190:193], v[120:123]
	v_mfma_f32_16x16x32_bf16 v[108:111], v[158:161], v[198:201], v[108:111]
	v_mfma_f32_16x16x32_bf16 v[104:107], v[166:169], v[198:201], v[104:107]
	v_mfma_f32_16x16x32_bf16 v[92:95], v[158:161], v[206:209], v[92:95]
	v_mfma_f32_16x16x32_bf16 v[88:91], v[166:169], v[206:209], v[88:91]
	v_mfma_f32_16x16x32_bf16 v[76:79], v[158:161], v[214:217], v[76:79]
	v_mfma_f32_16x16x32_bf16 v[72:75], v[166:169], v[214:217], v[72:75]
	v_mfma_f32_16x16x32_bf16 v[116:119], v[170:173], v[186:189], v[116:119]
	v_mfma_f32_16x16x32_bf16 v[112:115], v[178:181], v[186:189], v[112:115]
	v_mfma_f32_16x16x32_bf16 v[100:103], v[170:173], v[194:197], v[100:103]
	v_mfma_f32_16x16x32_bf16 v[96:99], v[178:181], v[194:197], v[96:99]
	v_mfma_f32_16x16x32_bf16 v[84:87], v[170:173], v[202:205], v[84:87]
	v_mfma_f32_16x16x32_bf16 v[80:83], v[178:181], v[202:205], v[80:83]
	v_mfma_f32_16x16x32_bf16 v[68:71], v[170:173], v[210:213], v[68:71]
	v_mfma_f32_16x16x32_bf16 v[64:67], v[178:181], v[210:213], v[64:67]
	v_mfma_f32_16x16x32_bf16 v[116:119], v[174:177], v[190:193], v[116:119]
	v_mfma_f32_16x16x32_bf16 v[112:115], v[182:185], v[190:193], v[112:115]
	v_mfma_f32_16x16x32_bf16 v[100:103], v[174:177], v[198:201], v[100:103]
	v_mfma_f32_16x16x32_bf16 v[96:99], v[182:185], v[198:201], v[96:99]
	v_mfma_f32_16x16x32_bf16 v[84:87], v[174:177], v[206:209], v[84:87]
	v_mfma_f32_16x16x32_bf16 v[80:83], v[182:185], v[206:209], v[80:83]
	v_mfma_f32_16x16x32_bf16 v[68:71], v[174:177], v[214:217], v[68:71]
	v_mfma_f32_16x16x32_bf16 v[64:67], v[182:185], v[214:217], v[64:67]
	s_setprio 0
	s_barrier
	s_add_i32 s3, s3, s8
	s_add_u32 s42, s90, 0x80
	s_addc_u32 s43, s91, 0
	s_mov_b32 m0, s3
	ds_read_b128 v[186:189], v152 offset:49152
	ds_read_b128 v[190:193], v152 offset:50176
	ds_read_b128 v[194:197], v152 offset:51200
	ds_read_b128 v[198:201], v152 offset:52224
	ds_read_b128 v[202:205], v152 offset:53248
	ds_read_b128 v[206:209], v152 offset:54272
	ds_read_b128 v[210:213], v152 offset:55296
	ds_read_b128 v[214:217], v152 offset:56320
	global_load_lds_dwordx4 v130, s[42:43]
	s_add_i32 m0, s3, 0x2000
	s_add_i32 s3, s44, s8
	global_load_lds_dwordx4 v134, s[42:43]
	s_add_u32 s42, s42, 0x80000
	s_addc_u32 s43, s43, 0
	s_mov_b32 m0, s3
	s_nop 0
	global_load_lds_dwordx4 v130, s[42:43]
	s_add_i32 m0, s3, 0x2000
	s_nop 0
	global_load_lds_dwordx4 v134, s[42:43]
	s_add_u32 s92, s92, 0x80
	s_addc_u32 s93, s93, 0
	s_mov_b32 m0, s30
	s_nop 0
	global_load_lds_dwordx4 v128, s[92:93]
	s_mov_b32 m0, s31
	s_nop 0
	global_load_lds_dwordx4 v132, s[92:93]
	s_waitcnt vmcnt(8)
	s_waitcnt lgkmcnt(0)
	s_barrier
	s_setprio 1
	s_waitcnt lgkmcnt(0)
	v_mfma_f32_16x16x32_bf16 v[60:63], v[154:157], v[186:189], v[60:63]
	v_mfma_f32_16x16x32_bf16 v[56:59], v[162:165], v[186:189], v[56:59]
	v_mfma_f32_16x16x32_bf16 v[44:47], v[154:157], v[194:197], v[44:47]
	v_mfma_f32_16x16x32_bf16 v[40:43], v[162:165], v[194:197], v[40:43]
	v_mfma_f32_16x16x32_bf16 v[28:31], v[154:157], v[202:205], v[28:31]
	v_mfma_f32_16x16x32_bf16 v[24:27], v[162:165], v[202:205], v[24:27]
	v_mfma_f32_16x16x32_bf16 v[12:15], v[154:157], v[210:213], v[12:15]
	v_mfma_f32_16x16x32_bf16 v[8:11], v[162:165], v[210:213], v[8:11]
	v_mfma_f32_16x16x32_bf16 v[60:63], v[158:161], v[190:193], v[60:63]
	v_mfma_f32_16x16x32_bf16 v[56:59], v[166:169], v[190:193], v[56:59]
	v_mfma_f32_16x16x32_bf16 v[44:47], v[158:161], v[198:201], v[44:47]
	v_mfma_f32_16x16x32_bf16 v[40:43], v[166:169], v[198:201], v[40:43]
	v_mfma_f32_16x16x32_bf16 v[28:31], v[158:161], v[206:209], v[28:31]
	v_mfma_f32_16x16x32_bf16 v[24:27], v[166:169], v[206:209], v[24:27]
	v_mfma_f32_16x16x32_bf16 v[12:15], v[158:161], v[214:217], v[12:15]
	v_mfma_f32_16x16x32_bf16 v[8:11], v[166:169], v[214:217], v[8:11]
	v_mfma_f32_16x16x32_bf16 v[52:55], v[170:173], v[186:189], v[52:55]
	v_mfma_f32_16x16x32_bf16 v[48:51], v[178:181], v[186:189], v[48:51]
	v_mfma_f32_16x16x32_bf16 v[36:39], v[170:173], v[194:197], v[36:39]
	v_mfma_f32_16x16x32_bf16 v[32:35], v[178:181], v[194:197], v[32:35]
	v_mfma_f32_16x16x32_bf16 v[20:23], v[170:173], v[202:205], v[20:23]
	v_mfma_f32_16x16x32_bf16 v[16:19], v[178:181], v[202:205], v[16:19]
	v_mfma_f32_16x16x32_bf16 v[4:7], v[170:173], v[210:213], v[4:7]
	v_mfma_f32_16x16x32_bf16 v[0:3], v[178:181], v[210:213], v[0:3]
	v_mfma_f32_16x16x32_bf16 v[52:55], v[174:177], v[190:193], v[52:55]
	v_mfma_f32_16x16x32_bf16 v[48:51], v[182:185], v[190:193], v[48:51]
	v_mfma_f32_16x16x32_bf16 v[36:39], v[174:177], v[198:201], v[36:39]
	v_mfma_f32_16x16x32_bf16 v[32:35], v[182:185], v[198:201], v[32:35]
	v_mfma_f32_16x16x32_bf16 v[20:23], v[174:177], v[206:209], v[20:23]
	v_mfma_f32_16x16x32_bf16 v[16:19], v[182:185], v[206:209], v[16:19]
	v_mfma_f32_16x16x32_bf16 v[4:7], v[174:177], v[214:217], v[4:7]
	v_mfma_f32_16x16x32_bf16 v[0:3], v[182:185], v[214:217], v[0:3]
	s_setprio 0
	s_barrier
	s_add_i32 s37, s37, 2
	s_add_u32 s88, s88, 0x100
	s_addc_u32 s89, s89, 0
	s_add_u32 s35, s35, 0x100
	s_addc_u32 s36, s36, 0
	s_cmp_gt_u32 s37, 29
	s_cbranch_scc0 .LBB0_1624
	s_and_b64 vcc, exec, s[16:17]
	s_cbranch_vccz .LBB0_1627
	s_barrier

.LBB0_1700:
	ds_read_b128 v[140:143], v149
	ds_read_b128 v[152:155], v149 offset:1024
	ds_read_b128 v[156:159], v149 offset:2048
	ds_read_b128 v[160:163], v149 offset:3072
	ds_read_b128 v[164:167], v150
	ds_read_b128 v[168:171], v150 offset:1024
	ds_read_b128 v[172:175], v150 offset:2048
	ds_read_b128 v[176:179], v150 offset:3072
	s_add_u32 s3, s86, 0xffe00080
	s_addc_u32 s37, s87, -1
	s_cmpk_eq_i32 s36, 0x7c
	s_cselect_b32 s91, s0, s37
	s_cselect_b32 s90, s1, s3
	s_cselect_b32 s89, s17, s35
	s_cselect_b32 s88, s27, s33
	s_add_i32 m0, s18, 0xc000
	ds_read_b128 v[180:183], v151
	ds_read_b128 v[184:187], v151 offset:1024
	ds_read_b128 v[188:191], v151 offset:2048
	ds_read_b128 v[192:195], v151 offset:3072
	ds_read_b128 v[196:199], v151 offset:4096
	ds_read_b128 v[200:203], v151 offset:5120
	ds_read_b128 v[204:207], v151 offset:6144
	ds_read_b128 v[208:211], v151 offset:7168
	global_load_lds_dwordx4 v132, s[86:87]
	s_add_i32 m0, s18, 0xe000
	s_nop 0
	global_load_lds_dwordx4 v134, s[86:87]
	s_waitcnt vmcnt(8)
	s_waitcnt lgkmcnt(0)
	s_barrier
	s_setprio 1
	s_waitcnt lgkmcnt(0)
	v_mfma_f32_16x16x32_bf16 v[124:127], v[140:143], v[180:183], v[124:127]
	v_mfma_f32_16x16x32_bf16 v[120:123], v[156:159], v[180:183], v[120:123]
	v_mfma_f32_16x16x32_bf16 v[112:115], v[140:143], v[188:191], v[112:115]
	v_mfma_f32_16x16x32_bf16 v[104:107], v[156:159], v[188:191], v[104:107]
	v_mfma_f32_16x16x32_bf16 v[96:99], v[140:143], v[196:199], v[96:99]
	v_mfma_f32_16x16x32_bf16 v[88:91], v[156:159], v[196:199], v[88:91]
	v_mfma_f32_16x16x32_bf16 v[80:83], v[140:143], v[204:207], v[80:83]
	v_mfma_f32_16x16x32_bf16 v[72:75], v[156:159], v[204:207], v[72:75]
	v_mfma_f32_16x16x32_bf16 v[124:127], v[152:155], v[184:187], v[124:127]
	v_mfma_f32_16x16x32_bf16 v[120:123], v[160:163], v[184:187], v[120:123]
	v_mfma_f32_16x16x32_bf16 v[112:115], v[152:155], v[192:195], v[112:115]
	v_mfma_f32_16x16x32_bf16 v[104:107], v[160:163], v[192:195], v[104:107]
	v_mfma_f32_16x16x32_bf16 v[96:99], v[152:155], v[200:203], v[96:99]
	v_mfma_f32_16x16x32_bf16 v[88:91], v[160:163], v[200:203], v[88:91]
	v_mfma_f32_16x16x32_bf16 v[80:83], v[152:155], v[208:211], v[80:83]
	v_mfma_f32_16x16x32_bf16 v[72:75], v[160:163], v[208:211], v[72:75]
	v_mfma_f32_16x16x32_bf16 v[116:119], v[164:167], v[180:183], v[116:119]
	v_mfma_f32_16x16x32_bf16 v[108:111], v[172:175], v[180:183], v[108:111]
	v_mfma_f32_16x16x32_bf16 v[100:103], v[164:167], v[188:191], v[100:103]
	v_mfma_f32_16x16x32_bf16 v[92:95], v[172:175], v[188:191], v[92:95]
	v_mfma_f32_16x16x32_bf16 v[84:87], v[164:167], v[196:199], v[84:87]
	v_mfma_f32_16x16x32_bf16 v[76:79], v[172:175], v[196:199], v[76:79]
	v_mfma_f32_16x16x32_bf16 v[68:71], v[164:167], v[204:207], v[68:71]
	v_mfma_f32_16x16x32_bf16 v[64:67], v[172:175], v[204:207], v[64:67]
	v_mfma_f32_16x16x32_bf16 v[116:119], v[168:171], v[184:187], v[116:119]
	v_mfma_f32_16x16x32_bf16 v[108:111], v[176:179], v[184:187], v[108:111]
	v_mfma_f32_16x16x32_bf16 v[100:103], v[168:171], v[192:195], v[100:103]
	v_mfma_f32_16x16x32_bf16 v[92:95], v[176:179], v[192:195], v[92:95]
	v_mfma_f32_16x16x32_bf16 v[84:87], v[168:171], v[200:203], v[84:87]
	v_mfma_f32_16x16x32_bf16 v[76:79], v[176:179], v[200:203], v[76:79]
	v_mfma_f32_16x16x32_bf16 v[68:71], v[168:171], v[208:211], v[68:71]
	v_mfma_f32_16x16x32_bf16 v[64:67], v[176:179], v[208:211], v[64:67]
	s_setprio 0
	s_barrier
	s_add_i32 s3, s49, s9
	s_mov_b32 m0, s3
	ds_read_b128 v[180:183], v151 offset:16384
	ds_read_b128 v[184:187], v151 offset:17408
	ds_read_b128 v[188:191], v151 offset:18432
	ds_read_b128 v[192:195], v151 offset:19456
	ds_read_b128 v[196:199], v151 offset:20480
	ds_read_b128 v[200:203], v151 offset:21504
	ds_read_b128 v[204:207], v151 offset:22528
	ds_read_b128 v[208:211], v151 offset:23552
	global_load_lds_dwordx4 v128, s[88:89]
	s_add_i32 m0, s3, 0x2000
	s_add_u32 s42, s88, 0x200000
	s_addc_u32 s43, s89, 0
	s_add_i32 s3, s52, s9
	global_load_lds_dwordx4 v130, s[88:89]
	s_mov_b32 m0, s3
	s_nop 0
	global_load_lds_dwordx4 v128, s[42:43]
	s_add_i32 m0, s3, 0x2000
	s_nop 0
	global_load_lds_dwordx4 v130, s[42:43]
	s_mov_b32 m0, s18
	s_nop 0
	global_load_lds_dwordx4 v128, s[90:91]
	s_mov_b32 m0, s19
	s_nop 0
	global_load_lds_dwordx4 v130, s[90:91]
	s_waitcnt vmcnt(8)
	s_waitcnt lgkmcnt(0)
	s_barrier
	s_setprio 1
	s_waitcnt lgkmcnt(0)
	v_mfma_f32_16x16x32_bf16 v[60:63], v[140:143], v[180:183], v[60:63]
	v_mfma_f32_16x16x32_bf16 v[56:59], v[156:159], v[180:183], v[56:59]
	v_mfma_f32_16x16x32_bf16 v[48:51], v[140:143], v[188:191], v[48:51]
	v_mfma_f32_16x16x32_bf16 v[40:43], v[156:159], v[188:191], v[40:43]
	v_mfma_f32_16x16x32_bf16 v[32:35], v[140:143], v[196:199], v[32:35]
	v_mfma_f32_16x16x32_bf16 v[24:27], v[156:159], v[196:199], v[24:27]
	v_mfma_f32_16x16x32_bf16 v[16:19], v[140:143], v[204:207], v[16:19]
	v_mfma_f32_16x16x32_bf16 v[8:11], v[156:159], v[204:207], v[8:11]
	v_mfma_f32_16x16x32_bf16 v[60:63], v[152:155], v[184:187], v[60:63]
	v_mfma_f32_16x16x32_bf16 v[56:59], v[160:163], v[184:187], v[56:59]
	v_mfma_f32_16x16x32_bf16 v[48:51], v[152:155], v[192:195], v[48:51]
	v_mfma_f32_16x16x32_bf16 v[40:43], v[160:163], v[192:195], v[40:43]
	v_mfma_f32_16x16x32_bf16 v[32:35], v[152:155], v[200:203], v[32:35]
	v_mfma_f32_16x16x32_bf16 v[24:27], v[160:163], v[200:203], v[24:27]
	v_mfma_f32_16x16x32_bf16 v[16:19], v[152:155], v[208:211], v[16:19]
	v_mfma_f32_16x16x32_bf16 v[8:11], v[160:163], v[208:211], v[8:11]
	v_mfma_f32_16x16x32_bf16 v[52:55], v[164:167], v[180:183], v[52:55]
	v_mfma_f32_16x16x32_bf16 v[44:47], v[172:175], v[180:183], v[44:47]
	v_mfma_f32_16x16x32_bf16 v[36:39], v[164:167], v[188:191], v[36:39]
	v_mfma_f32_16x16x32_bf16 v[28:31], v[172:175], v[188:191], v[28:31]
	v_mfma_f32_16x16x32_bf16 v[20:23], v[164:167], v[196:199], v[20:23]
	v_mfma_f32_16x16x32_bf16 v[12:15], v[172:175], v[196:199], v[12:15]
	v_mfma_f32_16x16x32_bf16 v[4:7], v[164:167], v[204:207], v[4:7]
	v_mfma_f32_16x16x32_bf16 v[0:3], v[172:175], v[204:207], v[0:3]
	v_mfma_f32_16x16x32_bf16 v[52:55], v[168:171], v[184:187], v[52:55]
	v_mfma_f32_16x16x32_bf16 v[44:47], v[176:179], v[184:187], v[44:47]
	v_mfma_f32_16x16x32_bf16 v[36:39], v[168:171], v[192:195], v[36:39]
	v_mfma_f32_16x16x32_bf16 v[28:31], v[176:179], v[192:195], v[28:31]
	v_mfma_f32_16x16x32_bf16 v[20:23], v[168:171], v[200:203], v[20:23]
	v_mfma_f32_16x16x32_bf16 v[12:15], v[176:179], v[200:203], v[12:15]
	v_mfma_f32_16x16x32_bf16 v[4:7], v[168:171], v[208:211], v[4:7]
	v_mfma_f32_16x16x32_bf16 v[0:3], v[176:179], v[208:211], v[0:3]
	s_setprio 0
	s_barrier
	s_add_i32 s3, 0, 0x18000
	s_add_i32 s37, 0, 0x1c000
	v_add_u32_e32 v160, s3, v147
	v_add_u32_e32 v176, s37, v147
	ds_read_b128 v[140:143], v160
	ds_read_b128 v[152:155], v160 offset:1024
	ds_read_b128 v[156:159], v160 offset:2048
	ds_read_b128 v[160:163], v160 offset:3072
	ds_read_b128 v[164:167], v176
	ds_read_b128 v[168:171], v176 offset:1024
	ds_read_b128 v[172:175], v176 offset:2048
	ds_read_b128 v[176:179], v176 offset:3072
	s_add_u32 s42, s90, 0x200000
	s_addc_u32 s43, s91, 0
	s_mov_b32 m0, s25
	ds_read_b128 v[180:183], v151 offset:32768
	ds_read_b128 v[184:187], v151 offset:33792
	ds_read_b128 v[188:191], v151 offset:34816
	ds_read_b128 v[192:195], v151 offset:35840
	ds_read_b128 v[196:199], v151 offset:36864
	ds_read_b128 v[200:203], v151 offset:37888
	ds_read_b128 v[204:207], v151 offset:38912
	ds_read_b128 v[208:211], v151 offset:39936
	global_load_lds_dwordx4 v128, s[42:43]
	v_lshl_add_u64 v[218:219], s[42:43], 0, v[130:131]
	s_mov_b32 m0, s30
	s_nop 0
	global_load_lds_dwordx4 v[218:219], off
	s_waitcnt vmcnt(8)
	s_waitcnt lgkmcnt(0)
	s_barrier
	s_setprio 1
	s_waitcnt lgkmcnt(0)
	v_mfma_f32_16x16x32_bf16 v[124:127], v[140:143], v[180:183], v[124:127]
	v_mfma_f32_16x16x32_bf16 v[120:123], v[156:159], v[180:183], v[120:123]
	v_mfma_f32_16x16x32_bf16 v[112:115], v[140:143], v[188:191], v[112:115]
	v_mfma_f32_16x16x32_bf16 v[104:107], v[156:159], v[188:191], v[104:107]
	v_mfma_f32_16x16x32_bf16 v[96:99], v[140:143], v[196:199], v[96:99]
	v_mfma_f32_16x16x32_bf16 v[88:91], v[156:159], v[196:199], v[88:91]
	v_mfma_f32_16x16x32_bf16 v[80:83], v[140:143], v[204:207], v[80:83]
	v_mfma_f32_16x16x32_bf16 v[72:75], v[156:159], v[204:207], v[72:75]
	v_mfma_f32_16x16x32_bf16 v[124:127], v[152:155], v[184:187], v[124:127]
	v_mfma_f32_16x16x32_bf16 v[120:123], v[160:163], v[184:187], v[120:123]
	v_mfma_f32_16x16x32_bf16 v[112:115], v[152:155], v[192:195], v[112:115]
	v_mfma_f32_16x16x32_bf16 v[104:107], v[160:163], v[192:195], v[104:107]
	v_mfma_f32_16x16x32_bf16 v[96:99], v[152:155], v[200:203], v[96:99]
	v_mfma_f32_16x16x32_bf16 v[88:91], v[160:163], v[200:203], v[88:91]
	v_mfma_f32_16x16x32_bf16 v[80:83], v[152:155], v[208:211], v[80:83]
	v_mfma_f32_16x16x32_bf16 v[72:75], v[160:163], v[208:211], v[72:75]
	v_mfma_f32_16x16x32_bf16 v[116:119], v[164:167], v[180:183], v[116:119]
	v_mfma_f32_16x16x32_bf16 v[108:111], v[172:175], v[180:183], v[108:111]
	v_mfma_f32_16x16x32_bf16 v[100:103], v[164:167], v[188:191], v[100:103]
	v_mfma_f32_16x16x32_bf16 v[92:95], v[172:175], v[188:191], v[92:95]
	v_mfma_f32_16x16x32_bf16 v[84:87], v[164:167], v[196:199], v[84:87]
	v_mfma_f32_16x16x32_bf16 v[76:79], v[172:175], v[196:199], v[76:79]
	v_mfma_f32_16x16x32_bf16 v[68:71], v[164:167], v[204:207], v[68:71]
	v_mfma_f32_16x16x32_bf16 v[64:67], v[172:175], v[204:207], v[64:67]
	v_mfma_f32_16x16x32_bf16 v[116:119], v[168:171], v[184:187], v[116:119]
	v_mfma_f32_16x16x32_bf16 v[108:111], v[176:179], v[184:187], v[108:111]
	v_mfma_f32_16x16x32_bf16 v[100:103], v[168:171], v[192:195], v[100:103]
	v_mfma_f32_16x16x32_bf16 v[92:95], v[176:179], v[192:195], v[92:95]
	v_mfma_f32_16x16x32_bf16 v[84:87], v[168:171], v[200:203], v[84:87]
	v_mfma_f32_16x16x32_bf16 v[76:79], v[176:179], v[200:203], v[76:79]
	v_mfma_f32_16x16x32_bf16 v[68:71], v[168:171], v[208:211], v[68:71]
	v_mfma_f32_16x16x32_bf16 v[64:67], v[176:179], v[208:211], v[64:67]
	s_setprio 0
	s_barrier
	s_add_i32 s3, s3, s9
	s_add_u32 s42, s88, 0x80
	s_addc_u32 s43, s89, 0
	s_mov_b32 m0, s3
	ds_read_b128 v[180:183], v151 offset:49152
	ds_read_b128 v[184:187], v151 offset:50176
	ds_read_b128 v[188:191], v151 offset:51200
	ds_read_b128 v[192:195], v151 offset:52224
	ds_read_b128 v[196:199], v151 offset:53248
	ds_read_b128 v[200:203], v151 offset:54272
	ds_read_b128 v[204:207], v151 offset:55296
	ds_read_b128 v[208:211], v151 offset:56320
	global_load_lds_dwordx4 v128, s[42:43]
	s_add_i32 m0, s3, 0x2000
	s_add_i32 s3, s37, s9
	global_load_lds_dwordx4 v130, s[42:43]
	s_add_u32 s42, s42, 0x200000
	s_addc_u32 s43, s43, 0
	s_mov_b32 m0, s3
	s_nop 0
	global_load_lds_dwordx4 v128, s[42:43]
	s_add_i32 m0, s3, 0x2000
	s_nop 0
	global_load_lds_dwordx4 v130, s[42:43]
	s_add_u32 s90, s90, 0x80
	s_addc_u32 s91, s91, 0
	s_mov_b32 m0, s8
	s_nop 0
	global_load_lds_dwordx4 v128, s[90:91]
	s_mov_b32 m0, s48
	s_nop 0
	global_load_lds_dwordx4 v130, s[90:91]
	s_waitcnt vmcnt(8)
	s_waitcnt lgkmcnt(0)
	s_barrier
	s_setprio 1
	s_waitcnt lgkmcnt(0)
	v_mfma_f32_16x16x32_bf16 v[60:63], v[140:143], v[180:183], v[60:63]
	v_mfma_f32_16x16x32_bf16 v[56:59], v[156:159], v[180:183], v[56:59]
	v_mfma_f32_16x16x32_bf16 v[48:51], v[140:143], v[188:191], v[48:51]
	v_mfma_f32_16x16x32_bf16 v[40:43], v[156:159], v[188:191], v[40:43]
	v_mfma_f32_16x16x32_bf16 v[32:35], v[140:143], v[196:199], v[32:35]
	v_mfma_f32_16x16x32_bf16 v[24:27], v[156:159], v[196:199], v[24:27]
	v_mfma_f32_16x16x32_bf16 v[16:19], v[140:143], v[204:207], v[16:19]
	v_mfma_f32_16x16x32_bf16 v[8:11], v[156:159], v[204:207], v[8:11]
	v_mfma_f32_16x16x32_bf16 v[60:63], v[152:155], v[184:187], v[60:63]
	v_mfma_f32_16x16x32_bf16 v[56:59], v[160:163], v[184:187], v[56:59]
	v_mfma_f32_16x16x32_bf16 v[48:51], v[152:155], v[192:195], v[48:51]
	v_mfma_f32_16x16x32_bf16 v[40:43], v[160:163], v[192:195], v[40:43]
	v_mfma_f32_16x16x32_bf16 v[32:35], v[152:155], v[200:203], v[32:35]
	v_mfma_f32_16x16x32_bf16 v[24:27], v[160:163], v[200:203], v[24:27]
	v_mfma_f32_16x16x32_bf16 v[16:19], v[152:155], v[208:211], v[16:19]
	v_mfma_f32_16x16x32_bf16 v[8:11], v[160:163], v[208:211], v[8:11]
	v_mfma_f32_16x16x32_bf16 v[52:55], v[164:167], v[180:183], v[52:55]
	v_mfma_f32_16x16x32_bf16 v[44:47], v[172:175], v[180:183], v[44:47]
	v_mfma_f32_16x16x32_bf16 v[36:39], v[164:167], v[188:191], v[36:39]
	v_mfma_f32_16x16x32_bf16 v[28:31], v[172:175], v[188:191], v[28:31]
	v_mfma_f32_16x16x32_bf16 v[20:23], v[164:167], v[196:199], v[20:23]
	v_mfma_f32_16x16x32_bf16 v[12:15], v[172:175], v[196:199], v[12:15]
	v_mfma_f32_16x16x32_bf16 v[4:7], v[164:167], v[204:207], v[4:7]
	v_mfma_f32_16x16x32_bf16 v[0:3], v[172:175], v[204:207], v[0:3]
	v_mfma_f32_16x16x32_bf16 v[52:55], v[168:171], v[184:187], v[52:55]
	v_mfma_f32_16x16x32_bf16 v[44:47], v[176:179], v[184:187], v[44:47]
	v_mfma_f32_16x16x32_bf16 v[36:39], v[168:171], v[192:195], v[36:39]
	v_mfma_f32_16x16x32_bf16 v[28:31], v[176:179], v[192:195], v[28:31]
	v_mfma_f32_16x16x32_bf16 v[20:23], v[168:171], v[200:203], v[20:23]
	v_mfma_f32_16x16x32_bf16 v[12:15], v[176:179], v[200:203], v[12:15]
	v_mfma_f32_16x16x32_bf16 v[4:7], v[168:171], v[208:211], v[4:7]
	v_mfma_f32_16x16x32_bf16 v[0:3], v[176:179], v[208:211], v[0:3]
	s_setprio 0
	s_barrier
	s_add_i32 s36, s36, 2
	s_add_u32 s86, s86, 0x100
	s_addc_u32 s87, s87, 0
	s_add_u32 s33, s33, 0x100
	s_addc_u32 s35, s35, 0
	s_cmpk_gt_u32 s36, 0x7d
	s_cbranch_scc0 .LBB0_1700
	s_and_b64 vcc, exec, s[14:15]
	s_cbranch_vccz .LBB0_1703
	s_barrier

.LBB0_1773:
	ds_read_b128 v[128:131], v173
	ds_read_b128 v[132:135], v173 offset:1024
	ds_read_b128 v[158:161], v173 offset:2048
	ds_read_b128 v[178:181], v173 offset:3072
	ds_read_b128 v[182:185], v174
	ds_read_b128 v[186:189], v174 offset:1024
	ds_read_b128 v[190:193], v174 offset:2048
	ds_read_b128 v[194:197], v174 offset:3072
	s_add_u32 s3, s34, 0xfff80080
	s_addc_u32 s19, s35, -1
	s_cmp_eq_u32 s18, 28
	s_cselect_b32 vcc_hi, s0, s19
	s_cselect_b32 vcc_lo, s1, s3
	s_cselect_b32 s97, s8, s17
	s_cselect_b32 s96, s9, s15
	s_add_i32 m0, s48, 0xc000
	ds_read_b128 v[198:201], v175
	ds_read_b128 v[202:205], v175 offset:1024
	ds_read_b128 v[206:209], v175 offset:2048
	ds_read_b128 v[210:213], v175 offset:3072
	ds_read_b128 v[214:217], v175 offset:4096
	ds_read_b128 v[218:221], v175 offset:5120
	ds_read_b128 v[222:225], v175 offset:6144
	ds_read_b128 v[230:233], v175 offset:7168
	global_load_lds_dwordx4 v148, s[34:35]
	s_add_i32 m0, s48, 0xe000
	s_nop 0
	global_load_lds_dwordx4 v150, s[34:35]
	s_waitcnt vmcnt(8)
	s_waitcnt lgkmcnt(0)
	s_barrier
	s_setprio 1
	s_waitcnt lgkmcnt(0)
	v_mfma_f32_16x16x32_bf16 v[124:127], v[128:131], v[198:201], v[124:127]
	v_mfma_f32_16x16x32_bf16 v[120:123], v[158:161], v[198:201], v[120:123]
	v_mfma_f32_16x16x32_bf16 v[108:111], v[128:131], v[206:209], v[108:111]
	v_mfma_f32_16x16x32_bf16 v[104:107], v[158:161], v[206:209], v[104:107]
	v_mfma_f32_16x16x32_bf16 v[92:95], v[128:131], v[214:217], v[92:95]
	v_mfma_f32_16x16x32_bf16 v[88:91], v[158:161], v[214:217], v[88:91]
	v_mfma_f32_16x16x32_bf16 v[76:79], v[128:131], v[222:225], v[76:79]
	v_mfma_f32_16x16x32_bf16 v[72:75], v[158:161], v[222:225], v[72:75]
	v_mfma_f32_16x16x32_bf16 v[124:127], v[132:135], v[202:205], v[124:127]
	v_mfma_f32_16x16x32_bf16 v[120:123], v[178:181], v[202:205], v[120:123]
	v_mfma_f32_16x16x32_bf16 v[108:111], v[132:135], v[210:213], v[108:111]
	v_mfma_f32_16x16x32_bf16 v[104:107], v[178:181], v[210:213], v[104:107]
	v_mfma_f32_16x16x32_bf16 v[92:95], v[132:135], v[218:221], v[92:95]
	v_mfma_f32_16x16x32_bf16 v[88:91], v[178:181], v[218:221], v[88:91]
	v_mfma_f32_16x16x32_bf16 v[76:79], v[132:135], v[230:233], v[76:79]
	v_mfma_f32_16x16x32_bf16 v[72:75], v[178:181], v[230:233], v[72:75]
	v_mfma_f32_16x16x32_bf16 v[116:119], v[182:185], v[198:201], v[116:119]
	v_mfma_f32_16x16x32_bf16 v[112:115], v[190:193], v[198:201], v[112:115]
	v_mfma_f32_16x16x32_bf16 v[100:103], v[182:185], v[206:209], v[100:103]
	v_mfma_f32_16x16x32_bf16 v[96:99], v[190:193], v[206:209], v[96:99]
	v_mfma_f32_16x16x32_bf16 v[84:87], v[182:185], v[214:217], v[84:87]
	v_mfma_f32_16x16x32_bf16 v[80:83], v[190:193], v[214:217], v[80:83]
	v_mfma_f32_16x16x32_bf16 v[68:71], v[182:185], v[222:225], v[68:71]
	v_mfma_f32_16x16x32_bf16 v[64:67], v[190:193], v[222:225], v[64:67]
	v_mfma_f32_16x16x32_bf16 v[116:119], v[186:189], v[202:205], v[116:119]
	v_mfma_f32_16x16x32_bf16 v[112:115], v[194:197], v[202:205], v[112:115]
	v_mfma_f32_16x16x32_bf16 v[100:103], v[186:189], v[210:213], v[100:103]
	v_mfma_f32_16x16x32_bf16 v[96:99], v[194:197], v[210:213], v[96:99]
	v_mfma_f32_16x16x32_bf16 v[84:87], v[186:189], v[218:221], v[84:87]
	v_mfma_f32_16x16x32_bf16 v[80:83], v[194:197], v[218:221], v[80:83]
	v_mfma_f32_16x16x32_bf16 v[68:71], v[186:189], v[230:233], v[68:71]
	v_mfma_f32_16x16x32_bf16 v[64:67], v[194:197], v[230:233], v[64:67]
	s_setprio 0
	s_barrier
	s_add_i32 s3, s76, s25
	s_mov_b32 m0, s3
	ds_read_b128 v[198:201], v175 offset:16384
	ds_read_b128 v[202:205], v175 offset:17408
	ds_read_b128 v[206:209], v175 offset:18432
	ds_read_b128 v[210:213], v175 offset:19456
	ds_read_b128 v[214:217], v175 offset:20480
	ds_read_b128 v[218:221], v175 offset:21504
	ds_read_b128 v[222:225], v175 offset:22528
	ds_read_b128 v[230:233], v175 offset:23552
	global_load_lds_dwordx4 v138, s[96:97]
	s_add_i32 m0, s3, 0x2000
	s_add_u32 s36, s96, 0x80000
	s_addc_u32 s37, s97, 0
	s_add_i32 s3, s77, s25
	global_load_lds_dwordx4 v142, s[96:97]
	s_mov_b32 m0, s3
	s_nop 0
	global_load_lds_dwordx4 v138, s[36:37]
	s_add_i32 m0, s3, 0x2000
	s_nop 0
	global_load_lds_dwordx4 v142, s[36:37]
	s_mov_b32 m0, s48
	s_nop 0
	global_load_lds_dwordx4 v136, vcc
	s_mov_b32 m0, s49
	s_nop 0
	global_load_lds_dwordx4 v140, vcc
	s_waitcnt vmcnt(8)
	s_waitcnt lgkmcnt(0)
	s_barrier
	s_setprio 1
	s_waitcnt lgkmcnt(0)
	v_mfma_f32_16x16x32_bf16 v[60:63], v[128:131], v[198:201], v[60:63]
	v_mfma_f32_16x16x32_bf16 v[56:59], v[158:161], v[198:201], v[56:59]
	v_mfma_f32_16x16x32_bf16 v[44:47], v[128:131], v[206:209], v[44:47]
	v_mfma_f32_16x16x32_bf16 v[40:43], v[158:161], v[206:209], v[40:43]
	v_mfma_f32_16x16x32_bf16 v[28:31], v[128:131], v[214:217], v[28:31]
	v_mfma_f32_16x16x32_bf16 v[24:27], v[158:161], v[214:217], v[24:27]
	v_mfma_f32_16x16x32_bf16 v[12:15], v[128:131], v[222:225], v[12:15]
	v_mfma_f32_16x16x32_bf16 v[8:11], v[158:161], v[222:225], v[8:11]
	v_mfma_f32_16x16x32_bf16 v[60:63], v[132:135], v[202:205], v[60:63]
	v_mfma_f32_16x16x32_bf16 v[56:59], v[178:181], v[202:205], v[56:59]
	v_mfma_f32_16x16x32_bf16 v[44:47], v[132:135], v[210:213], v[44:47]
	v_mfma_f32_16x16x32_bf16 v[40:43], v[178:181], v[210:213], v[40:43]
	v_mfma_f32_16x16x32_bf16 v[28:31], v[132:135], v[218:221], v[28:31]
	v_mfma_f32_16x16x32_bf16 v[24:27], v[178:181], v[218:221], v[24:27]
	v_mfma_f32_16x16x32_bf16 v[12:15], v[132:135], v[230:233], v[12:15]
	v_mfma_f32_16x16x32_bf16 v[8:11], v[178:181], v[230:233], v[8:11]
	v_mfma_f32_16x16x32_bf16 v[52:55], v[182:185], v[198:201], v[52:55]
	v_mfma_f32_16x16x32_bf16 v[48:51], v[190:193], v[198:201], v[48:51]
	v_mfma_f32_16x16x32_bf16 v[36:39], v[182:185], v[206:209], v[36:39]
	v_mfma_f32_16x16x32_bf16 v[32:35], v[190:193], v[206:209], v[32:35]
	v_mfma_f32_16x16x32_bf16 v[20:23], v[182:185], v[214:217], v[20:23]
	v_mfma_f32_16x16x32_bf16 v[16:19], v[190:193], v[214:217], v[16:19]
	v_mfma_f32_16x16x32_bf16 v[4:7], v[182:185], v[222:225], v[4:7]
	v_mfma_f32_16x16x32_bf16 v[0:3], v[190:193], v[222:225], v[0:3]
	v_mfma_f32_16x16x32_bf16 v[52:55], v[186:189], v[202:205], v[52:55]
	v_mfma_f32_16x16x32_bf16 v[48:51], v[194:197], v[202:205], v[48:51]
	v_mfma_f32_16x16x32_bf16 v[36:39], v[186:189], v[210:213], v[36:39]
	v_mfma_f32_16x16x32_bf16 v[32:35], v[194:197], v[210:213], v[32:35]
	v_mfma_f32_16x16x32_bf16 v[20:23], v[186:189], v[218:221], v[20:23]
	v_mfma_f32_16x16x32_bf16 v[16:19], v[194:197], v[218:221], v[16:19]
	v_mfma_f32_16x16x32_bf16 v[4:7], v[186:189], v[230:233], v[4:7]
	v_mfma_f32_16x16x32_bf16 v[0:3], v[194:197], v[230:233], v[0:3]
	s_setprio 0
	s_barrier
	s_add_i32 s3, 0, 0x18000
	v_add_u32_e32 v144, s3, v165
	s_add_i32 s19, 0, 0x1c000
	ds_read_b128 v[128:131], v144
	ds_read_b128 v[132:135], v144 offset:1024
	ds_read_b128 v[158:161], v144 offset:2048
	ds_read_b128 v[178:181], v144 offset:3072
	v_add_u32_e32 v144, s19, v165
	ds_read_b128 v[182:185], v144
	ds_read_b128 v[186:189], v144 offset:1024
	ds_read_b128 v[190:193], v144 offset:2048
	ds_read_b128 v[194:197], v144 offset:3072
	s_add_u32 s36, vcc_lo, 0x80000
	s_addc_u32 s37, vcc_hi, 0
	s_mov_b32 m0, s52
	ds_read_b128 v[198:201], v175 offset:32768
	ds_read_b128 v[202:205], v175 offset:33792
	ds_read_b128 v[206:209], v175 offset:34816
	ds_read_b128 v[210:213], v175 offset:35840
	ds_read_b128 v[214:217], v175 offset:36864
	ds_read_b128 v[218:221], v175 offset:37888
	ds_read_b128 v[222:225], v175 offset:38912
	ds_read_b128 v[230:233], v175 offset:39936
	global_load_lds_dwordx4 v136, s[36:37]
	s_mov_b32 m0, s53
	s_nop 0
	global_load_lds_dwordx4 v140, s[36:37]
	s_waitcnt vmcnt(8)
	s_waitcnt lgkmcnt(0)
	s_barrier
	s_setprio 1
	s_waitcnt lgkmcnt(0)
	v_mfma_f32_16x16x32_bf16 v[124:127], v[128:131], v[198:201], v[124:127]
	v_mfma_f32_16x16x32_bf16 v[120:123], v[158:161], v[198:201], v[120:123]
	v_mfma_f32_16x16x32_bf16 v[108:111], v[128:131], v[206:209], v[108:111]
	v_mfma_f32_16x16x32_bf16 v[104:107], v[158:161], v[206:209], v[104:107]
	v_mfma_f32_16x16x32_bf16 v[92:95], v[128:131], v[214:217], v[92:95]
	v_mfma_f32_16x16x32_bf16 v[88:91], v[158:161], v[214:217], v[88:91]
	v_mfma_f32_16x16x32_bf16 v[76:79], v[128:131], v[222:225], v[76:79]
	v_mfma_f32_16x16x32_bf16 v[72:75], v[158:161], v[222:225], v[72:75]
	v_mfma_f32_16x16x32_bf16 v[124:127], v[132:135], v[202:205], v[124:127]
	v_mfma_f32_16x16x32_bf16 v[120:123], v[178:181], v[202:205], v[120:123]
	v_mfma_f32_16x16x32_bf16 v[108:111], v[132:135], v[210:213], v[108:111]
	v_mfma_f32_16x16x32_bf16 v[104:107], v[178:181], v[210:213], v[104:107]
	v_mfma_f32_16x16x32_bf16 v[92:95], v[132:135], v[218:221], v[92:95]
	v_mfma_f32_16x16x32_bf16 v[88:91], v[178:181], v[218:221], v[88:91]
	v_mfma_f32_16x16x32_bf16 v[76:79], v[132:135], v[230:233], v[76:79]
	v_mfma_f32_16x16x32_bf16 v[72:75], v[178:181], v[230:233], v[72:75]
	v_mfma_f32_16x16x32_bf16 v[116:119], v[182:185], v[198:201], v[116:119]
	v_mfma_f32_16x16x32_bf16 v[112:115], v[190:193], v[198:201], v[112:115]
	v_mfma_f32_16x16x32_bf16 v[100:103], v[182:185], v[206:209], v[100:103]
	v_mfma_f32_16x16x32_bf16 v[96:99], v[190:193], v[206:209], v[96:99]
	v_mfma_f32_16x16x32_bf16 v[84:87], v[182:185], v[214:217], v[84:87]
	v_mfma_f32_16x16x32_bf16 v[80:83], v[190:193], v[214:217], v[80:83]
	v_mfma_f32_16x16x32_bf16 v[68:71], v[182:185], v[222:225], v[68:71]
	v_mfma_f32_16x16x32_bf16 v[64:67], v[190:193], v[222:225], v[64:67]
	v_mfma_f32_16x16x32_bf16 v[116:119], v[186:189], v[202:205], v[116:119]
	v_mfma_f32_16x16x32_bf16 v[112:115], v[194:197], v[202:205], v[112:115]
	v_mfma_f32_16x16x32_bf16 v[100:103], v[186:189], v[210:213], v[100:103]
	v_mfma_f32_16x16x32_bf16 v[96:99], v[194:197], v[210:213], v[96:99]
	v_mfma_f32_16x16x32_bf16 v[84:87], v[186:189], v[218:221], v[84:87]
	v_mfma_f32_16x16x32_bf16 v[80:83], v[194:197], v[218:221], v[80:83]
	v_mfma_f32_16x16x32_bf16 v[68:71], v[186:189], v[230:233], v[68:71]
	v_mfma_f32_16x16x32_bf16 v[64:67], v[194:197], v[230:233], v[64:67]
	s_setprio 0
	s_barrier
	s_add_i32 s3, s3, s25
	s_add_u32 s36, s96, 0x80
	s_addc_u32 s37, s97, 0
	s_mov_b32 m0, s3
	ds_read_b128 v[198:201], v175 offset:49152
	ds_read_b128 v[202:205], v175 offset:50176
	ds_read_b128 v[206:209], v175 offset:51200
	ds_read_b128 v[210:213], v175 offset:52224
	ds_read_b128 v[214:217], v175 offset:53248
	ds_read_b128 v[218:221], v175 offset:54272
	ds_read_b128 v[222:225], v175 offset:55296
	ds_read_b128 v[230:233], v175 offset:56320
	global_load_lds_dwordx4 v138, s[36:37]
	s_add_i32 m0, s3, 0x2000
	s_add_i32 s3, s19, s25
	global_load_lds_dwordx4 v142, s[36:37]
	s_add_u32 s36, s36, 0x80000
	s_addc_u32 s37, s37, 0
	s_mov_b32 m0, s3
	s_nop 0
	global_load_lds_dwordx4 v138, s[36:37]
	s_add_i32 m0, s3, 0x2000
	s_nop 0
	global_load_lds_dwordx4 v142, s[36:37]
	s_add_u32 vcc_lo, vcc_lo, 0x80
	s_addc_u32 vcc_hi, vcc_hi, 0
	s_mov_b32 m0, s56
	s_nop 0
	global_load_lds_dwordx4 v136, vcc
	s_mov_b32 m0, s57
	s_nop 0
	global_load_lds_dwordx4 v140, vcc
	s_waitcnt vmcnt(8)
	s_waitcnt lgkmcnt(0)
	s_barrier
	s_setprio 1
	s_waitcnt lgkmcnt(0)
	v_mfma_f32_16x16x32_bf16 v[60:63], v[128:131], v[198:201], v[60:63]
	v_mfma_f32_16x16x32_bf16 v[56:59], v[158:161], v[198:201], v[56:59]
	v_mfma_f32_16x16x32_bf16 v[44:47], v[128:131], v[206:209], v[44:47]
	v_mfma_f32_16x16x32_bf16 v[40:43], v[158:161], v[206:209], v[40:43]
	v_mfma_f32_16x16x32_bf16 v[28:31], v[128:131], v[214:217], v[28:31]
	v_mfma_f32_16x16x32_bf16 v[24:27], v[158:161], v[214:217], v[24:27]
	v_mfma_f32_16x16x32_bf16 v[12:15], v[128:131], v[222:225], v[12:15]
	v_mfma_f32_16x16x32_bf16 v[8:11], v[158:161], v[222:225], v[8:11]
	v_mfma_f32_16x16x32_bf16 v[60:63], v[132:135], v[202:205], v[60:63]
	v_mfma_f32_16x16x32_bf16 v[56:59], v[178:181], v[202:205], v[56:59]
	v_mfma_f32_16x16x32_bf16 v[44:47], v[132:135], v[210:213], v[44:47]
	v_mfma_f32_16x16x32_bf16 v[40:43], v[178:181], v[210:213], v[40:43]
	v_mfma_f32_16x16x32_bf16 v[28:31], v[132:135], v[218:221], v[28:31]
	v_mfma_f32_16x16x32_bf16 v[24:27], v[178:181], v[218:221], v[24:27]
	v_mfma_f32_16x16x32_bf16 v[12:15], v[132:135], v[230:233], v[12:15]
	v_mfma_f32_16x16x32_bf16 v[8:11], v[178:181], v[230:233], v[8:11]
	v_mfma_f32_16x16x32_bf16 v[52:55], v[182:185], v[198:201], v[52:55]
	v_mfma_f32_16x16x32_bf16 v[48:51], v[190:193], v[198:201], v[48:51]
	v_mfma_f32_16x16x32_bf16 v[36:39], v[182:185], v[206:209], v[36:39]
	v_mfma_f32_16x16x32_bf16 v[32:35], v[190:193], v[206:209], v[32:35]
	v_mfma_f32_16x16x32_bf16 v[20:23], v[182:185], v[214:217], v[20:23]
	v_mfma_f32_16x16x32_bf16 v[16:19], v[190:193], v[214:217], v[16:19]
	v_mfma_f32_16x16x32_bf16 v[4:7], v[182:185], v[222:225], v[4:7]
	v_mfma_f32_16x16x32_bf16 v[0:3], v[190:193], v[222:225], v[0:3]
	v_mfma_f32_16x16x32_bf16 v[52:55], v[186:189], v[202:205], v[52:55]
	v_mfma_f32_16x16x32_bf16 v[48:51], v[194:197], v[202:205], v[48:51]
	v_mfma_f32_16x16x32_bf16 v[36:39], v[186:189], v[210:213], v[36:39]
	v_mfma_f32_16x16x32_bf16 v[32:35], v[194:197], v[210:213], v[32:35]
	v_mfma_f32_16x16x32_bf16 v[20:23], v[186:189], v[218:221], v[20:23]
	v_mfma_f32_16x16x32_bf16 v[16:19], v[194:197], v[218:221], v[16:19]
	v_mfma_f32_16x16x32_bf16 v[4:7], v[186:189], v[230:233], v[4:7]
	v_mfma_f32_16x16x32_bf16 v[0:3], v[194:197], v[230:233], v[0:3]
	s_setprio 0
	s_barrier
	s_add_i32 s18, s18, 2
	s_add_u32 s34, s34, 0x100
	s_addc_u32 s35, s35, 0
	s_add_u32 s15, s15, 0x100
	s_addc_u32 s17, s17, 0
	s_cmp_gt_u32 s18, 29
	s_cbranch_scc0 .LBB0_1773
	s_and_b64 vcc, exec, s[84:85]
	s_cbranch_vccz .LBB0_1776
	s_barrier

.LBB0_2248:
	ds_read_b128 v[144:147], v153
	ds_read_b128 v[156:159], v153 offset:1024
	ds_read_b128 v[160:163], v153 offset:2048
	ds_read_b128 v[164:167], v153 offset:3072
	ds_read_b128 v[168:171], v154
	ds_read_b128 v[172:175], v154 offset:1024
	ds_read_b128 v[176:179], v154 offset:2048
	ds_read_b128 v[180:183], v154 offset:3072
	s_add_u32 s3, s52, 0xfffc0080
	s_addc_u32 s45, s53, -1
	s_cmp_eq_u32 s44, 12
	s_cselect_b32 s59, s0, s45
	s_cselect_b32 s58, s1, s3
	s_cselect_b32 s57, s17, s35
	s_cselect_b32 s56, s27, s33
	s_add_i32 m0, s9, 0xc000
	ds_read_b128 v[184:187], v155
	ds_read_b128 v[188:191], v155 offset:1024
	ds_read_b128 v[192:195], v155 offset:2048
	ds_read_b128 v[196:199], v155 offset:3072
	ds_read_b128 v[200:203], v155 offset:4096
	ds_read_b128 v[204:207], v155 offset:5120
	ds_read_b128 v[208:211], v155 offset:6144
	ds_read_b128 v[212:215], v155 offset:7168
	global_load_lds_dwordx4 v136, s[52:53]
	s_add_i32 m0, s9, 0xe000
	s_nop 0
	global_load_lds_dwordx4 v138, s[52:53]
	s_waitcnt vmcnt(8)
	s_waitcnt lgkmcnt(0)
	s_barrier
	s_setprio 1
	s_waitcnt lgkmcnt(0)
	v_mfma_f32_16x16x32_bf16 v[124:127], v[144:147], v[184:187], v[124:127]
	v_mfma_f32_16x16x32_bf16 v[120:123], v[160:163], v[184:187], v[120:123]
	v_mfma_f32_16x16x32_bf16 v[108:111], v[144:147], v[192:195], v[108:111]
	v_mfma_f32_16x16x32_bf16 v[104:107], v[160:163], v[192:195], v[104:107]
	v_mfma_f32_16x16x32_bf16 v[92:95], v[144:147], v[200:203], v[92:95]
	v_mfma_f32_16x16x32_bf16 v[88:91], v[160:163], v[200:203], v[88:91]
	v_mfma_f32_16x16x32_bf16 v[76:79], v[144:147], v[208:211], v[76:79]
	v_mfma_f32_16x16x32_bf16 v[72:75], v[160:163], v[208:211], v[72:75]
	v_mfma_f32_16x16x32_bf16 v[124:127], v[156:159], v[188:191], v[124:127]
	v_mfma_f32_16x16x32_bf16 v[120:123], v[164:167], v[188:191], v[120:123]
	v_mfma_f32_16x16x32_bf16 v[108:111], v[156:159], v[196:199], v[108:111]
	v_mfma_f32_16x16x32_bf16 v[104:107], v[164:167], v[196:199], v[104:107]
	v_mfma_f32_16x16x32_bf16 v[92:95], v[156:159], v[204:207], v[92:95]
	v_mfma_f32_16x16x32_bf16 v[88:91], v[164:167], v[204:207], v[88:91]
	v_mfma_f32_16x16x32_bf16 v[76:79], v[156:159], v[212:215], v[76:79]
	v_mfma_f32_16x16x32_bf16 v[72:75], v[164:167], v[212:215], v[72:75]
	v_mfma_f32_16x16x32_bf16 v[116:119], v[168:171], v[184:187], v[116:119]
	v_mfma_f32_16x16x32_bf16 v[112:115], v[176:179], v[184:187], v[112:115]
	v_mfma_f32_16x16x32_bf16 v[100:103], v[168:171], v[192:195], v[100:103]
	v_mfma_f32_16x16x32_bf16 v[96:99], v[176:179], v[192:195], v[96:99]
	v_mfma_f32_16x16x32_bf16 v[84:87], v[168:171], v[200:203], v[84:87]
	v_mfma_f32_16x16x32_bf16 v[80:83], v[176:179], v[200:203], v[80:83]
	v_mfma_f32_16x16x32_bf16 v[68:71], v[168:171], v[208:211], v[68:71]
	v_mfma_f32_16x16x32_bf16 v[64:67], v[176:179], v[208:211], v[64:67]
	v_mfma_f32_16x16x32_bf16 v[116:119], v[172:175], v[188:191], v[116:119]
	v_mfma_f32_16x16x32_bf16 v[112:115], v[180:183], v[188:191], v[112:115]
	v_mfma_f32_16x16x32_bf16 v[100:103], v[172:175], v[196:199], v[100:103]
	v_mfma_f32_16x16x32_bf16 v[96:99], v[180:183], v[196:199], v[96:99]
	v_mfma_f32_16x16x32_bf16 v[84:87], v[172:175], v[204:207], v[84:87]
	v_mfma_f32_16x16x32_bf16 v[80:83], v[180:183], v[204:207], v[80:83]
	v_mfma_f32_16x16x32_bf16 v[68:71], v[172:175], v[212:215], v[68:71]
	v_mfma_f32_16x16x32_bf16 v[64:67], v[180:183], v[212:215], v[64:67]
	s_setprio 0
	s_barrier
	s_add_i32 s3, s62, s8
	s_mov_b32 m0, s3
	ds_read_b128 v[184:187], v155 offset:16384
	ds_read_b128 v[188:191], v155 offset:17408
	ds_read_b128 v[192:195], v155 offset:18432
	ds_read_b128 v[196:199], v155 offset:19456
	ds_read_b128 v[200:203], v155 offset:20480
	ds_read_b128 v[204:207], v155 offset:21504
	ds_read_b128 v[208:211], v155 offset:22528
	ds_read_b128 v[212:215], v155 offset:23552
	global_load_lds_dwordx4 v130, s[56:57]
	s_add_i32 m0, s3, 0x2000
	s_add_u32 s50, s56, 0x40000
	s_addc_u32 s51, s57, 0
	s_add_i32 s3, s63, s8
	global_load_lds_dwordx4 v134, s[56:57]
	s_mov_b32 m0, s3
	s_nop 0
	global_load_lds_dwordx4 v130, s[50:51]
	s_add_i32 m0, s3, 0x2000
	s_nop 0
	global_load_lds_dwordx4 v134, s[50:51]
	s_mov_b32 m0, s9
	s_nop 0
	global_load_lds_dwordx4 v128, s[58:59]
	s_mov_b32 m0, s18
	s_nop 0
	global_load_lds_dwordx4 v132, s[58:59]
	s_waitcnt vmcnt(8)
	s_waitcnt lgkmcnt(0)
	s_barrier
	s_setprio 1
	s_waitcnt lgkmcnt(0)
	v_mfma_f32_16x16x32_bf16 v[60:63], v[144:147], v[184:187], v[60:63]
	v_mfma_f32_16x16x32_bf16 v[56:59], v[160:163], v[184:187], v[56:59]
	v_mfma_f32_16x16x32_bf16 v[44:47], v[144:147], v[192:195], v[44:47]
	v_mfma_f32_16x16x32_bf16 v[40:43], v[160:163], v[192:195], v[40:43]
	v_mfma_f32_16x16x32_bf16 v[28:31], v[144:147], v[200:203], v[28:31]
	v_mfma_f32_16x16x32_bf16 v[24:27], v[160:163], v[200:203], v[24:27]
	v_mfma_f32_16x16x32_bf16 v[12:15], v[144:147], v[208:211], v[12:15]
	v_mfma_f32_16x16x32_bf16 v[8:11], v[160:163], v[208:211], v[8:11]
	v_mfma_f32_16x16x32_bf16 v[60:63], v[156:159], v[188:191], v[60:63]
	v_mfma_f32_16x16x32_bf16 v[56:59], v[164:167], v[188:191], v[56:59]
	v_mfma_f32_16x16x32_bf16 v[44:47], v[156:159], v[196:199], v[44:47]
	v_mfma_f32_16x16x32_bf16 v[40:43], v[164:167], v[196:199], v[40:43]
	v_mfma_f32_16x16x32_bf16 v[28:31], v[156:159], v[204:207], v[28:31]
	v_mfma_f32_16x16x32_bf16 v[24:27], v[164:167], v[204:207], v[24:27]
	v_mfma_f32_16x16x32_bf16 v[12:15], v[156:159], v[212:215], v[12:15]
	v_mfma_f32_16x16x32_bf16 v[8:11], v[164:167], v[212:215], v[8:11]
	v_mfma_f32_16x16x32_bf16 v[52:55], v[168:171], v[184:187], v[52:55]
	v_mfma_f32_16x16x32_bf16 v[48:51], v[176:179], v[184:187], v[48:51]
	v_mfma_f32_16x16x32_bf16 v[36:39], v[168:171], v[192:195], v[36:39]
	v_mfma_f32_16x16x32_bf16 v[32:35], v[176:179], v[192:195], v[32:35]
	v_mfma_f32_16x16x32_bf16 v[20:23], v[168:171], v[200:203], v[20:23]
	v_mfma_f32_16x16x32_bf16 v[16:19], v[176:179], v[200:203], v[16:19]
	v_mfma_f32_16x16x32_bf16 v[4:7], v[168:171], v[208:211], v[4:7]
	v_mfma_f32_16x16x32_bf16 v[0:3], v[176:179], v[208:211], v[0:3]
	v_mfma_f32_16x16x32_bf16 v[52:55], v[172:175], v[188:191], v[52:55]
	v_mfma_f32_16x16x32_bf16 v[48:51], v[180:183], v[188:191], v[48:51]
	v_mfma_f32_16x16x32_bf16 v[36:39], v[172:175], v[196:199], v[36:39]
	v_mfma_f32_16x16x32_bf16 v[32:35], v[180:183], v[196:199], v[32:35]
	v_mfma_f32_16x16x32_bf16 v[20:23], v[172:175], v[204:207], v[20:23]
	v_mfma_f32_16x16x32_bf16 v[16:19], v[180:183], v[204:207], v[16:19]
	v_mfma_f32_16x16x32_bf16 v[4:7], v[172:175], v[212:215], v[4:7]
	v_mfma_f32_16x16x32_bf16 v[0:3], v[180:183], v[212:215], v[0:3]
	s_setprio 0
	s_barrier
	s_add_i32 s3, 0, 0x18000
	s_add_i32 s45, 0, 0x1c000
	v_add_u32_e32 v164, s3, v151
	v_add_u32_e32 v180, s45, v151
	ds_read_b128 v[144:147], v164
	ds_read_b128 v[156:159], v164 offset:1024
	ds_read_b128 v[160:163], v164 offset:2048
	ds_read_b128 v[164:167], v164 offset:3072
	ds_read_b128 v[168:171], v180
	ds_read_b128 v[172:175], v180 offset:1024
	ds_read_b128 v[176:179], v180 offset:2048
	ds_read_b128 v[180:183], v180 offset:3072
	s_add_u32 s50, s58, 0x40000
	s_addc_u32 s51, s59, 0
	s_mov_b32 m0, s19
	ds_read_b128 v[184:187], v155 offset:32768
	ds_read_b128 v[188:191], v155 offset:33792
	ds_read_b128 v[192:195], v155 offset:34816
	ds_read_b128 v[196:199], v155 offset:35840
	ds_read_b128 v[200:203], v155 offset:36864
	ds_read_b128 v[204:207], v155 offset:37888
	ds_read_b128 v[208:211], v155 offset:38912
	ds_read_b128 v[212:215], v155 offset:39936
	global_load_lds_dwordx4 v128, s[50:51]
	s_mov_b32 m0, s25
	s_nop 0
	global_load_lds_dwordx4 v132, s[50:51]
	s_waitcnt vmcnt(8)
	s_waitcnt lgkmcnt(0)
	s_barrier
	s_setprio 1
	s_waitcnt lgkmcnt(0)
	v_mfma_f32_16x16x32_bf16 v[124:127], v[144:147], v[184:187], v[124:127]
	v_mfma_f32_16x16x32_bf16 v[120:123], v[160:163], v[184:187], v[120:123]
	v_mfma_f32_16x16x32_bf16 v[108:111], v[144:147], v[192:195], v[108:111]
	v_mfma_f32_16x16x32_bf16 v[104:107], v[160:163], v[192:195], v[104:107]
	v_mfma_f32_16x16x32_bf16 v[92:95], v[144:147], v[200:203], v[92:95]
	v_mfma_f32_16x16x32_bf16 v[88:91], v[160:163], v[200:203], v[88:91]
	v_mfma_f32_16x16x32_bf16 v[76:79], v[144:147], v[208:211], v[76:79]
	v_mfma_f32_16x16x32_bf16 v[72:75], v[160:163], v[208:211], v[72:75]
	v_mfma_f32_16x16x32_bf16 v[124:127], v[156:159], v[188:191], v[124:127]
	v_mfma_f32_16x16x32_bf16 v[120:123], v[164:167], v[188:191], v[120:123]
	v_mfma_f32_16x16x32_bf16 v[108:111], v[156:159], v[196:199], v[108:111]
	v_mfma_f32_16x16x32_bf16 v[104:107], v[164:167], v[196:199], v[104:107]
	v_mfma_f32_16x16x32_bf16 v[92:95], v[156:159], v[204:207], v[92:95]
	v_mfma_f32_16x16x32_bf16 v[88:91], v[164:167], v[204:207], v[88:91]
	v_mfma_f32_16x16x32_bf16 v[76:79], v[156:159], v[212:215], v[76:79]
	v_mfma_f32_16x16x32_bf16 v[72:75], v[164:167], v[212:215], v[72:75]
	v_mfma_f32_16x16x32_bf16 v[116:119], v[168:171], v[184:187], v[116:119]
	v_mfma_f32_16x16x32_bf16 v[112:115], v[176:179], v[184:187], v[112:115]
	v_mfma_f32_16x16x32_bf16 v[100:103], v[168:171], v[192:195], v[100:103]
	v_mfma_f32_16x16x32_bf16 v[96:99], v[176:179], v[192:195], v[96:99]
	v_mfma_f32_16x16x32_bf16 v[84:87], v[168:171], v[200:203], v[84:87]
	v_mfma_f32_16x16x32_bf16 v[80:83], v[176:179], v[200:203], v[80:83]
	v_mfma_f32_16x16x32_bf16 v[68:71], v[168:171], v[208:211], v[68:71]
	v_mfma_f32_16x16x32_bf16 v[64:67], v[176:179], v[208:211], v[64:67]
	v_mfma_f32_16x16x32_bf16 v[116:119], v[172:175], v[188:191], v[116:119]
	v_mfma_f32_16x16x32_bf16 v[112:115], v[180:183], v[188:191], v[112:115]
	v_mfma_f32_16x16x32_bf16 v[100:103], v[172:175], v[196:199], v[100:103]
	v_mfma_f32_16x16x32_bf16 v[96:99], v[180:183], v[196:199], v[96:99]
	v_mfma_f32_16x16x32_bf16 v[84:87], v[172:175], v[204:207], v[84:87]
	v_mfma_f32_16x16x32_bf16 v[80:83], v[180:183], v[204:207], v[80:83]
	v_mfma_f32_16x16x32_bf16 v[68:71], v[172:175], v[212:215], v[68:71]
	v_mfma_f32_16x16x32_bf16 v[64:67], v[180:183], v[212:215], v[64:67]
	s_setprio 0
	s_barrier
	s_add_i32 s3, s3, s8
	s_add_u32 s50, s56, 0x80
	s_addc_u32 s51, s57, 0
	s_mov_b32 m0, s3
	ds_read_b128 v[184:187], v155 offset:49152
	ds_read_b128 v[188:191], v155 offset:50176
	ds_read_b128 v[192:195], v155 offset:51200
	ds_read_b128 v[196:199], v155 offset:52224
	ds_read_b128 v[200:203], v155 offset:53248
	ds_read_b128 v[204:207], v155 offset:54272
	ds_read_b128 v[208:211], v155 offset:55296
	ds_read_b128 v[212:215], v155 offset:56320
	global_load_lds_dwordx4 v130, s[50:51]
	s_add_i32 m0, s3, 0x2000
	s_add_i32 s3, s45, s8
	global_load_lds_dwordx4 v134, s[50:51]
	s_add_u32 s50, s50, 0x40000
	s_addc_u32 s51, s51, 0
	s_mov_b32 m0, s3
	s_nop 0
	global_load_lds_dwordx4 v130, s[50:51]
	s_add_i32 m0, s3, 0x2000
	s_nop 0
	global_load_lds_dwordx4 v134, s[50:51]
	s_add_u32 s58, s58, 0x80
	s_addc_u32 s59, s59, 0
	s_mov_b32 m0, s60
	s_nop 0
	global_load_lds_dwordx4 v128, s[58:59]
	s_mov_b32 m0, s61
	s_nop 0
	global_load_lds_dwordx4 v132, s[58:59]
	s_waitcnt vmcnt(8)
	s_waitcnt lgkmcnt(0)
	s_barrier
	s_setprio 1
	s_waitcnt lgkmcnt(0)
	v_mfma_f32_16x16x32_bf16 v[60:63], v[144:147], v[184:187], v[60:63]
	v_mfma_f32_16x16x32_bf16 v[56:59], v[160:163], v[184:187], v[56:59]
	v_mfma_f32_16x16x32_bf16 v[44:47], v[144:147], v[192:195], v[44:47]
	v_mfma_f32_16x16x32_bf16 v[40:43], v[160:163], v[192:195], v[40:43]
	v_mfma_f32_16x16x32_bf16 v[28:31], v[144:147], v[200:203], v[28:31]
	v_mfma_f32_16x16x32_bf16 v[24:27], v[160:163], v[200:203], v[24:27]
	v_mfma_f32_16x16x32_bf16 v[12:15], v[144:147], v[208:211], v[12:15]
	v_mfma_f32_16x16x32_bf16 v[8:11], v[160:163], v[208:211], v[8:11]
	v_mfma_f32_16x16x32_bf16 v[60:63], v[156:159], v[188:191], v[60:63]
	v_mfma_f32_16x16x32_bf16 v[56:59], v[164:167], v[188:191], v[56:59]
	v_mfma_f32_16x16x32_bf16 v[44:47], v[156:159], v[196:199], v[44:47]
	v_mfma_f32_16x16x32_bf16 v[40:43], v[164:167], v[196:199], v[40:43]
	v_mfma_f32_16x16x32_bf16 v[28:31], v[156:159], v[204:207], v[28:31]
	v_mfma_f32_16x16x32_bf16 v[24:27], v[164:167], v[204:207], v[24:27]
	v_mfma_f32_16x16x32_bf16 v[12:15], v[156:159], v[212:215], v[12:15]
	v_mfma_f32_16x16x32_bf16 v[8:11], v[164:167], v[212:215], v[8:11]
	v_mfma_f32_16x16x32_bf16 v[52:55], v[168:171], v[184:187], v[52:55]
	v_mfma_f32_16x16x32_bf16 v[48:51], v[176:179], v[184:187], v[48:51]
	v_mfma_f32_16x16x32_bf16 v[36:39], v[168:171], v[192:195], v[36:39]
	v_mfma_f32_16x16x32_bf16 v[32:35], v[176:179], v[192:195], v[32:35]
	v_mfma_f32_16x16x32_bf16 v[20:23], v[168:171], v[200:203], v[20:23]
	v_mfma_f32_16x16x32_bf16 v[16:19], v[176:179], v[200:203], v[16:19]
	v_mfma_f32_16x16x32_bf16 v[4:7], v[168:171], v[208:211], v[4:7]
	v_mfma_f32_16x16x32_bf16 v[0:3], v[176:179], v[208:211], v[0:3]
	v_mfma_f32_16x16x32_bf16 v[52:55], v[172:175], v[188:191], v[52:55]
	v_mfma_f32_16x16x32_bf16 v[48:51], v[180:183], v[188:191], v[48:51]
	v_mfma_f32_16x16x32_bf16 v[36:39], v[172:175], v[196:199], v[36:39]
	v_mfma_f32_16x16x32_bf16 v[32:35], v[180:183], v[196:199], v[32:35]
	v_mfma_f32_16x16x32_bf16 v[20:23], v[172:175], v[204:207], v[20:23]
	v_mfma_f32_16x16x32_bf16 v[16:19], v[180:183], v[204:207], v[16:19]
	v_mfma_f32_16x16x32_bf16 v[4:7], v[172:175], v[212:215], v[4:7]
	v_mfma_f32_16x16x32_bf16 v[0:3], v[180:183], v[212:215], v[0:3]
	s_setprio 0
	s_barrier
	s_add_i32 s44, s44, 2
	s_add_u32 s52, s52, 0x100
	s_addc_u32 s53, s53, 0
	s_add_u32 s33, s33, 0x100
	s_addc_u32 s35, s35, 0
	s_cmp_gt_u32 s44, 13
	s_cbranch_scc0 .LBB0_2248
	s_and_b64 vcc, exec, s[12:13]
	s_cbranch_vccz .LBB0_2251
	s_barrier

.LBB0_2272:
	ds_read_b128 v[144:147], v155
	ds_read_b128 v[148:151], v155 offset:1024
	ds_read_b128 v[158:161], v155 offset:2048
	ds_read_b128 v[162:165], v155 offset:3072
	ds_read_b128 v[166:169], v156
	ds_read_b128 v[170:173], v156 offset:1024
	ds_read_b128 v[174:177], v156 offset:2048
	ds_read_b128 v[178:181], v156 offset:3072
	s_add_u32 s3, s52, 0xfffe0080
	s_addc_u32 s51, s53, -1
	s_cmp_eq_u32 s50, 4
	s_cselect_b32 s59, s0, s51
	s_cselect_b32 s58, s1, s3
	s_cselect_b32 s57, s17, s45
	s_cselect_b32 s56, s35, s44
	s_add_i32 m0, s9, 0xc000
	ds_read_b128 v[182:185], v157
	ds_read_b128 v[186:189], v157 offset:1024
	ds_read_b128 v[190:193], v157 offset:2048
	ds_read_b128 v[194:197], v157 offset:3072
	ds_read_b128 v[198:201], v157 offset:4096
	ds_read_b128 v[202:205], v157 offset:5120
	ds_read_b128 v[206:209], v157 offset:6144
	ds_read_b128 v[210:213], v157 offset:7168
	global_load_lds_dwordx4 v136, s[52:53]
	s_add_i32 m0, s9, 0xe000
	s_nop 0
	global_load_lds_dwordx4 v138, s[52:53]
	s_waitcnt vmcnt(8)
	s_waitcnt lgkmcnt(0)
	s_barrier
	s_setprio 1
	s_waitcnt lgkmcnt(0)
	v_mfma_f32_16x16x32_bf16 v[124:127], v[144:147], v[182:185], v[124:127]
	v_mfma_f32_16x16x32_bf16 v[120:123], v[158:161], v[182:185], v[120:123]
	v_mfma_f32_16x16x32_bf16 v[108:111], v[144:147], v[190:193], v[108:111]
	v_mfma_f32_16x16x32_bf16 v[104:107], v[158:161], v[190:193], v[104:107]
	v_mfma_f32_16x16x32_bf16 v[92:95], v[144:147], v[198:201], v[92:95]
	v_mfma_f32_16x16x32_bf16 v[88:91], v[158:161], v[198:201], v[88:91]
	v_mfma_f32_16x16x32_bf16 v[76:79], v[144:147], v[206:209], v[76:79]
	v_mfma_f32_16x16x32_bf16 v[72:75], v[158:161], v[206:209], v[72:75]
	v_mfma_f32_16x16x32_bf16 v[124:127], v[148:151], v[186:189], v[124:127]
	v_mfma_f32_16x16x32_bf16 v[120:123], v[162:165], v[186:189], v[120:123]
	v_mfma_f32_16x16x32_bf16 v[108:111], v[148:151], v[194:197], v[108:111]
	v_mfma_f32_16x16x32_bf16 v[104:107], v[162:165], v[194:197], v[104:107]
	v_mfma_f32_16x16x32_bf16 v[92:95], v[148:151], v[202:205], v[92:95]
	v_mfma_f32_16x16x32_bf16 v[88:91], v[162:165], v[202:205], v[88:91]
	v_mfma_f32_16x16x32_bf16 v[76:79], v[148:151], v[210:213], v[76:79]
	v_mfma_f32_16x16x32_bf16 v[72:75], v[162:165], v[210:213], v[72:75]
	v_mfma_f32_16x16x32_bf16 v[116:119], v[166:169], v[182:185], v[116:119]
	v_mfma_f32_16x16x32_bf16 v[112:115], v[174:177], v[182:185], v[112:115]
	v_mfma_f32_16x16x32_bf16 v[100:103], v[166:169], v[190:193], v[100:103]
	v_mfma_f32_16x16x32_bf16 v[96:99], v[174:177], v[190:193], v[96:99]
	v_mfma_f32_16x16x32_bf16 v[84:87], v[166:169], v[198:201], v[84:87]
	v_mfma_f32_16x16x32_bf16 v[80:83], v[174:177], v[198:201], v[80:83]
	v_mfma_f32_16x16x32_bf16 v[68:71], v[166:169], v[206:209], v[68:71]
	v_mfma_f32_16x16x32_bf16 v[64:67], v[174:177], v[206:209], v[64:67]
	v_mfma_f32_16x16x32_bf16 v[116:119], v[170:173], v[186:189], v[116:119]
	v_mfma_f32_16x16x32_bf16 v[112:115], v[178:181], v[186:189], v[112:115]
	v_mfma_f32_16x16x32_bf16 v[100:103], v[170:173], v[194:197], v[100:103]
	v_mfma_f32_16x16x32_bf16 v[96:99], v[178:181], v[194:197], v[96:99]
	v_mfma_f32_16x16x32_bf16 v[84:87], v[170:173], v[202:205], v[84:87]
	v_mfma_f32_16x16x32_bf16 v[80:83], v[178:181], v[202:205], v[80:83]
	v_mfma_f32_16x16x32_bf16 v[68:71], v[170:173], v[210:213], v[68:71]
	v_mfma_f32_16x16x32_bf16 v[64:67], v[178:181], v[210:213], v[64:67]
	s_setprio 0
	s_barrier
	s_add_i32 s3, s61, s8
	s_mov_b32 m0, s3
	ds_read_b128 v[182:185], v157 offset:16384
	ds_read_b128 v[186:189], v157 offset:17408
	ds_read_b128 v[190:193], v157 offset:18432
	ds_read_b128 v[194:197], v157 offset:19456
	ds_read_b128 v[198:201], v157 offset:20480
	ds_read_b128 v[202:205], v157 offset:21504
	ds_read_b128 v[206:209], v157 offset:22528
	ds_read_b128 v[210:213], v157 offset:23552
	global_load_lds_dwordx4 v130, s[56:57]
	s_add_i32 m0, s3, 0x2000
	s_add_u32 s64, s56, 0x20000
	s_addc_u32 s65, s57, 0
	s_add_i32 s3, s62, s8
	global_load_lds_dwordx4 v134, s[56:57]
	s_mov_b32 m0, s3
	s_nop 0
	global_load_lds_dwordx4 v130, s[64:65]
	s_add_i32 m0, s3, 0x2000
	s_nop 0
	global_load_lds_dwordx4 v134, s[64:65]
	s_mov_b32 m0, s9
	s_nop 0
	global_load_lds_dwordx4 v128, s[58:59]
	s_mov_b32 m0, s18
	s_nop 0
	global_load_lds_dwordx4 v132, s[58:59]
	s_waitcnt vmcnt(8)
	s_waitcnt lgkmcnt(0)
	s_barrier
	s_setprio 1
	s_waitcnt lgkmcnt(0)
	v_mfma_f32_16x16x32_bf16 v[60:63], v[144:147], v[182:185], v[60:63]
	v_mfma_f32_16x16x32_bf16 v[56:59], v[158:161], v[182:185], v[56:59]
	v_mfma_f32_16x16x32_bf16 v[44:47], v[144:147], v[190:193], v[44:47]
	v_mfma_f32_16x16x32_bf16 v[40:43], v[158:161], v[190:193], v[40:43]
	v_mfma_f32_16x16x32_bf16 v[28:31], v[144:147], v[198:201], v[28:31]
	v_mfma_f32_16x16x32_bf16 v[24:27], v[158:161], v[198:201], v[24:27]
	v_mfma_f32_16x16x32_bf16 v[12:15], v[144:147], v[206:209], v[12:15]
	v_mfma_f32_16x16x32_bf16 v[8:11], v[158:161], v[206:209], v[8:11]
	v_mfma_f32_16x16x32_bf16 v[60:63], v[148:151], v[186:189], v[60:63]
	v_mfma_f32_16x16x32_bf16 v[56:59], v[162:165], v[186:189], v[56:59]
	v_mfma_f32_16x16x32_bf16 v[44:47], v[148:151], v[194:197], v[44:47]
	v_mfma_f32_16x16x32_bf16 v[40:43], v[162:165], v[194:197], v[40:43]
	v_mfma_f32_16x16x32_bf16 v[28:31], v[148:151], v[202:205], v[28:31]
	v_mfma_f32_16x16x32_bf16 v[24:27], v[162:165], v[202:205], v[24:27]
	v_mfma_f32_16x16x32_bf16 v[12:15], v[148:151], v[210:213], v[12:15]
	v_mfma_f32_16x16x32_bf16 v[8:11], v[162:165], v[210:213], v[8:11]
	v_mfma_f32_16x16x32_bf16 v[52:55], v[166:169], v[182:185], v[52:55]
	v_mfma_f32_16x16x32_bf16 v[48:51], v[174:177], v[182:185], v[48:51]
	v_mfma_f32_16x16x32_bf16 v[36:39], v[166:169], v[190:193], v[36:39]
	v_mfma_f32_16x16x32_bf16 v[32:35], v[174:177], v[190:193], v[32:35]
	v_mfma_f32_16x16x32_bf16 v[20:23], v[166:169], v[198:201], v[20:23]
	v_mfma_f32_16x16x32_bf16 v[16:19], v[174:177], v[198:201], v[16:19]
	v_mfma_f32_16x16x32_bf16 v[4:7], v[166:169], v[206:209], v[4:7]
	v_mfma_f32_16x16x32_bf16 v[0:3], v[174:177], v[206:209], v[0:3]
	v_mfma_f32_16x16x32_bf16 v[52:55], v[170:173], v[186:189], v[52:55]
	v_mfma_f32_16x16x32_bf16 v[48:51], v[178:181], v[186:189], v[48:51]
	v_mfma_f32_16x16x32_bf16 v[36:39], v[170:173], v[194:197], v[36:39]
	v_mfma_f32_16x16x32_bf16 v[32:35], v[178:181], v[194:197], v[32:35]
	v_mfma_f32_16x16x32_bf16 v[20:23], v[170:173], v[202:205], v[20:23]
	v_mfma_f32_16x16x32_bf16 v[16:19], v[178:181], v[202:205], v[16:19]
	v_mfma_f32_16x16x32_bf16 v[4:7], v[170:173], v[210:213], v[4:7]
	v_mfma_f32_16x16x32_bf16 v[0:3], v[178:181], v[210:213], v[0:3]
	s_setprio 0
	s_barrier
	s_add_i32 s3, 0, 0x18000
	s_add_i32 s51, 0, 0x1c000
	v_add_u32_e32 v162, s3, v153
	v_add_u32_e32 v178, s51, v153
	ds_read_b128 v[144:147], v162
	ds_read_b128 v[148:151], v162 offset:1024
	ds_read_b128 v[158:161], v162 offset:2048
	ds_read_b128 v[162:165], v162 offset:3072
	ds_read_b128 v[166:169], v178
	ds_read_b128 v[170:173], v178 offset:1024
	ds_read_b128 v[174:177], v178 offset:2048
	ds_read_b128 v[178:181], v178 offset:3072
	s_add_u32 s58, s58, 0x20000
	s_addc_u32 s59, s59, 0
	s_mov_b32 m0, s19
	ds_read_b128 v[182:185], v157 offset:32768
	ds_read_b128 v[186:189], v157 offset:33792
	ds_read_b128 v[190:193], v157 offset:34816
	ds_read_b128 v[194:197], v157 offset:35840
	ds_read_b128 v[198:201], v157 offset:36864
	ds_read_b128 v[202:205], v157 offset:37888
	ds_read_b128 v[206:209], v157 offset:38912
	ds_read_b128 v[210:213], v157 offset:39936
	global_load_lds_dwordx4 v128, s[58:59]
	s_mov_b32 m0, s25
	s_nop 0
	global_load_lds_dwordx4 v132, s[58:59]
	s_waitcnt vmcnt(8)
	s_waitcnt lgkmcnt(0)
	s_barrier
	s_setprio 1
	s_waitcnt lgkmcnt(0)
	v_mfma_f32_16x16x32_bf16 v[124:127], v[144:147], v[182:185], v[124:127]
	v_mfma_f32_16x16x32_bf16 v[120:123], v[158:161], v[182:185], v[120:123]
	v_mfma_f32_16x16x32_bf16 v[108:111], v[144:147], v[190:193], v[108:111]
	v_mfma_f32_16x16x32_bf16 v[104:107], v[158:161], v[190:193], v[104:107]
	v_mfma_f32_16x16x32_bf16 v[92:95], v[144:147], v[198:201], v[92:95]
	v_mfma_f32_16x16x32_bf16 v[88:91], v[158:161], v[198:201], v[88:91]
	v_mfma_f32_16x16x32_bf16 v[76:79], v[144:147], v[206:209], v[76:79]
	v_mfma_f32_16x16x32_bf16 v[72:75], v[158:161], v[206:209], v[72:75]
	v_mfma_f32_16x16x32_bf16 v[124:127], v[148:151], v[186:189], v[124:127]
	v_mfma_f32_16x16x32_bf16 v[120:123], v[162:165], v[186:189], v[120:123]
	v_mfma_f32_16x16x32_bf16 v[108:111], v[148:151], v[194:197], v[108:111]
	v_mfma_f32_16x16x32_bf16 v[104:107], v[162:165], v[194:197], v[104:107]
	v_mfma_f32_16x16x32_bf16 v[92:95], v[148:151], v[202:205], v[92:95]
	v_mfma_f32_16x16x32_bf16 v[88:91], v[162:165], v[202:205], v[88:91]
	v_mfma_f32_16x16x32_bf16 v[76:79], v[148:151], v[210:213], v[76:79]
	v_mfma_f32_16x16x32_bf16 v[72:75], v[162:165], v[210:213], v[72:75]
	v_mfma_f32_16x16x32_bf16 v[116:119], v[166:169], v[182:185], v[116:119]
	v_mfma_f32_16x16x32_bf16 v[112:115], v[174:177], v[182:185], v[112:115]
	v_mfma_f32_16x16x32_bf16 v[100:103], v[166:169], v[190:193], v[100:103]
	v_mfma_f32_16x16x32_bf16 v[96:99], v[174:177], v[190:193], v[96:99]
	v_mfma_f32_16x16x32_bf16 v[84:87], v[166:169], v[198:201], v[84:87]
	v_mfma_f32_16x16x32_bf16 v[80:83], v[174:177], v[198:201], v[80:83]
	v_mfma_f32_16x16x32_bf16 v[68:71], v[166:169], v[206:209], v[68:71]
	v_mfma_f32_16x16x32_bf16 v[64:67], v[174:177], v[206:209], v[64:67]
	v_mfma_f32_16x16x32_bf16 v[116:119], v[170:173], v[186:189], v[116:119]
	v_mfma_f32_16x16x32_bf16 v[112:115], v[178:181], v[186:189], v[112:115]
	v_mfma_f32_16x16x32_bf16 v[100:103], v[170:173], v[194:197], v[100:103]
	v_mfma_f32_16x16x32_bf16 v[96:99], v[178:181], v[194:197], v[96:99]
	v_mfma_f32_16x16x32_bf16 v[84:87], v[170:173], v[202:205], v[84:87]
	v_mfma_f32_16x16x32_bf16 v[80:83], v[178:181], v[202:205], v[80:83]
	v_mfma_f32_16x16x32_bf16 v[68:71], v[170:173], v[210:213], v[68:71]
	v_mfma_f32_16x16x32_bf16 v[64:67], v[178:181], v[210:213], v[64:67]
	s_setprio 0
	s_barrier
	s_add_i32 s3, s3, s8
	s_add_u32 s56, s56, 0x80
	s_addc_u32 s57, s57, 0
	s_mov_b32 m0, s3
	ds_read_b128 v[182:185], v157 offset:49152
	ds_read_b128 v[186:189], v157 offset:50176
	ds_read_b128 v[190:193], v157 offset:51200
	ds_read_b128 v[194:197], v157 offset:52224
	ds_read_b128 v[198:201], v157 offset:53248
	ds_read_b128 v[202:205], v157 offset:54272
	ds_read_b128 v[206:209], v157 offset:55296
	ds_read_b128 v[210:213], v157 offset:56320
	global_load_lds_dwordx4 v130, s[56:57]
	s_add_i32 m0, s3, 0x2000
	s_add_i32 s3, s51, s8
	global_load_lds_dwordx4 v134, s[56:57]
	s_add_u32 s56, s56, 0x20000
	s_addc_u32 s57, s57, 0
	s_mov_b32 m0, s3
	s_nop 0
	global_load_lds_dwordx4 v130, s[56:57]
	s_add_i32 m0, s3, 0x2000
	s_nop 0
	global_load_lds_dwordx4 v134, s[56:57]
	s_add_u32 s58, s58, 0xfffe0080
	s_addc_u32 s59, s59, -1
	s_mov_b32 m0, s49
	s_nop 0
	global_load_lds_dwordx4 v128, s[58:59]
	s_mov_b32 m0, s60
	s_nop 0
	global_load_lds_dwordx4 v132, s[58:59]
	s_waitcnt vmcnt(8)
	s_waitcnt lgkmcnt(0)
	s_barrier
	s_setprio 1
	s_waitcnt lgkmcnt(0)
	v_mfma_f32_16x16x32_bf16 v[60:63], v[144:147], v[182:185], v[60:63]
	v_mfma_f32_16x16x32_bf16 v[56:59], v[158:161], v[182:185], v[56:59]
	v_mfma_f32_16x16x32_bf16 v[44:47], v[144:147], v[190:193], v[44:47]
	v_mfma_f32_16x16x32_bf16 v[40:43], v[158:161], v[190:193], v[40:43]
	v_mfma_f32_16x16x32_bf16 v[28:31], v[144:147], v[198:201], v[28:31]
	v_mfma_f32_16x16x32_bf16 v[24:27], v[158:161], v[198:201], v[24:27]
	v_mfma_f32_16x16x32_bf16 v[12:15], v[144:147], v[206:209], v[12:15]
	v_mfma_f32_16x16x32_bf16 v[8:11], v[158:161], v[206:209], v[8:11]
	v_mfma_f32_16x16x32_bf16 v[60:63], v[148:151], v[186:189], v[60:63]
	v_mfma_f32_16x16x32_bf16 v[56:59], v[162:165], v[186:189], v[56:59]
	v_mfma_f32_16x16x32_bf16 v[44:47], v[148:151], v[194:197], v[44:47]
	v_mfma_f32_16x16x32_bf16 v[40:43], v[162:165], v[194:197], v[40:43]
	v_mfma_f32_16x16x32_bf16 v[28:31], v[148:151], v[202:205], v[28:31]
	v_mfma_f32_16x16x32_bf16 v[24:27], v[162:165], v[202:205], v[24:27]
	v_mfma_f32_16x16x32_bf16 v[12:15], v[148:151], v[210:213], v[12:15]
	v_mfma_f32_16x16x32_bf16 v[8:11], v[162:165], v[210:213], v[8:11]
	v_mfma_f32_16x16x32_bf16 v[52:55], v[166:169], v[182:185], v[52:55]
	v_mfma_f32_16x16x32_bf16 v[48:51], v[174:177], v[182:185], v[48:51]
	v_mfma_f32_16x16x32_bf16 v[36:39], v[166:169], v[190:193], v[36:39]
	v_mfma_f32_16x16x32_bf16 v[32:35], v[174:177], v[190:193], v[32:35]
	v_mfma_f32_16x16x32_bf16 v[20:23], v[166:169], v[198:201], v[20:23]
	v_mfma_f32_16x16x32_bf16 v[16:19], v[174:177], v[198:201], v[16:19]
	v_mfma_f32_16x16x32_bf16 v[4:7], v[166:169], v[206:209], v[4:7]
	v_mfma_f32_16x16x32_bf16 v[0:3], v[174:177], v[206:209], v[0:3]
	v_mfma_f32_16x16x32_bf16 v[52:55], v[170:173], v[186:189], v[52:55]
	v_mfma_f32_16x16x32_bf16 v[48:51], v[178:181], v[186:189], v[48:51]
	v_mfma_f32_16x16x32_bf16 v[36:39], v[170:173], v[194:197], v[36:39]
	v_mfma_f32_16x16x32_bf16 v[32:35], v[178:181], v[194:197], v[32:35]
	v_mfma_f32_16x16x32_bf16 v[20:23], v[170:173], v[202:205], v[20:23]
	v_mfma_f32_16x16x32_bf16 v[16:19], v[178:181], v[202:205], v[16:19]
	v_mfma_f32_16x16x32_bf16 v[4:7], v[170:173], v[210:213], v[4:7]
	v_mfma_f32_16x16x32_bf16 v[0:3], v[178:181], v[210:213], v[0:3]
	s_setprio 0
	s_barrier
	s_add_i32 s50, s50, 2
	s_add_u32 s52, s52, 0x100
	s_addc_u32 s53, s53, 0
	s_add_u32 s44, s44, 0x100
	s_addc_u32 s45, s45, 0
	s_cmp_gt_u32 s50, 5
	s_cbranch_scc0 .LBB0_2272
	s_and_b64 vcc, exec, s[12:13]
	s_cbranch_vccz .LBB0_2275
	s_barrier

.LBB0_2348:
	ds_read_b128 v[140:143], v149
	ds_read_b128 v[152:155], v149 offset:1024
	ds_read_b128 v[156:159], v149 offset:2048
	ds_read_b128 v[160:163], v149 offset:3072
	ds_read_b128 v[164:167], v150
	ds_read_b128 v[168:171], v150 offset:1024
	ds_read_b128 v[172:175], v150 offset:2048
	ds_read_b128 v[176:179], v150 offset:3072
	s_add_u32 s3, s66, 0xfff80080
	s_addc_u32 s59, s67, -1
	s_cmp_eq_u32 s57, 28
	s_cselect_b32 s75, s0, s59
	s_cselect_b32 s74, s1, s3
	s_cselect_b32 s73, s44, s51
	s_cselect_b32 s72, s45, s50
	s_add_i32 m0, s9, 0xc000
	ds_read_b128 v[180:183], v151
	ds_read_b128 v[184:187], v151 offset:1024
	ds_read_b128 v[188:191], v151 offset:2048
	ds_read_b128 v[192:195], v151 offset:3072
	ds_read_b128 v[196:199], v151 offset:4096
	ds_read_b128 v[200:203], v151 offset:5120
	ds_read_b128 v[204:207], v151 offset:6144
	ds_read_b128 v[208:211], v151 offset:7168
	global_load_lds_dwordx4 v132, s[66:67]
	s_add_i32 m0, s9, 0xe000
	s_nop 0
	global_load_lds_dwordx4 v134, s[66:67]
	s_waitcnt vmcnt(8)
	s_waitcnt lgkmcnt(0)
	s_barrier
	s_setprio 1
	s_waitcnt lgkmcnt(0)
	v_mfma_f32_16x16x32_bf16 v[124:127], v[140:143], v[180:183], v[124:127]
	v_mfma_f32_16x16x32_bf16 v[120:123], v[156:159], v[180:183], v[120:123]
	v_mfma_f32_16x16x32_bf16 v[108:111], v[140:143], v[188:191], v[108:111]
	v_mfma_f32_16x16x32_bf16 v[104:107], v[156:159], v[188:191], v[104:107]
	v_mfma_f32_16x16x32_bf16 v[92:95], v[140:143], v[196:199], v[92:95]
	v_mfma_f32_16x16x32_bf16 v[88:91], v[156:159], v[196:199], v[88:91]
	v_mfma_f32_16x16x32_bf16 v[76:79], v[140:143], v[204:207], v[76:79]
	v_mfma_f32_16x16x32_bf16 v[72:75], v[156:159], v[204:207], v[72:75]
	v_mfma_f32_16x16x32_bf16 v[124:127], v[152:155], v[184:187], v[124:127]
	v_mfma_f32_16x16x32_bf16 v[120:123], v[160:163], v[184:187], v[120:123]
	v_mfma_f32_16x16x32_bf16 v[108:111], v[152:155], v[192:195], v[108:111]
	v_mfma_f32_16x16x32_bf16 v[104:107], v[160:163], v[192:195], v[104:107]
	v_mfma_f32_16x16x32_bf16 v[92:95], v[152:155], v[200:203], v[92:95]
	v_mfma_f32_16x16x32_bf16 v[88:91], v[160:163], v[200:203], v[88:91]
	v_mfma_f32_16x16x32_bf16 v[76:79], v[152:155], v[208:211], v[76:79]
	v_mfma_f32_16x16x32_bf16 v[72:75], v[160:163], v[208:211], v[72:75]
	v_mfma_f32_16x16x32_bf16 v[116:119], v[164:167], v[180:183], v[116:119]
	v_mfma_f32_16x16x32_bf16 v[112:115], v[172:175], v[180:183], v[112:115]
	v_mfma_f32_16x16x32_bf16 v[100:103], v[164:167], v[188:191], v[100:103]
	v_mfma_f32_16x16x32_bf16 v[96:99], v[172:175], v[188:191], v[96:99]
	v_mfma_f32_16x16x32_bf16 v[84:87], v[164:167], v[196:199], v[84:87]
	v_mfma_f32_16x16x32_bf16 v[80:83], v[172:175], v[196:199], v[80:83]
	v_mfma_f32_16x16x32_bf16 v[68:71], v[164:167], v[204:207], v[68:71]
	v_mfma_f32_16x16x32_bf16 v[64:67], v[172:175], v[204:207], v[64:67]
	v_mfma_f32_16x16x32_bf16 v[116:119], v[168:171], v[184:187], v[116:119]
	v_mfma_f32_16x16x32_bf16 v[112:115], v[176:179], v[184:187], v[112:115]
	v_mfma_f32_16x16x32_bf16 v[100:103], v[168:171], v[192:195], v[100:103]
	v_mfma_f32_16x16x32_bf16 v[96:99], v[176:179], v[192:195], v[96:99]
	v_mfma_f32_16x16x32_bf16 v[84:87], v[168:171], v[200:203], v[84:87]
	v_mfma_f32_16x16x32_bf16 v[80:83], v[176:179], v[200:203], v[80:83]
	v_mfma_f32_16x16x32_bf16 v[68:71], v[168:171], v[208:211], v[68:71]
	v_mfma_f32_16x16x32_bf16 v[64:67], v[176:179], v[208:211], v[64:67]
	s_setprio 0
	s_barrier
	s_add_i32 s3, s68, s8
	s_mov_b32 m0, s3
	ds_read_b128 v[180:183], v151 offset:16384
	ds_read_b128 v[184:187], v151 offset:17408
	ds_read_b128 v[188:191], v151 offset:18432
	ds_read_b128 v[192:195], v151 offset:19456
	ds_read_b128 v[196:199], v151 offset:20480
	ds_read_b128 v[200:203], v151 offset:21504
	ds_read_b128 v[204:207], v151 offset:22528
	ds_read_b128 v[208:211], v151 offset:23552
	global_load_lds_dwordx4 v128, s[72:73]
	s_add_i32 m0, s3, 0x2000
	s_add_u32 s70, s72, 0x80000
	s_addc_u32 s71, s73, 0
	s_add_i32 s3, s69, s8
	global_load_lds_dwordx4 v130, s[72:73]
	s_mov_b32 m0, s3
	s_nop 0
	global_load_lds_dwordx4 v128, s[70:71]
	s_add_i32 m0, s3, 0x2000
	s_nop 0
	global_load_lds_dwordx4 v130, s[70:71]
	s_mov_b32 m0, s9
	s_nop 0
	global_load_lds_dwordx4 v128, s[74:75]
	s_mov_b32 m0, s18
	s_nop 0
	global_load_lds_dwordx4 v130, s[74:75]
	s_waitcnt vmcnt(8)
	s_waitcnt lgkmcnt(0)
	s_barrier
	s_setprio 1
	s_waitcnt lgkmcnt(0)
	v_mfma_f32_16x16x32_bf16 v[60:63], v[140:143], v[180:183], v[60:63]
	v_mfma_f32_16x16x32_bf16 v[56:59], v[156:159], v[180:183], v[56:59]
	v_mfma_f32_16x16x32_bf16 v[44:47], v[140:143], v[188:191], v[44:47]
	v_mfma_f32_16x16x32_bf16 v[40:43], v[156:159], v[188:191], v[40:43]
	v_mfma_f32_16x16x32_bf16 v[28:31], v[140:143], v[196:199], v[28:31]
	v_mfma_f32_16x16x32_bf16 v[24:27], v[156:159], v[196:199], v[24:27]
	v_mfma_f32_16x16x32_bf16 v[12:15], v[140:143], v[204:207], v[12:15]
	v_mfma_f32_16x16x32_bf16 v[8:11], v[156:159], v[204:207], v[8:11]
	v_mfma_f32_16x16x32_bf16 v[60:63], v[152:155], v[184:187], v[60:63]
	v_mfma_f32_16x16x32_bf16 v[56:59], v[160:163], v[184:187], v[56:59]
	v_mfma_f32_16x16x32_bf16 v[44:47], v[152:155], v[192:195], v[44:47]
	v_mfma_f32_16x16x32_bf16 v[40:43], v[160:163], v[192:195], v[40:43]
	v_mfma_f32_16x16x32_bf16 v[28:31], v[152:155], v[200:203], v[28:31]
	v_mfma_f32_16x16x32_bf16 v[24:27], v[160:163], v[200:203], v[24:27]
	v_mfma_f32_16x16x32_bf16 v[12:15], v[152:155], v[208:211], v[12:15]
	v_mfma_f32_16x16x32_bf16 v[8:11], v[160:163], v[208:211], v[8:11]
	v_mfma_f32_16x16x32_bf16 v[52:55], v[164:167], v[180:183], v[52:55]
	v_mfma_f32_16x16x32_bf16 v[48:51], v[172:175], v[180:183], v[48:51]
	v_mfma_f32_16x16x32_bf16 v[36:39], v[164:167], v[188:191], v[36:39]
	v_mfma_f32_16x16x32_bf16 v[32:35], v[172:175], v[188:191], v[32:35]
	v_mfma_f32_16x16x32_bf16 v[20:23], v[164:167], v[196:199], v[20:23]
	v_mfma_f32_16x16x32_bf16 v[16:19], v[172:175], v[196:199], v[16:19]
	v_mfma_f32_16x16x32_bf16 v[4:7], v[164:167], v[204:207], v[4:7]
	v_mfma_f32_16x16x32_bf16 v[0:3], v[172:175], v[204:207], v[0:3]
	v_mfma_f32_16x16x32_bf16 v[52:55], v[168:171], v[184:187], v[52:55]
	v_mfma_f32_16x16x32_bf16 v[48:51], v[176:179], v[184:187], v[48:51]
	v_mfma_f32_16x16x32_bf16 v[36:39], v[168:171], v[192:195], v[36:39]
	v_mfma_f32_16x16x32_bf16 v[32:35], v[176:179], v[192:195], v[32:35]
	v_mfma_f32_16x16x32_bf16 v[20:23], v[168:171], v[200:203], v[20:23]
	v_mfma_f32_16x16x32_bf16 v[16:19], v[176:179], v[200:203], v[16:19]
	v_mfma_f32_16x16x32_bf16 v[4:7], v[168:171], v[208:211], v[4:7]
	v_mfma_f32_16x16x32_bf16 v[0:3], v[176:179], v[208:211], v[0:3]
	s_setprio 0
	s_barrier
	s_add_i32 s3, 0, 0x18000
	s_add_i32 s59, 0, 0x1c000
	v_add_u32_e32 v160, s3, v147
	v_add_u32_e32 v176, s59, v147
	ds_read_b128 v[140:143], v160
	ds_read_b128 v[152:155], v160 offset:1024
	ds_read_b128 v[156:159], v160 offset:2048
	ds_read_b128 v[160:163], v160 offset:3072
	ds_read_b128 v[164:167], v176
	ds_read_b128 v[168:171], v176 offset:1024
	ds_read_b128 v[172:175], v176 offset:2048
	ds_read_b128 v[176:179], v176 offset:3072
	s_add_u32 s70, s74, 0x80000
	s_addc_u32 s71, s75, 0
	s_mov_b32 m0, s19
	ds_read_b128 v[180:183], v151 offset:32768
	ds_read_b128 v[184:187], v151 offset:33792
	ds_read_b128 v[188:191], v151 offset:34816
	ds_read_b128 v[192:195], v151 offset:35840
	ds_read_b128 v[196:199], v151 offset:36864
	ds_read_b128 v[200:203], v151 offset:37888
	ds_read_b128 v[204:207], v151 offset:38912
	ds_read_b128 v[208:211], v151 offset:39936
	global_load_lds_dwordx4 v128, s[70:71]
	s_mov_b32 m0, s25
	s_nop 0
	global_load_lds_dwordx4 v130, s[70:71]
	s_waitcnt vmcnt(8)
	s_waitcnt lgkmcnt(0)
	s_barrier
	s_setprio 1
	s_waitcnt lgkmcnt(0)
	v_mfma_f32_16x16x32_bf16 v[124:127], v[140:143], v[180:183], v[124:127]
	v_mfma_f32_16x16x32_bf16 v[120:123], v[156:159], v[180:183], v[120:123]
	v_mfma_f32_16x16x32_bf16 v[108:111], v[140:143], v[188:191], v[108:111]
	v_mfma_f32_16x16x32_bf16 v[104:107], v[156:159], v[188:191], v[104:107]
	v_mfma_f32_16x16x32_bf16 v[92:95], v[140:143], v[196:199], v[92:95]
	v_mfma_f32_16x16x32_bf16 v[88:91], v[156:159], v[196:199], v[88:91]
	v_mfma_f32_16x16x32_bf16 v[76:79], v[140:143], v[204:207], v[76:79]
	v_mfma_f32_16x16x32_bf16 v[72:75], v[156:159], v[204:207], v[72:75]
	v_mfma_f32_16x16x32_bf16 v[124:127], v[152:155], v[184:187], v[124:127]
	v_mfma_f32_16x16x32_bf16 v[120:123], v[160:163], v[184:187], v[120:123]
	v_mfma_f32_16x16x32_bf16 v[108:111], v[152:155], v[192:195], v[108:111]
	v_mfma_f32_16x16x32_bf16 v[104:107], v[160:163], v[192:195], v[104:107]
	v_mfma_f32_16x16x32_bf16 v[92:95], v[152:155], v[200:203], v[92:95]
	v_mfma_f32_16x16x32_bf16 v[88:91], v[160:163], v[200:203], v[88:91]
	v_mfma_f32_16x16x32_bf16 v[76:79], v[152:155], v[208:211], v[76:79]
	v_mfma_f32_16x16x32_bf16 v[72:75], v[160:163], v[208:211], v[72:75]
	v_mfma_f32_16x16x32_bf16 v[116:119], v[164:167], v[180:183], v[116:119]
	v_mfma_f32_16x16x32_bf16 v[112:115], v[172:175], v[180:183], v[112:115]
	v_mfma_f32_16x16x32_bf16 v[100:103], v[164:167], v[188:191], v[100:103]
	v_mfma_f32_16x16x32_bf16 v[96:99], v[172:175], v[188:191], v[96:99]
	v_mfma_f32_16x16x32_bf16 v[84:87], v[164:167], v[196:199], v[84:87]
	v_mfma_f32_16x16x32_bf16 v[80:83], v[172:175], v[196:199], v[80:83]
	v_mfma_f32_16x16x32_bf16 v[68:71], v[164:167], v[204:207], v[68:71]
	v_mfma_f32_16x16x32_bf16 v[64:67], v[172:175], v[204:207], v[64:67]
	v_mfma_f32_16x16x32_bf16 v[116:119], v[168:171], v[184:187], v[116:119]
	v_mfma_f32_16x16x32_bf16 v[112:115], v[176:179], v[184:187], v[112:115]
	v_mfma_f32_16x16x32_bf16 v[100:103], v[168:171], v[192:195], v[100:103]
	v_mfma_f32_16x16x32_bf16 v[96:99], v[176:179], v[192:195], v[96:99]
	v_mfma_f32_16x16x32_bf16 v[84:87], v[168:171], v[200:203], v[84:87]
	v_mfma_f32_16x16x32_bf16 v[80:83], v[176:179], v[200:203], v[80:83]
	v_mfma_f32_16x16x32_bf16 v[68:71], v[168:171], v[208:211], v[68:71]
	v_mfma_f32_16x16x32_bf16 v[64:67], v[176:179], v[208:211], v[64:67]
	s_setprio 0
	s_barrier
	s_add_i32 s3, s3, s8
	s_add_u32 s70, s72, 0x80
	s_addc_u32 s71, s73, 0
	s_mov_b32 m0, s3
	ds_read_b128 v[180:183], v151 offset:49152
	ds_read_b128 v[184:187], v151 offset:50176
	ds_read_b128 v[188:191], v151 offset:51200
	ds_read_b128 v[192:195], v151 offset:52224
	ds_read_b128 v[196:199], v151 offset:53248
	ds_read_b128 v[200:203], v151 offset:54272
	ds_read_b128 v[204:207], v151 offset:55296
	ds_read_b128 v[208:211], v151 offset:56320
	global_load_lds_dwordx4 v128, s[70:71]
	s_add_i32 m0, s3, 0x2000
	s_add_i32 s3, s59, s8
	global_load_lds_dwordx4 v130, s[70:71]
	s_add_u32 s70, s70, 0x80000
	s_addc_u32 s71, s71, 0
	s_mov_b32 m0, s3
	s_nop 0
	global_load_lds_dwordx4 v128, s[70:71]
	s_add_i32 m0, s3, 0x2000
	s_nop 0
	global_load_lds_dwordx4 v130, s[70:71]
	s_add_u32 s74, s74, 0x80
	s_addc_u32 s75, s75, 0
	s_mov_b32 m0, s33
	s_nop 0
	global_load_lds_dwordx4 v128, s[74:75]
	s_mov_b32 m0, s65
	s_nop 0
	global_load_lds_dwordx4 v130, s[74:75]
	s_waitcnt vmcnt(8)
	s_waitcnt lgkmcnt(0)
	s_barrier
	s_setprio 1
	s_waitcnt lgkmcnt(0)
	v_mfma_f32_16x16x32_bf16 v[60:63], v[140:143], v[180:183], v[60:63]
	v_mfma_f32_16x16x32_bf16 v[56:59], v[156:159], v[180:183], v[56:59]
	v_mfma_f32_16x16x32_bf16 v[44:47], v[140:143], v[188:191], v[44:47]
	v_mfma_f32_16x16x32_bf16 v[40:43], v[156:159], v[188:191], v[40:43]
	v_mfma_f32_16x16x32_bf16 v[28:31], v[140:143], v[196:199], v[28:31]
	v_mfma_f32_16x16x32_bf16 v[24:27], v[156:159], v[196:199], v[24:27]
	v_mfma_f32_16x16x32_bf16 v[12:15], v[140:143], v[204:207], v[12:15]
	v_mfma_f32_16x16x32_bf16 v[8:11], v[156:159], v[204:207], v[8:11]
	v_mfma_f32_16x16x32_bf16 v[60:63], v[152:155], v[184:187], v[60:63]
	v_mfma_f32_16x16x32_bf16 v[56:59], v[160:163], v[184:187], v[56:59]
	v_mfma_f32_16x16x32_bf16 v[44:47], v[152:155], v[192:195], v[44:47]
	v_mfma_f32_16x16x32_bf16 v[40:43], v[160:163], v[192:195], v[40:43]
	v_mfma_f32_16x16x32_bf16 v[28:31], v[152:155], v[200:203], v[28:31]
	v_mfma_f32_16x16x32_bf16 v[24:27], v[160:163], v[200:203], v[24:27]
	v_mfma_f32_16x16x32_bf16 v[12:15], v[152:155], v[208:211], v[12:15]
	v_mfma_f32_16x16x32_bf16 v[8:11], v[160:163], v[208:211], v[8:11]
	v_mfma_f32_16x16x32_bf16 v[52:55], v[164:167], v[180:183], v[52:55]
	v_mfma_f32_16x16x32_bf16 v[48:51], v[172:175], v[180:183], v[48:51]
	v_mfma_f32_16x16x32_bf16 v[36:39], v[164:167], v[188:191], v[36:39]
	v_mfma_f32_16x16x32_bf16 v[32:35], v[172:175], v[188:191], v[32:35]
	v_mfma_f32_16x16x32_bf16 v[20:23], v[164:167], v[196:199], v[20:23]
	v_mfma_f32_16x16x32_bf16 v[16:19], v[172:175], v[196:199], v[16:19]
	v_mfma_f32_16x16x32_bf16 v[4:7], v[164:167], v[204:207], v[4:7]
	v_mfma_f32_16x16x32_bf16 v[0:3], v[172:175], v[204:207], v[0:3]
	v_mfma_f32_16x16x32_bf16 v[52:55], v[168:171], v[184:187], v[52:55]
	v_mfma_f32_16x16x32_bf16 v[48:51], v[176:179], v[184:187], v[48:51]
	v_mfma_f32_16x16x32_bf16 v[36:39], v[168:171], v[192:195], v[36:39]
	v_mfma_f32_16x16x32_bf16 v[32:35], v[176:179], v[192:195], v[32:35]
	v_mfma_f32_16x16x32_bf16 v[20:23], v[168:171], v[200:203], v[20:23]
	v_mfma_f32_16x16x32_bf16 v[16:19], v[176:179], v[200:203], v[16:19]
	v_mfma_f32_16x16x32_bf16 v[4:7], v[168:171], v[208:211], v[4:7]
	v_mfma_f32_16x16x32_bf16 v[0:3], v[176:179], v[208:211], v[0:3]
	s_setprio 0
	s_barrier
	s_add_i32 s57, s57, 2
	s_add_u32 s66, s66, 0x100
	s_addc_u32 s67, s67, 0
	s_add_u32 s50, s50, 0x100
	s_addc_u32 s51, s51, 0
	s_cmp_gt_u32 s57, 29
	s_cbranch_scc0 .LBB0_2348
	s_and_b64 vcc, exec, s[14:15]
	s_cbranch_vccz .LBB0_2351
	s_barrier

.LBB0_2479:
	ds_read_b128 v[154:157], v150
	ds_read_b128 v[158:161], v150 offset:1024
	ds_read_b128 v[162:165], v150 offset:2048
	ds_read_b128 v[166:169], v150 offset:3072
	ds_read_b128 v[170:173], v151
	ds_read_b128 v[174:177], v151 offset:1024
	ds_read_b128 v[178:181], v151 offset:2048
	ds_read_b128 v[182:185], v151 offset:3072
	s_add_u32 s3, s42, 0xfff80080
	s_addc_u32 s44, s43, -1
	s_cmp_eq_u32 s51, 28
	s_cselect_b32 s49, s0, s44
	s_cselect_b32 s48, s1, s3
	s_cselect_b32 s45, s15, s50
	s_cselect_b32 s44, s17, s41
	s_add_i32 m0, s19, 0xc000
	ds_read_b128 v[186:189], v152
	ds_read_b128 v[190:193], v152 offset:1024
	ds_read_b128 v[194:197], v152 offset:2048
	ds_read_b128 v[198:201], v152 offset:3072
	ds_read_b128 v[202:205], v152 offset:4096
	ds_read_b128 v[206:209], v152 offset:5120
	ds_read_b128 v[210:213], v152 offset:6144
	ds_read_b128 v[214:217], v152 offset:7168
	global_load_lds_dwordx4 v138, s[42:43]
	s_add_i32 m0, s19, 0xe000
	s_nop 0
	global_load_lds_dwordx4 v140, s[42:43]
	s_waitcnt vmcnt(8)
	s_waitcnt lgkmcnt(0)
	s_barrier
	s_setprio 1
	s_waitcnt lgkmcnt(0)
	v_mfma_f32_16x16x32_bf16 v[124:127], v[154:157], v[186:189], v[124:127]
	v_mfma_f32_16x16x32_bf16 v[120:123], v[162:165], v[186:189], v[120:123]
	v_mfma_f32_16x16x32_bf16 v[108:111], v[154:157], v[194:197], v[108:111]
	v_mfma_f32_16x16x32_bf16 v[104:107], v[162:165], v[194:197], v[104:107]
	v_mfma_f32_16x16x32_bf16 v[92:95], v[154:157], v[202:205], v[92:95]
	v_mfma_f32_16x16x32_bf16 v[88:91], v[162:165], v[202:205], v[88:91]
	v_mfma_f32_16x16x32_bf16 v[76:79], v[154:157], v[210:213], v[76:79]
	v_mfma_f32_16x16x32_bf16 v[72:75], v[162:165], v[210:213], v[72:75]
	v_mfma_f32_16x16x32_bf16 v[124:127], v[158:161], v[190:193], v[124:127]
	v_mfma_f32_16x16x32_bf16 v[120:123], v[166:169], v[190:193], v[120:123]
	v_mfma_f32_16x16x32_bf16 v[108:111], v[158:161], v[198:201], v[108:111]
	v_mfma_f32_16x16x32_bf16 v[104:107], v[166:169], v[198:201], v[104:107]
	v_mfma_f32_16x16x32_bf16 v[92:95], v[158:161], v[206:209], v[92:95]
	v_mfma_f32_16x16x32_bf16 v[88:91], v[166:169], v[206:209], v[88:91]
	v_mfma_f32_16x16x32_bf16 v[76:79], v[158:161], v[214:217], v[76:79]
	v_mfma_f32_16x16x32_bf16 v[72:75], v[166:169], v[214:217], v[72:75]
	v_mfma_f32_16x16x32_bf16 v[116:119], v[170:173], v[186:189], v[116:119]
	v_mfma_f32_16x16x32_bf16 v[112:115], v[178:181], v[186:189], v[112:115]
	v_mfma_f32_16x16x32_bf16 v[100:103], v[170:173], v[194:197], v[100:103]
	v_mfma_f32_16x16x32_bf16 v[96:99], v[178:181], v[194:197], v[96:99]
	v_mfma_f32_16x16x32_bf16 v[84:87], v[170:173], v[202:205], v[84:87]
	v_mfma_f32_16x16x32_bf16 v[80:83], v[178:181], v[202:205], v[80:83]
	v_mfma_f32_16x16x32_bf16 v[68:71], v[170:173], v[210:213], v[68:71]
	v_mfma_f32_16x16x32_bf16 v[64:67], v[178:181], v[210:213], v[64:67]
	v_mfma_f32_16x16x32_bf16 v[116:119], v[174:177], v[190:193], v[116:119]
	v_mfma_f32_16x16x32_bf16 v[112:115], v[182:185], v[190:193], v[112:115]
	v_mfma_f32_16x16x32_bf16 v[100:103], v[174:177], v[198:201], v[100:103]
	v_mfma_f32_16x16x32_bf16 v[96:99], v[182:185], v[198:201], v[96:99]
	v_mfma_f32_16x16x32_bf16 v[84:87], v[174:177], v[206:209], v[84:87]
	v_mfma_f32_16x16x32_bf16 v[80:83], v[182:185], v[206:209], v[80:83]
	v_mfma_f32_16x16x32_bf16 v[68:71], v[174:177], v[214:217], v[68:71]
	v_mfma_f32_16x16x32_bf16 v[64:67], v[182:185], v[214:217], v[64:67]
	s_setprio 0
	s_barrier
	s_add_i32 s3, s54, s18
	s_mov_b32 m0, s3
	ds_read_b128 v[186:189], v152 offset:16384
	ds_read_b128 v[190:193], v152 offset:17408
	ds_read_b128 v[194:197], v152 offset:18432
	ds_read_b128 v[198:201], v152 offset:19456
	ds_read_b128 v[202:205], v152 offset:20480
	ds_read_b128 v[206:209], v152 offset:21504
	ds_read_b128 v[210:213], v152 offset:22528
	ds_read_b128 v[214:217], v152 offset:23552
	global_load_lds_dwordx4 v130, s[44:45]
	s_add_i32 m0, s3, 0x2000
	s_add_u32 s58, s44, 0x80000
	s_addc_u32 s59, s45, 0
	s_add_i32 s3, s55, s18
	global_load_lds_dwordx4 v134, s[44:45]
	s_mov_b32 m0, s3
	s_nop 0
	global_load_lds_dwordx4 v130, s[58:59]
	s_add_i32 m0, s3, 0x2000
	s_nop 0
	global_load_lds_dwordx4 v134, s[58:59]
	s_mov_b32 m0, s19
	s_nop 0
	global_load_lds_dwordx4 v128, s[48:49]
	s_mov_b32 m0, s25
	s_nop 0
	global_load_lds_dwordx4 v132, s[48:49]
	s_waitcnt vmcnt(8)
	s_waitcnt lgkmcnt(0)
	s_barrier
	s_setprio 1
	s_waitcnt lgkmcnt(0)
	v_mfma_f32_16x16x32_bf16 v[60:63], v[154:157], v[186:189], v[60:63]
	v_mfma_f32_16x16x32_bf16 v[56:59], v[162:165], v[186:189], v[56:59]
	v_mfma_f32_16x16x32_bf16 v[44:47], v[154:157], v[194:197], v[44:47]
	v_mfma_f32_16x16x32_bf16 v[40:43], v[162:165], v[194:197], v[40:43]
	v_mfma_f32_16x16x32_bf16 v[28:31], v[154:157], v[202:205], v[28:31]
	v_mfma_f32_16x16x32_bf16 v[24:27], v[162:165], v[202:205], v[24:27]
	v_mfma_f32_16x16x32_bf16 v[12:15], v[154:157], v[210:213], v[12:15]
	v_mfma_f32_16x16x32_bf16 v[8:11], v[162:165], v[210:213], v[8:11]
	v_mfma_f32_16x16x32_bf16 v[60:63], v[158:161], v[190:193], v[60:63]
	v_mfma_f32_16x16x32_bf16 v[56:59], v[166:169], v[190:193], v[56:59]
	v_mfma_f32_16x16x32_bf16 v[44:47], v[158:161], v[198:201], v[44:47]
	v_mfma_f32_16x16x32_bf16 v[40:43], v[166:169], v[198:201], v[40:43]
	v_mfma_f32_16x16x32_bf16 v[28:31], v[158:161], v[206:209], v[28:31]
	v_mfma_f32_16x16x32_bf16 v[24:27], v[166:169], v[206:209], v[24:27]
	v_mfma_f32_16x16x32_bf16 v[12:15], v[158:161], v[214:217], v[12:15]
	v_mfma_f32_16x16x32_bf16 v[8:11], v[166:169], v[214:217], v[8:11]
	v_mfma_f32_16x16x32_bf16 v[52:55], v[170:173], v[186:189], v[52:55]
	v_mfma_f32_16x16x32_bf16 v[48:51], v[178:181], v[186:189], v[48:51]
	v_mfma_f32_16x16x32_bf16 v[36:39], v[170:173], v[194:197], v[36:39]
	v_mfma_f32_16x16x32_bf16 v[32:35], v[178:181], v[194:197], v[32:35]
	v_mfma_f32_16x16x32_bf16 v[20:23], v[170:173], v[202:205], v[20:23]
	v_mfma_f32_16x16x32_bf16 v[16:19], v[178:181], v[202:205], v[16:19]
	v_mfma_f32_16x16x32_bf16 v[4:7], v[170:173], v[210:213], v[4:7]
	v_mfma_f32_16x16x32_bf16 v[0:3], v[178:181], v[210:213], v[0:3]
	v_mfma_f32_16x16x32_bf16 v[52:55], v[174:177], v[190:193], v[52:55]
	v_mfma_f32_16x16x32_bf16 v[48:51], v[182:185], v[190:193], v[48:51]
	v_mfma_f32_16x16x32_bf16 v[36:39], v[174:177], v[198:201], v[36:39]
	v_mfma_f32_16x16x32_bf16 v[32:35], v[182:185], v[198:201], v[32:35]
	v_mfma_f32_16x16x32_bf16 v[20:23], v[174:177], v[206:209], v[20:23]
	v_mfma_f32_16x16x32_bf16 v[16:19], v[182:185], v[206:209], v[16:19]
	v_mfma_f32_16x16x32_bf16 v[4:7], v[174:177], v[214:217], v[4:7]
	v_mfma_f32_16x16x32_bf16 v[0:3], v[182:185], v[214:217], v[0:3]
	s_setprio 0
	s_barrier
	s_add_i32 s3, 0, 0x18000
	v_add_u32_e32 v153, s3, v149
	s_add_i32 s57, 0, 0x1c000
	ds_read_b128 v[154:157], v153
	ds_read_b128 v[158:161], v153 offset:1024
	ds_read_b128 v[162:165], v153 offset:2048
	ds_read_b128 v[166:169], v153 offset:3072
	v_add_u32_e32 v153, s57, v149
	ds_read_b128 v[170:173], v153
	ds_read_b128 v[174:177], v153 offset:1024
	ds_read_b128 v[178:181], v153 offset:2048
	ds_read_b128 v[182:185], v153 offset:3072
	s_add_u32 s48, s48, 0x80000
	s_addc_u32 s49, s49, 0
	s_mov_b32 m0, s27
	ds_read_b128 v[186:189], v152 offset:32768
	ds_read_b128 v[190:193], v152 offset:33792
	ds_read_b128 v[194:197], v152 offset:34816
	ds_read_b128 v[198:201], v152 offset:35840
	ds_read_b128 v[202:205], v152 offset:36864
	ds_read_b128 v[206:209], v152 offset:37888
	ds_read_b128 v[210:213], v152 offset:38912
	ds_read_b128 v[214:217], v152 offset:39936
	global_load_lds_dwordx4 v128, s[48:49]
	s_mov_b32 m0, s33
	s_nop 0
	global_load_lds_dwordx4 v132, s[48:49]
	s_waitcnt vmcnt(8)
	s_waitcnt lgkmcnt(0)
	s_barrier
	s_setprio 1
	s_waitcnt lgkmcnt(0)
	v_mfma_f32_16x16x32_bf16 v[124:127], v[154:157], v[186:189], v[124:127]
	v_mfma_f32_16x16x32_bf16 v[120:123], v[162:165], v[186:189], v[120:123]
	v_mfma_f32_16x16x32_bf16 v[108:111], v[154:157], v[194:197], v[108:111]
	v_mfma_f32_16x16x32_bf16 v[104:107], v[162:165], v[194:197], v[104:107]
	v_mfma_f32_16x16x32_bf16 v[92:95], v[154:157], v[202:205], v[92:95]
	v_mfma_f32_16x16x32_bf16 v[88:91], v[162:165], v[202:205], v[88:91]
	v_mfma_f32_16x16x32_bf16 v[76:79], v[154:157], v[210:213], v[76:79]
	v_mfma_f32_16x16x32_bf16 v[72:75], v[162:165], v[210:213], v[72:75]
	v_mfma_f32_16x16x32_bf16 v[124:127], v[158:161], v[190:193], v[124:127]
	v_mfma_f32_16x16x32_bf16 v[120:123], v[166:169], v[190:193], v[120:123]
	v_mfma_f32_16x16x32_bf16 v[108:111], v[158:161], v[198:201], v[108:111]
	v_mfma_f32_16x16x32_bf16 v[104:107], v[166:169], v[198:201], v[104:107]
	v_mfma_f32_16x16x32_bf16 v[92:95], v[158:161], v[206:209], v[92:95]
	v_mfma_f32_16x16x32_bf16 v[88:91], v[166:169], v[206:209], v[88:91]
	v_mfma_f32_16x16x32_bf16 v[76:79], v[158:161], v[214:217], v[76:79]
	v_mfma_f32_16x16x32_bf16 v[72:75], v[166:169], v[214:217], v[72:75]
	v_mfma_f32_16x16x32_bf16 v[116:119], v[170:173], v[186:189], v[116:119]
	v_mfma_f32_16x16x32_bf16 v[112:115], v[178:181], v[186:189], v[112:115]
	v_mfma_f32_16x16x32_bf16 v[100:103], v[170:173], v[194:197], v[100:103]
	v_mfma_f32_16x16x32_bf16 v[96:99], v[178:181], v[194:197], v[96:99]
	v_mfma_f32_16x16x32_bf16 v[84:87], v[170:173], v[202:205], v[84:87]
	v_mfma_f32_16x16x32_bf16 v[80:83], v[178:181], v[202:205], v[80:83]
	v_mfma_f32_16x16x32_bf16 v[68:71], v[170:173], v[210:213], v[68:71]
	v_mfma_f32_16x16x32_bf16 v[64:67], v[178:181], v[210:213], v[64:67]
	v_mfma_f32_16x16x32_bf16 v[116:119], v[174:177], v[190:193], v[116:119]
	v_mfma_f32_16x16x32_bf16 v[112:115], v[182:185], v[190:193], v[112:115]
	v_mfma_f32_16x16x32_bf16 v[100:103], v[174:177], v[198:201], v[100:103]
	v_mfma_f32_16x16x32_bf16 v[96:99], v[182:185], v[198:201], v[96:99]
	v_mfma_f32_16x16x32_bf16 v[84:87], v[174:177], v[206:209], v[84:87]
	v_mfma_f32_16x16x32_bf16 v[80:83], v[182:185], v[206:209], v[80:83]
	v_mfma_f32_16x16x32_bf16 v[68:71], v[174:177], v[214:217], v[68:71]
	v_mfma_f32_16x16x32_bf16 v[64:67], v[182:185], v[214:217], v[64:67]
	s_setprio 0
	s_barrier
	s_add_i32 s3, s3, s18
	s_add_u32 s44, s44, 0x80
	s_addc_u32 s45, s45, 0
	s_mov_b32 m0, s3
	ds_read_b128 v[186:189], v152 offset:49152
	ds_read_b128 v[190:193], v152 offset:50176
	ds_read_b128 v[194:197], v152 offset:51200
	ds_read_b128 v[198:201], v152 offset:52224
	ds_read_b128 v[202:205], v152 offset:53248
	ds_read_b128 v[206:209], v152 offset:54272
	ds_read_b128 v[210:213], v152 offset:55296
	ds_read_b128 v[214:217], v152 offset:56320
	global_load_lds_dwordx4 v130, s[44:45]
	s_add_i32 m0, s3, 0x2000
	s_add_i32 s3, s57, s18
	global_load_lds_dwordx4 v134, s[44:45]
	s_add_u32 s44, s44, 0x80000
	s_addc_u32 s45, s45, 0
	s_mov_b32 m0, s3
	s_nop 0
	global_load_lds_dwordx4 v130, s[44:45]
	s_add_i32 m0, s3, 0x2000
	s_nop 0
	global_load_lds_dwordx4 v134, s[44:45]
	s_add_u32 s48, s48, 0xfff80080
	s_addc_u32 s49, s49, -1
	s_mov_b32 m0, s52
	s_nop 0
	global_load_lds_dwordx4 v128, s[48:49]
	s_mov_b32 m0, s53
	s_nop 0
	global_load_lds_dwordx4 v132, s[48:49]
	s_waitcnt vmcnt(8)
	s_waitcnt lgkmcnt(0)
	s_barrier
	s_setprio 1
	s_waitcnt lgkmcnt(0)
	v_mfma_f32_16x16x32_bf16 v[60:63], v[154:157], v[186:189], v[60:63]
	v_mfma_f32_16x16x32_bf16 v[56:59], v[162:165], v[186:189], v[56:59]
	v_mfma_f32_16x16x32_bf16 v[44:47], v[154:157], v[194:197], v[44:47]
	v_mfma_f32_16x16x32_bf16 v[40:43], v[162:165], v[194:197], v[40:43]
	v_mfma_f32_16x16x32_bf16 v[28:31], v[154:157], v[202:205], v[28:31]
	v_mfma_f32_16x16x32_bf16 v[24:27], v[162:165], v[202:205], v[24:27]
	v_mfma_f32_16x16x32_bf16 v[12:15], v[154:157], v[210:213], v[12:15]
	v_mfma_f32_16x16x32_bf16 v[8:11], v[162:165], v[210:213], v[8:11]
	v_mfma_f32_16x16x32_bf16 v[60:63], v[158:161], v[190:193], v[60:63]
	v_mfma_f32_16x16x32_bf16 v[56:59], v[166:169], v[190:193], v[56:59]
	v_mfma_f32_16x16x32_bf16 v[44:47], v[158:161], v[198:201], v[44:47]
	v_mfma_f32_16x16x32_bf16 v[40:43], v[166:169], v[198:201], v[40:43]
	v_mfma_f32_16x16x32_bf16 v[28:31], v[158:161], v[206:209], v[28:31]
	v_mfma_f32_16x16x32_bf16 v[24:27], v[166:169], v[206:209], v[24:27]
	v_mfma_f32_16x16x32_bf16 v[12:15], v[158:161], v[214:217], v[12:15]
	v_mfma_f32_16x16x32_bf16 v[8:11], v[166:169], v[214:217], v[8:11]
	v_mfma_f32_16x16x32_bf16 v[52:55], v[170:173], v[186:189], v[52:55]
	v_mfma_f32_16x16x32_bf16 v[48:51], v[178:181], v[186:189], v[48:51]
	v_mfma_f32_16x16x32_bf16 v[36:39], v[170:173], v[194:197], v[36:39]
	v_mfma_f32_16x16x32_bf16 v[32:35], v[178:181], v[194:197], v[32:35]
	v_mfma_f32_16x16x32_bf16 v[20:23], v[170:173], v[202:205], v[20:23]
	v_mfma_f32_16x16x32_bf16 v[16:19], v[178:181], v[202:205], v[16:19]
	v_mfma_f32_16x16x32_bf16 v[4:7], v[170:173], v[210:213], v[4:7]
	v_mfma_f32_16x16x32_bf16 v[0:3], v[178:181], v[210:213], v[0:3]
	v_mfma_f32_16x16x32_bf16 v[52:55], v[174:177], v[190:193], v[52:55]
	v_mfma_f32_16x16x32_bf16 v[48:51], v[182:185], v[190:193], v[48:51]
	v_mfma_f32_16x16x32_bf16 v[36:39], v[174:177], v[198:201], v[36:39]
	v_mfma_f32_16x16x32_bf16 v[32:35], v[182:185], v[198:201], v[32:35]
	v_mfma_f32_16x16x32_bf16 v[20:23], v[174:177], v[206:209], v[20:23]
	v_mfma_f32_16x16x32_bf16 v[16:19], v[182:185], v[206:209], v[16:19]
	v_mfma_f32_16x16x32_bf16 v[4:7], v[174:177], v[214:217], v[4:7]
	v_mfma_f32_16x16x32_bf16 v[0:3], v[182:185], v[214:217], v[0:3]
	s_setprio 0
	s_barrier
	s_add_i32 s51, s51, 2
	s_add_u32 s42, s42, 0x100
	s_addc_u32 s43, s43, 0
	s_add_u32 s41, s41, 0x100
	s_addc_u32 s50, s50, 0
	s_cmp_gt_u32 s51, 29
	s_cbranch_scc0 .LBB0_2479
	s_and_b64 vcc, exec, s[12:13]
	s_cbranch_vccz .LBB0_2482
	s_barrier

.LBB0_2555:
	ds_read_b128 v[140:143], v149
	ds_read_b128 v[152:155], v149 offset:1024
	ds_read_b128 v[156:159], v149 offset:2048
	ds_read_b128 v[160:163], v149 offset:3072
	ds_read_b128 v[164:167], v150
	ds_read_b128 v[168:171], v150 offset:1024
	ds_read_b128 v[172:175], v150 offset:2048
	ds_read_b128 v[176:179], v150 offset:3072
	s_add_u32 s3, s48, 0xffe00080
	s_addc_u32 s52, s49, -1
	s_cmpk_eq_i32 s64, 0x7c
	s_cselect_b32 s55, s0, s52
	s_cselect_b32 s54, s1, s3
	s_cselect_b32 s53, s35, s51
	s_cselect_b32 s52, s37, s50
	s_add_i32 m0, s27, 0xc000
	ds_read_b128 v[180:183], v151
	ds_read_b128 v[184:187], v151 offset:1024
	ds_read_b128 v[188:191], v151 offset:2048
	ds_read_b128 v[192:195], v151 offset:3072
	ds_read_b128 v[196:199], v151 offset:4096
	ds_read_b128 v[200:203], v151 offset:5120
	ds_read_b128 v[204:207], v151 offset:6144
	ds_read_b128 v[208:211], v151 offset:7168
	global_load_lds_dwordx4 v132, s[48:49]
	s_add_i32 m0, s27, 0xe000
	s_nop 0
	global_load_lds_dwordx4 v134, s[48:49]
	s_waitcnt vmcnt(8)
	s_waitcnt lgkmcnt(0)
	s_barrier
	s_setprio 1
	s_waitcnt lgkmcnt(0)
	v_mfma_f32_16x16x32_bf16 v[124:127], v[140:143], v[180:183], v[124:127]
	v_mfma_f32_16x16x32_bf16 v[120:123], v[156:159], v[180:183], v[120:123]
	v_mfma_f32_16x16x32_bf16 v[112:115], v[140:143], v[188:191], v[112:115]
	v_mfma_f32_16x16x32_bf16 v[104:107], v[156:159], v[188:191], v[104:107]
	v_mfma_f32_16x16x32_bf16 v[96:99], v[140:143], v[196:199], v[96:99]
	v_mfma_f32_16x16x32_bf16 v[88:91], v[156:159], v[196:199], v[88:91]
	v_mfma_f32_16x16x32_bf16 v[80:83], v[140:143], v[204:207], v[80:83]
	v_mfma_f32_16x16x32_bf16 v[72:75], v[156:159], v[204:207], v[72:75]
	v_mfma_f32_16x16x32_bf16 v[124:127], v[152:155], v[184:187], v[124:127]
	v_mfma_f32_16x16x32_bf16 v[120:123], v[160:163], v[184:187], v[120:123]
	v_mfma_f32_16x16x32_bf16 v[112:115], v[152:155], v[192:195], v[112:115]
	v_mfma_f32_16x16x32_bf16 v[104:107], v[160:163], v[192:195], v[104:107]
	v_mfma_f32_16x16x32_bf16 v[96:99], v[152:155], v[200:203], v[96:99]
	v_mfma_f32_16x16x32_bf16 v[88:91], v[160:163], v[200:203], v[88:91]
	v_mfma_f32_16x16x32_bf16 v[80:83], v[152:155], v[208:211], v[80:83]
	v_mfma_f32_16x16x32_bf16 v[72:75], v[160:163], v[208:211], v[72:75]
	v_mfma_f32_16x16x32_bf16 v[116:119], v[164:167], v[180:183], v[116:119]
	v_mfma_f32_16x16x32_bf16 v[108:111], v[172:175], v[180:183], v[108:111]
	v_mfma_f32_16x16x32_bf16 v[100:103], v[164:167], v[188:191], v[100:103]
	v_mfma_f32_16x16x32_bf16 v[92:95], v[172:175], v[188:191], v[92:95]
	v_mfma_f32_16x16x32_bf16 v[84:87], v[164:167], v[196:199], v[84:87]
	v_mfma_f32_16x16x32_bf16 v[76:79], v[172:175], v[196:199], v[76:79]
	v_mfma_f32_16x16x32_bf16 v[68:71], v[164:167], v[204:207], v[68:71]
	v_mfma_f32_16x16x32_bf16 v[64:67], v[172:175], v[204:207], v[64:67]
	v_mfma_f32_16x16x32_bf16 v[116:119], v[168:171], v[184:187], v[116:119]
	v_mfma_f32_16x16x32_bf16 v[108:111], v[176:179], v[184:187], v[108:111]
	v_mfma_f32_16x16x32_bf16 v[100:103], v[168:171], v[192:195], v[100:103]
	v_mfma_f32_16x16x32_bf16 v[92:95], v[176:179], v[192:195], v[92:95]
	v_mfma_f32_16x16x32_bf16 v[84:87], v[168:171], v[200:203], v[84:87]
	v_mfma_f32_16x16x32_bf16 v[76:79], v[176:179], v[200:203], v[76:79]
	v_mfma_f32_16x16x32_bf16 v[68:71], v[168:171], v[208:211], v[68:71]
	v_mfma_f32_16x16x32_bf16 v[64:67], v[176:179], v[208:211], v[64:67]
	s_setprio 0
	s_barrier
	s_add_i32 s3, s58, s25
	s_mov_b32 m0, s3
	ds_read_b128 v[180:183], v151 offset:16384
	ds_read_b128 v[184:187], v151 offset:17408
	ds_read_b128 v[188:191], v151 offset:18432
	ds_read_b128 v[192:195], v151 offset:19456
	ds_read_b128 v[196:199], v151 offset:20480
	ds_read_b128 v[200:203], v151 offset:21504
	ds_read_b128 v[204:207], v151 offset:22528
	ds_read_b128 v[208:211], v151 offset:23552
	global_load_lds_dwordx4 v128, s[52:53]
	s_add_i32 m0, s3, 0x2000
	s_add_u32 s66, s52, 0x200000
	s_addc_u32 s67, s53, 0
	s_add_i32 s3, s59, s25
	global_load_lds_dwordx4 v130, s[52:53]
	s_mov_b32 m0, s3
	s_nop 0
	global_load_lds_dwordx4 v128, s[66:67]
	s_add_i32 m0, s3, 0x2000
	s_nop 0
	global_load_lds_dwordx4 v130, s[66:67]
	s_mov_b32 m0, s27
	s_nop 0
	global_load_lds_dwordx4 v128, s[54:55]
	s_mov_b32 m0, s30
	s_nop 0
	global_load_lds_dwordx4 v130, s[54:55]
	s_waitcnt vmcnt(8)
	s_waitcnt lgkmcnt(0)
	s_barrier
	s_setprio 1
	s_waitcnt lgkmcnt(0)
	v_mfma_f32_16x16x32_bf16 v[60:63], v[140:143], v[180:183], v[60:63]
	v_mfma_f32_16x16x32_bf16 v[56:59], v[156:159], v[180:183], v[56:59]
	v_mfma_f32_16x16x32_bf16 v[48:51], v[140:143], v[188:191], v[48:51]
	v_mfma_f32_16x16x32_bf16 v[40:43], v[156:159], v[188:191], v[40:43]
	v_mfma_f32_16x16x32_bf16 v[32:35], v[140:143], v[196:199], v[32:35]
	v_mfma_f32_16x16x32_bf16 v[24:27], v[156:159], v[196:199], v[24:27]
	v_mfma_f32_16x16x32_bf16 v[16:19], v[140:143], v[204:207], v[16:19]
	v_mfma_f32_16x16x32_bf16 v[8:11], v[156:159], v[204:207], v[8:11]
	v_mfma_f32_16x16x32_bf16 v[60:63], v[152:155], v[184:187], v[60:63]
	v_mfma_f32_16x16x32_bf16 v[56:59], v[160:163], v[184:187], v[56:59]
	v_mfma_f32_16x16x32_bf16 v[48:51], v[152:155], v[192:195], v[48:51]
	v_mfma_f32_16x16x32_bf16 v[40:43], v[160:163], v[192:195], v[40:43]
	v_mfma_f32_16x16x32_bf16 v[32:35], v[152:155], v[200:203], v[32:35]
	v_mfma_f32_16x16x32_bf16 v[24:27], v[160:163], v[200:203], v[24:27]
	v_mfma_f32_16x16x32_bf16 v[16:19], v[152:155], v[208:211], v[16:19]
	v_mfma_f32_16x16x32_bf16 v[8:11], v[160:163], v[208:211], v[8:11]
	v_mfma_f32_16x16x32_bf16 v[52:55], v[164:167], v[180:183], v[52:55]
	v_mfma_f32_16x16x32_bf16 v[44:47], v[172:175], v[180:183], v[44:47]
	v_mfma_f32_16x16x32_bf16 v[36:39], v[164:167], v[188:191], v[36:39]
	v_mfma_f32_16x16x32_bf16 v[28:31], v[172:175], v[188:191], v[28:31]
	v_mfma_f32_16x16x32_bf16 v[20:23], v[164:167], v[196:199], v[20:23]
	v_mfma_f32_16x16x32_bf16 v[12:15], v[172:175], v[196:199], v[12:15]
	v_mfma_f32_16x16x32_bf16 v[4:7], v[164:167], v[204:207], v[4:7]
	v_mfma_f32_16x16x32_bf16 v[0:3], v[172:175], v[204:207], v[0:3]
	v_mfma_f32_16x16x32_bf16 v[52:55], v[168:171], v[184:187], v[52:55]
	v_mfma_f32_16x16x32_bf16 v[44:47], v[176:179], v[184:187], v[44:47]
	v_mfma_f32_16x16x32_bf16 v[36:39], v[168:171], v[192:195], v[36:39]
	v_mfma_f32_16x16x32_bf16 v[28:31], v[176:179], v[192:195], v[28:31]
	v_mfma_f32_16x16x32_bf16 v[20:23], v[168:171], v[200:203], v[20:23]
	v_mfma_f32_16x16x32_bf16 v[12:15], v[176:179], v[200:203], v[12:15]
	v_mfma_f32_16x16x32_bf16 v[4:7], v[168:171], v[208:211], v[4:7]
	v_mfma_f32_16x16x32_bf16 v[0:3], v[176:179], v[208:211], v[0:3]
	s_setprio 0
	s_barrier
	s_add_i32 s3, 0, 0x18000
	s_add_i32 s65, 0, 0x1c000
	v_add_u32_e32 v160, s3, v147
	v_add_u32_e32 v176, s65, v147
	ds_read_b128 v[140:143], v160
	ds_read_b128 v[152:155], v160 offset:1024
	ds_read_b128 v[156:159], v160 offset:2048
	ds_read_b128 v[160:163], v160 offset:3072
	ds_read_b128 v[164:167], v176
	ds_read_b128 v[168:171], v176 offset:1024
	ds_read_b128 v[172:175], v176 offset:2048
	ds_read_b128 v[176:179], v176 offset:3072
	s_add_u32 s54, s54, 0x200000
	s_addc_u32 s55, s55, 0
	s_mov_b32 m0, s31
	ds_read_b128 v[180:183], v151 offset:32768
	ds_read_b128 v[184:187], v151 offset:33792
	ds_read_b128 v[188:191], v151 offset:34816
	ds_read_b128 v[192:195], v151 offset:35840
	ds_read_b128 v[196:199], v151 offset:36864
	ds_read_b128 v[200:203], v151 offset:37888
	ds_read_b128 v[204:207], v151 offset:38912
	ds_read_b128 v[208:211], v151 offset:39936
	global_load_lds_dwordx4 v128, s[54:55]
	s_mov_b32 m0, s33
	s_nop 0
	global_load_lds_dwordx4 v130, s[54:55]
	s_waitcnt vmcnt(8)
	s_waitcnt lgkmcnt(0)
	s_barrier
	s_setprio 1
	s_waitcnt lgkmcnt(0)
	v_mfma_f32_16x16x32_bf16 v[124:127], v[140:143], v[180:183], v[124:127]
	v_mfma_f32_16x16x32_bf16 v[120:123], v[156:159], v[180:183], v[120:123]
	v_mfma_f32_16x16x32_bf16 v[112:115], v[140:143], v[188:191], v[112:115]
	v_mfma_f32_16x16x32_bf16 v[104:107], v[156:159], v[188:191], v[104:107]
	v_mfma_f32_16x16x32_bf16 v[96:99], v[140:143], v[196:199], v[96:99]
	v_mfma_f32_16x16x32_bf16 v[88:91], v[156:159], v[196:199], v[88:91]
	v_mfma_f32_16x16x32_bf16 v[80:83], v[140:143], v[204:207], v[80:83]
	v_mfma_f32_16x16x32_bf16 v[72:75], v[156:159], v[204:207], v[72:75]
	v_mfma_f32_16x16x32_bf16 v[124:127], v[152:155], v[184:187], v[124:127]
	v_mfma_f32_16x16x32_bf16 v[120:123], v[160:163], v[184:187], v[120:123]
	v_mfma_f32_16x16x32_bf16 v[112:115], v[152:155], v[192:195], v[112:115]
	v_mfma_f32_16x16x32_bf16 v[104:107], v[160:163], v[192:195], v[104:107]
	v_mfma_f32_16x16x32_bf16 v[96:99], v[152:155], v[200:203], v[96:99]
	v_mfma_f32_16x16x32_bf16 v[88:91], v[160:163], v[200:203], v[88:91]
	v_mfma_f32_16x16x32_bf16 v[80:83], v[152:155], v[208:211], v[80:83]
	v_mfma_f32_16x16x32_bf16 v[72:75], v[160:163], v[208:211], v[72:75]
	v_mfma_f32_16x16x32_bf16 v[116:119], v[164:167], v[180:183], v[116:119]
	v_mfma_f32_16x16x32_bf16 v[108:111], v[172:175], v[180:183], v[108:111]
	v_mfma_f32_16x16x32_bf16 v[100:103], v[164:167], v[188:191], v[100:103]
	v_mfma_f32_16x16x32_bf16 v[92:95], v[172:175], v[188:191], v[92:95]
	v_mfma_f32_16x16x32_bf16 v[84:87], v[164:167], v[196:199], v[84:87]
	v_mfma_f32_16x16x32_bf16 v[76:79], v[172:175], v[196:199], v[76:79]
	v_mfma_f32_16x16x32_bf16 v[68:71], v[164:167], v[204:207], v[68:71]
	v_mfma_f32_16x16x32_bf16 v[64:67], v[172:175], v[204:207], v[64:67]
	v_mfma_f32_16x16x32_bf16 v[116:119], v[168:171], v[184:187], v[116:119]
	v_mfma_f32_16x16x32_bf16 v[108:111], v[176:179], v[184:187], v[108:111]
	v_mfma_f32_16x16x32_bf16 v[100:103], v[168:171], v[192:195], v[100:103]
	v_mfma_f32_16x16x32_bf16 v[92:95], v[176:179], v[192:195], v[92:95]
	v_mfma_f32_16x16x32_bf16 v[84:87], v[168:171], v[200:203], v[84:87]
	v_mfma_f32_16x16x32_bf16 v[76:79], v[176:179], v[200:203], v[76:79]
	v_mfma_f32_16x16x32_bf16 v[68:71], v[168:171], v[208:211], v[68:71]
	v_mfma_f32_16x16x32_bf16 v[64:67], v[176:179], v[208:211], v[64:67]
	s_setprio 0
	s_barrier
	s_add_i32 s3, s3, s25
	s_add_u32 s52, s52, 0x80
	s_addc_u32 s53, s53, 0
	s_mov_b32 m0, s3
	ds_read_b128 v[180:183], v151 offset:49152
	ds_read_b128 v[184:187], v151 offset:50176
	ds_read_b128 v[188:191], v151 offset:51200
	ds_read_b128 v[192:195], v151 offset:52224
	ds_read_b128 v[196:199], v151 offset:53248
	ds_read_b128 v[200:203], v151 offset:54272
	ds_read_b128 v[204:207], v151 offset:55296
	ds_read_b128 v[208:211], v151 offset:56320
	global_load_lds_dwordx4 v128, s[52:53]
	s_add_i32 m0, s3, 0x2000
	s_add_i32 s3, s65, s25
	global_load_lds_dwordx4 v130, s[52:53]
	s_add_u32 s52, s52, 0x200000
	s_addc_u32 s53, s53, 0
	s_mov_b32 m0, s3
	s_nop 0
	global_load_lds_dwordx4 v128, s[52:53]
	s_add_i32 m0, s3, 0x2000
	s_nop 0
	global_load_lds_dwordx4 v130, s[52:53]
	s_add_u32 s54, s54, 0xffe00080
	s_addc_u32 s55, s55, -1
	s_mov_b32 m0, s56
	s_nop 0
	global_load_lds_dwordx4 v128, s[54:55]
	s_mov_b32 m0, s57
	s_nop 0
	global_load_lds_dwordx4 v130, s[54:55]
	s_waitcnt vmcnt(8)
	s_waitcnt lgkmcnt(0)
	s_barrier
	s_setprio 1
	s_waitcnt lgkmcnt(0)
	v_mfma_f32_16x16x32_bf16 v[60:63], v[140:143], v[180:183], v[60:63]
	v_mfma_f32_16x16x32_bf16 v[56:59], v[156:159], v[180:183], v[56:59]
	v_mfma_f32_16x16x32_bf16 v[48:51], v[140:143], v[188:191], v[48:51]
	v_mfma_f32_16x16x32_bf16 v[40:43], v[156:159], v[188:191], v[40:43]
	v_mfma_f32_16x16x32_bf16 v[32:35], v[140:143], v[196:199], v[32:35]
	v_mfma_f32_16x16x32_bf16 v[24:27], v[156:159], v[196:199], v[24:27]
	v_mfma_f32_16x16x32_bf16 v[16:19], v[140:143], v[204:207], v[16:19]
	v_mfma_f32_16x16x32_bf16 v[8:11], v[156:159], v[204:207], v[8:11]
	v_mfma_f32_16x16x32_bf16 v[60:63], v[152:155], v[184:187], v[60:63]
	v_mfma_f32_16x16x32_bf16 v[56:59], v[160:163], v[184:187], v[56:59]
	v_mfma_f32_16x16x32_bf16 v[48:51], v[152:155], v[192:195], v[48:51]
	v_mfma_f32_16x16x32_bf16 v[40:43], v[160:163], v[192:195], v[40:43]
	v_mfma_f32_16x16x32_bf16 v[32:35], v[152:155], v[200:203], v[32:35]
	v_mfma_f32_16x16x32_bf16 v[24:27], v[160:163], v[200:203], v[24:27]
	v_mfma_f32_16x16x32_bf16 v[16:19], v[152:155], v[208:211], v[16:19]
	v_mfma_f32_16x16x32_bf16 v[8:11], v[160:163], v[208:211], v[8:11]
	v_mfma_f32_16x16x32_bf16 v[52:55], v[164:167], v[180:183], v[52:55]
	v_mfma_f32_16x16x32_bf16 v[44:47], v[172:175], v[180:183], v[44:47]
	v_mfma_f32_16x16x32_bf16 v[36:39], v[164:167], v[188:191], v[36:39]
	v_mfma_f32_16x16x32_bf16 v[28:31], v[172:175], v[188:191], v[28:31]
	v_mfma_f32_16x16x32_bf16 v[20:23], v[164:167], v[196:199], v[20:23]
	v_mfma_f32_16x16x32_bf16 v[12:15], v[172:175], v[196:199], v[12:15]
	v_mfma_f32_16x16x32_bf16 v[4:7], v[164:167], v[204:207], v[4:7]
	v_mfma_f32_16x16x32_bf16 v[0:3], v[172:175], v[204:207], v[0:3]
	v_mfma_f32_16x16x32_bf16 v[52:55], v[168:171], v[184:187], v[52:55]
	v_mfma_f32_16x16x32_bf16 v[44:47], v[176:179], v[184:187], v[44:47]
	v_mfma_f32_16x16x32_bf16 v[36:39], v[168:171], v[192:195], v[36:39]
	v_mfma_f32_16x16x32_bf16 v[28:31], v[176:179], v[192:195], v[28:31]
	v_mfma_f32_16x16x32_bf16 v[20:23], v[168:171], v[200:203], v[20:23]
	v_mfma_f32_16x16x32_bf16 v[12:15], v[176:179], v[200:203], v[12:15]
	v_mfma_f32_16x16x32_bf16 v[4:7], v[168:171], v[208:211], v[4:7]
	v_mfma_f32_16x16x32_bf16 v[0:3], v[176:179], v[208:211], v[0:3]
	s_setprio 0
	s_barrier
	s_add_i32 s64, s64, 2
	s_add_u32 s48, s48, 0x100
	s_addc_u32 s49, s49, 0
	s_add_u32 s50, s50, 0x100
	s_addc_u32 s51, s51, 0
	s_cmpk_gt_u32 s64, 0x7d
	s_cbranch_scc0 .LBB0_2555
	s_and_b64 vcc, exec, s[10:11]
	s_cbranch_vccz .LBB0_2558
	s_barrier
